# all 10 GEMM K loops: hipcc's 16 per-segment s_setprio flips deleted, one static s_setprio 1 for waves 4-7 before each K loop (reset after it); on top of v041
# speedup vs baseline: 1.0015x; 1.0015x over previous
.LBB0_310:
	s_ashr_i32 s55, s54, 31
	s_lshl_b64 s[58:59], s[54:55], 19
	s_add_u32 s58, s29, s58
	s_addc_u32 s59, s30, s59
	s_and_b64 s[60:61], s[38:39], exec
	s_cselect_b32 s33, s59, s35
	s_cselect_b32 s36, s58, s34
	s_ashr_i32 s53, s52, 31
	s_lshl_b64 s[60:61], s[52:53], 19
	s_add_u32 s60, s45, s60
	s_addc_u32 s61, s66, s61
	s_and_b64 s[62:63], s[38:39], exec
	s_cselect_b32 s53, s61, s65
	s_cselect_b32 s55, s60, s64
	s_add_u32 s62, s34, 0x40080
	s_addc_u32 s63, s35, 0
	s_add_u32 s75, s64, 0x100
	v_mov_b32_e32 v0, 0
	s_addc_u32 s79, s65, 0
	s_mov_b32 s82, -2
	v_mov_b32_e32 v1, v0
	v_mov_b32_e32 v2, v0
	v_mov_b32_e32 v3, v0
	v_mov_b32_e32 v4, v0
	v_mov_b32_e32 v5, v0
	v_mov_b32_e32 v6, v0
	v_mov_b32_e32 v7, v0
	v_mov_b32_e32 v16, v0
	v_mov_b32_e32 v17, v0
	v_mov_b32_e32 v18, v0
	v_mov_b32_e32 v19, v0
	v_mov_b32_e32 v20, v0
	v_mov_b32_e32 v21, v0
	v_mov_b32_e32 v22, v0
	v_mov_b32_e32 v23, v0
	v_mov_b32_e32 v32, v0
	v_mov_b32_e32 v33, v0
	v_mov_b32_e32 v34, v0
	v_mov_b32_e32 v35, v0
	v_mov_b32_e32 v36, v0
	v_mov_b32_e32 v37, v0
	v_mov_b32_e32 v38, v0
	v_mov_b32_e32 v39, v0
	v_mov_b32_e32 v48, v0
	v_mov_b32_e32 v49, v0
	v_mov_b32_e32 v50, v0
	v_mov_b32_e32 v51, v0
	v_mov_b32_e32 v52, v0
	v_mov_b32_e32 v53, v0
	v_mov_b32_e32 v54, v0
	v_mov_b32_e32 v55, v0
	v_mov_b32_e32 v8, v0
	v_mov_b32_e32 v9, v0
	v_mov_b32_e32 v10, v0
	v_mov_b32_e32 v11, v0
	v_mov_b32_e32 v12, v0
	v_mov_b32_e32 v13, v0
	v_mov_b32_e32 v14, v0
	v_mov_b32_e32 v15, v0
	v_mov_b32_e32 v24, v0
	v_mov_b32_e32 v25, v0
	v_mov_b32_e32 v26, v0
	v_mov_b32_e32 v27, v0
	v_mov_b32_e32 v28, v0
	v_mov_b32_e32 v29, v0
	v_mov_b32_e32 v30, v0
	v_mov_b32_e32 v31, v0
	v_mov_b32_e32 v40, v0
	v_mov_b32_e32 v41, v0
	v_mov_b32_e32 v42, v0
	v_mov_b32_e32 v43, v0
	v_mov_b32_e32 v44, v0
	v_mov_b32_e32 v45, v0
	v_mov_b32_e32 v46, v0
	v_mov_b32_e32 v47, v0
	v_mov_b32_e32 v56, v0
	v_mov_b32_e32 v57, v0
	v_mov_b32_e32 v58, v0
	v_mov_b32_e32 v59, v0
	v_mov_b32_e32 v60, v0
	v_mov_b32_e32 v61, v0
	v_mov_b32_e32 v62, v0
	v_mov_b32_e32 v63, v0
	v_mov_b32_e32 v64, v0
	v_mov_b32_e32 v65, v0
	v_mov_b32_e32 v66, v0
	v_mov_b32_e32 v67, v0
	v_mov_b32_e32 v68, v0
	v_mov_b32_e32 v69, v0
	v_mov_b32_e32 v70, v0
	v_mov_b32_e32 v71, v0
	v_mov_b32_e32 v80, v0
	v_mov_b32_e32 v81, v0
	v_mov_b32_e32 v82, v0
	v_mov_b32_e32 v83, v0
	v_mov_b32_e32 v84, v0
	v_mov_b32_e32 v85, v0
	v_mov_b32_e32 v86, v0
	v_mov_b32_e32 v87, v0
	v_mov_b32_e32 v96, v0
	v_mov_b32_e32 v97, v0
	v_mov_b32_e32 v98, v0
	v_mov_b32_e32 v99, v0
	v_mov_b32_e32 v100, v0
	v_mov_b32_e32 v101, v0
	v_mov_b32_e32 v102, v0
	v_mov_b32_e32 v103, v0
	v_mov_b32_e32 v112, v0
	v_mov_b32_e32 v113, v0
	v_mov_b32_e32 v114, v0
	v_mov_b32_e32 v115, v0
	v_mov_b32_e32 v116, v0
	v_mov_b32_e32 v117, v0
	v_mov_b32_e32 v118, v0
	v_mov_b32_e32 v119, v0
	v_mov_b32_e32 v72, v0
	v_mov_b32_e32 v73, v0
	v_mov_b32_e32 v74, v0
	v_mov_b32_e32 v75, v0
	v_mov_b32_e32 v76, v0
	v_mov_b32_e32 v77, v0
	v_mov_b32_e32 v78, v0
	v_mov_b32_e32 v79, v0
	v_mov_b32_e32 v88, v0
	v_mov_b32_e32 v89, v0
	v_mov_b32_e32 v90, v0
	v_mov_b32_e32 v91, v0
	v_mov_b32_e32 v92, v0
	v_mov_b32_e32 v93, v0
	v_mov_b32_e32 v94, v0
	v_mov_b32_e32 v95, v0
	v_mov_b32_e32 v104, v0
	v_mov_b32_e32 v105, v0
	v_mov_b32_e32 v106, v0
	v_mov_b32_e32 v107, v0
	v_mov_b32_e32 v108, v0
	v_mov_b32_e32 v109, v0
	v_mov_b32_e32 v110, v0
	v_mov_b32_e32 v111, v0
	v_mov_b32_e32 v120, v0
	v_mov_b32_e32 v121, v0
	v_mov_b32_e32 v122, v0
	v_mov_b32_e32 v123, v0
	v_mov_b32_e32 v124, v0
	v_mov_b32_e32 v125, v0
	v_mov_b32_e32 v126, v0
	v_mov_b32_e32 v127, v0
	v_readfirstlane_b32 s4, v182
	s_nop 3
	s_cmp_lt_u32 s4, 256
	s_cbranch_scc1 .Lkprio_311
	s_setprio 1
.Lkprio_311:
.LBB0_311:
	s_add_u32 s4, s62, 0xfffc0080
	s_addc_u32 s5, s63, -1
	s_add_i32 s84, 0, 0x10000
	s_cmp_eq_u32 s82, 12
	s_cselect_b32 s65, s33, s5
	s_cselect_b32 s64, s36, s4
	s_cselect_b32 s35, s53, s79
	s_cselect_b32 s34, s55, s75
	s_add_i32 s4, 0, 0x14000
	v_add_u32_e32 v164, s84, v143
	v_add_u32_e32 v180, s4, v143
	ds_read_b128 v[138:141], v164
	ds_read_b128 v[156:159], v164 offset:1024
	ds_read_b128 v[160:163], v164 offset:2048
	ds_read_b128 v[164:167], v164 offset:3072
	ds_read_b128 v[168:171], v180
	ds_read_b128 v[172:175], v180 offset:1024
	ds_read_b128 v[176:179], v180 offset:2048
	ds_read_b128 v[204:207], v180 offset:3072
	v_lshl_add_u64 v[180:181], s[62:63], 0, v[134:135]
	s_add_i32 m0, s68, 0xc000
	ds_read_b128 v[208:211], v155
	ds_read_b128 v[212:215], v155 offset:1024
	ds_read_b128 v[216:219], v155 offset:2048
	ds_read_b128 v[220:223], v155 offset:3072
	ds_read_b128 v[224:227], v155 offset:4096
	ds_read_b128 v[228:231], v155 offset:5120
	ds_read_b128 v[232:235], v155 offset:6144
	ds_read_b128 v[236:239], v155 offset:7168
	global_load_lds_dwordx4 v[180:181], off
	v_lshl_add_u64 v[180:181], s[62:63], 0, v[136:137]
	s_add_i32 m0, s68, 0xe000
	s_nop 0
	global_load_lds_dwordx4 v[180:181], off
	s_waitcnt vmcnt(8)
	s_waitcnt lgkmcnt(0)
	s_barrier
	s_waitcnt lgkmcnt(0)
	v_mfma_f32_16x16x32_bf16 v[124:127], v[138:141], v[208:211], v[124:127]
	v_mfma_f32_16x16x32_bf16 v[120:123], v[160:163], v[208:211], v[120:123]
	v_mfma_f32_16x16x32_bf16 v[108:111], v[138:141], v[216:219], v[108:111]
	v_mfma_f32_16x16x32_bf16 v[104:107], v[160:163], v[216:219], v[104:107]
	v_mfma_f32_16x16x32_bf16 v[92:95], v[138:141], v[224:227], v[92:95]
	v_mfma_f32_16x16x32_bf16 v[88:91], v[160:163], v[224:227], v[88:91]
	v_mfma_f32_16x16x32_bf16 v[76:79], v[138:141], v[232:235], v[76:79]
	v_mfma_f32_16x16x32_bf16 v[72:75], v[160:163], v[232:235], v[72:75]
	v_mfma_f32_16x16x32_bf16 v[124:127], v[156:159], v[212:215], v[124:127]
	v_mfma_f32_16x16x32_bf16 v[120:123], v[164:167], v[212:215], v[120:123]
	v_mfma_f32_16x16x32_bf16 v[108:111], v[156:159], v[220:223], v[108:111]
	v_mfma_f32_16x16x32_bf16 v[104:107], v[164:167], v[220:223], v[104:107]
	v_mfma_f32_16x16x32_bf16 v[92:95], v[156:159], v[228:231], v[92:95]
	v_mfma_f32_16x16x32_bf16 v[88:91], v[164:167], v[228:231], v[88:91]
	v_mfma_f32_16x16x32_bf16 v[76:79], v[156:159], v[236:239], v[76:79]
	v_mfma_f32_16x16x32_bf16 v[72:75], v[164:167], v[236:239], v[72:75]
	v_mfma_f32_16x16x32_bf16 v[116:119], v[168:171], v[208:211], v[116:119]
	v_mfma_f32_16x16x32_bf16 v[112:115], v[176:179], v[208:211], v[112:115]
	v_mfma_f32_16x16x32_bf16 v[100:103], v[168:171], v[216:219], v[100:103]
	v_mfma_f32_16x16x32_bf16 v[96:99], v[176:179], v[216:219], v[96:99]
	v_mfma_f32_16x16x32_bf16 v[84:87], v[168:171], v[224:227], v[84:87]
	v_mfma_f32_16x16x32_bf16 v[80:83], v[176:179], v[224:227], v[80:83]
	v_mfma_f32_16x16x32_bf16 v[68:71], v[168:171], v[232:235], v[68:71]
	v_mfma_f32_16x16x32_bf16 v[64:67], v[176:179], v[232:235], v[64:67]
	v_mfma_f32_16x16x32_bf16 v[116:119], v[172:175], v[212:215], v[116:119]
	v_mfma_f32_16x16x32_bf16 v[112:115], v[204:207], v[212:215], v[112:115]
	v_mfma_f32_16x16x32_bf16 v[100:103], v[172:175], v[220:223], v[100:103]
	v_mfma_f32_16x16x32_bf16 v[96:99], v[204:207], v[220:223], v[96:99]
	v_mfma_f32_16x16x32_bf16 v[84:87], v[172:175], v[228:231], v[84:87]
	v_mfma_f32_16x16x32_bf16 v[80:83], v[204:207], v[228:231], v[80:83]
	v_mfma_f32_16x16x32_bf16 v[68:71], v[172:175], v[236:239], v[68:71]
	v_mfma_f32_16x16x32_bf16 v[64:67], v[204:207], v[236:239], v[64:67]
	s_barrier
	s_add_i32 s5, s84, s28
	v_lshl_add_u64 v[180:181], s[34:35], 0, v[144:145]
	s_mov_b32 m0, s5
	ds_read_b128 v[208:211], v155 offset:16384
	ds_read_b128 v[212:215], v155 offset:17408
	ds_read_b128 v[216:219], v155 offset:18432
	ds_read_b128 v[220:223], v155 offset:19456
	ds_read_b128 v[224:227], v155 offset:20480
	ds_read_b128 v[228:231], v155 offset:21504
	ds_read_b128 v[232:235], v155 offset:22528
	ds_read_b128 v[236:239], v155 offset:23552
	global_load_lds_dwordx4 v[180:181], off
	s_add_i32 m0, s5, 0x2000
	s_add_u32 s88, s34, 0x40000
	v_lshl_add_u64 v[240:241], s[34:35], 0, v[128:129]
	s_addc_u32 s89, s35, 0
	s_add_i32 s4, s4, s28
	global_load_lds_dwordx4 v[240:241], off
	v_lshl_add_u64 v[242:243], s[88:89], 0, v[144:145]
	s_mov_b32 m0, s4
	v_lshl_add_u64 v[244:245], s[64:65], 0, v[130:131]
	global_load_lds_dwordx4 v[242:243], off
	v_lshl_add_u64 v[242:243], s[88:89], 0, v[128:129]
	s_add_i32 m0, s4, 0x2000
	s_nop 0
	global_load_lds_dwordx4 v[242:243], off
	v_lshl_add_u64 v[242:243], s[64:65], 0, v[132:133]
	s_mov_b32 m0, s68
	s_nop 0
	global_load_lds_dwordx4 v[242:243], off
	s_mov_b32 m0, s69
	s_nop 0
	global_load_lds_dwordx4 v[244:245], off
	s_waitcnt vmcnt(8)
	s_waitcnt lgkmcnt(0)
	s_barrier
	s_waitcnt lgkmcnt(0)
	v_mfma_f32_16x16x32_bf16 v[60:63], v[138:141], v[208:211], v[60:63]
	v_mfma_f32_16x16x32_bf16 v[56:59], v[160:163], v[208:211], v[56:59]
	v_mfma_f32_16x16x32_bf16 v[44:47], v[138:141], v[216:219], v[44:47]
	v_mfma_f32_16x16x32_bf16 v[40:43], v[160:163], v[216:219], v[40:43]
	v_mfma_f32_16x16x32_bf16 v[28:31], v[138:141], v[224:227], v[28:31]
	v_mfma_f32_16x16x32_bf16 v[24:27], v[160:163], v[224:227], v[24:27]
	v_mfma_f32_16x16x32_bf16 v[12:15], v[138:141], v[232:235], v[12:15]
	v_mfma_f32_16x16x32_bf16 v[8:11], v[160:163], v[232:235], v[8:11]
	v_mfma_f32_16x16x32_bf16 v[60:63], v[156:159], v[212:215], v[60:63]
	v_mfma_f32_16x16x32_bf16 v[56:59], v[164:167], v[212:215], v[56:59]
	v_mfma_f32_16x16x32_bf16 v[44:47], v[156:159], v[220:223], v[44:47]
	v_mfma_f32_16x16x32_bf16 v[40:43], v[164:167], v[220:223], v[40:43]
	v_mfma_f32_16x16x32_bf16 v[28:31], v[156:159], v[228:231], v[28:31]
	v_mfma_f32_16x16x32_bf16 v[24:27], v[164:167], v[228:231], v[24:27]
	v_mfma_f32_16x16x32_bf16 v[12:15], v[156:159], v[236:239], v[12:15]
	v_mfma_f32_16x16x32_bf16 v[8:11], v[164:167], v[236:239], v[8:11]
	v_mfma_f32_16x16x32_bf16 v[52:55], v[168:171], v[208:211], v[52:55]
	v_mfma_f32_16x16x32_bf16 v[48:51], v[176:179], v[208:211], v[48:51]
	v_mfma_f32_16x16x32_bf16 v[36:39], v[168:171], v[216:219], v[36:39]
	v_mfma_f32_16x16x32_bf16 v[32:35], v[176:179], v[216:219], v[32:35]
	v_mfma_f32_16x16x32_bf16 v[20:23], v[168:171], v[224:227], v[20:23]
	v_mfma_f32_16x16x32_bf16 v[16:19], v[176:179], v[224:227], v[16:19]
	v_mfma_f32_16x16x32_bf16 v[4:7], v[168:171], v[232:235], v[4:7]
	v_mfma_f32_16x16x32_bf16 v[0:3], v[176:179], v[232:235], v[0:3]
	v_mfma_f32_16x16x32_bf16 v[52:55], v[172:175], v[212:215], v[52:55]
	v_mfma_f32_16x16x32_bf16 v[48:51], v[204:207], v[212:215], v[48:51]
	v_mfma_f32_16x16x32_bf16 v[36:39], v[172:175], v[220:223], v[36:39]
	v_mfma_f32_16x16x32_bf16 v[32:35], v[204:207], v[220:223], v[32:35]
	v_mfma_f32_16x16x32_bf16 v[20:23], v[172:175], v[228:231], v[20:23]
	v_mfma_f32_16x16x32_bf16 v[16:19], v[204:207], v[228:231], v[16:19]
	v_mfma_f32_16x16x32_bf16 v[4:7], v[172:175], v[236:239], v[4:7]
	v_mfma_f32_16x16x32_bf16 v[0:3], v[204:207], v[236:239], v[0:3]
	s_barrier
	s_add_i32 s4, 0, 0x18000
	s_add_i32 s5, 0, 0x1c000
	v_add_u32_e32 v164, s4, v143
	v_add_u32_e32 v202, s5, v143
	ds_read_b128 v[138:141], v164
	ds_read_b128 v[156:159], v164 offset:1024
	ds_read_b128 v[160:163], v164 offset:2048
	ds_read_b128 v[164:167], v164 offset:3072
	ds_read_b128 v[168:171], v202
	ds_read_b128 v[172:175], v202 offset:1024
	ds_read_b128 v[176:179], v202 offset:2048
	ds_read_b128 v[204:207], v202 offset:3072
	s_add_u32 s64, s64, 0x40000
	s_addc_u32 s65, s65, 0
	s_mov_b32 m0, s70
	v_lshl_add_u64 v[246:247], s[64:65], 0, v[132:133]
	ds_read_b128 v[208:211], v155 offset:32768
	ds_read_b128 v[212:215], v155 offset:33792
	ds_read_b128 v[216:219], v155 offset:34816
	ds_read_b128 v[220:223], v155 offset:35840
	ds_read_b128 v[224:227], v155 offset:36864
	ds_read_b128 v[228:231], v155 offset:37888
	ds_read_b128 v[232:235], v155 offset:38912
	ds_read_b128 v[236:239], v155 offset:39936
	global_load_lds_dwordx4 v[246:247], off
	v_lshl_add_u64 v[246:247], s[64:65], 0, v[130:131]
	s_mov_b32 m0, s71
	s_nop 0
	global_load_lds_dwordx4 v[246:247], off
	s_waitcnt vmcnt(8)
	s_waitcnt lgkmcnt(0)
	s_barrier
	s_waitcnt lgkmcnt(0)
	v_mfma_f32_16x16x32_bf16 v[124:127], v[138:141], v[208:211], v[124:127]
	v_mfma_f32_16x16x32_bf16 v[120:123], v[160:163], v[208:211], v[120:123]
	v_mfma_f32_16x16x32_bf16 v[108:111], v[138:141], v[216:219], v[108:111]
	v_mfma_f32_16x16x32_bf16 v[104:107], v[160:163], v[216:219], v[104:107]
	v_mfma_f32_16x16x32_bf16 v[92:95], v[138:141], v[224:227], v[92:95]
	v_mfma_f32_16x16x32_bf16 v[88:91], v[160:163], v[224:227], v[88:91]
	v_mfma_f32_16x16x32_bf16 v[76:79], v[138:141], v[232:235], v[76:79]
	v_mfma_f32_16x16x32_bf16 v[72:75], v[160:163], v[232:235], v[72:75]
	v_mfma_f32_16x16x32_bf16 v[124:127], v[156:159], v[212:215], v[124:127]
	v_mfma_f32_16x16x32_bf16 v[120:123], v[164:167], v[212:215], v[120:123]
	v_mfma_f32_16x16x32_bf16 v[108:111], v[156:159], v[220:223], v[108:111]
	v_mfma_f32_16x16x32_bf16 v[104:107], v[164:167], v[220:223], v[104:107]
	v_mfma_f32_16x16x32_bf16 v[92:95], v[156:159], v[228:231], v[92:95]
	v_mfma_f32_16x16x32_bf16 v[88:91], v[164:167], v[228:231], v[88:91]
	v_mfma_f32_16x16x32_bf16 v[76:79], v[156:159], v[236:239], v[76:79]
	v_mfma_f32_16x16x32_bf16 v[72:75], v[164:167], v[236:239], v[72:75]
	v_mfma_f32_16x16x32_bf16 v[116:119], v[168:171], v[208:211], v[116:119]
	v_mfma_f32_16x16x32_bf16 v[112:115], v[176:179], v[208:211], v[112:115]
	v_mfma_f32_16x16x32_bf16 v[100:103], v[168:171], v[216:219], v[100:103]
	v_mfma_f32_16x16x32_bf16 v[96:99], v[176:179], v[216:219], v[96:99]
	v_mfma_f32_16x16x32_bf16 v[84:87], v[168:171], v[224:227], v[84:87]
	v_mfma_f32_16x16x32_bf16 v[80:83], v[176:179], v[224:227], v[80:83]
	v_mfma_f32_16x16x32_bf16 v[68:71], v[168:171], v[232:235], v[68:71]
	v_mfma_f32_16x16x32_bf16 v[64:67], v[176:179], v[232:235], v[64:67]
	v_mfma_f32_16x16x32_bf16 v[116:119], v[172:175], v[212:215], v[116:119]
	v_mfma_f32_16x16x32_bf16 v[112:115], v[204:207], v[212:215], v[112:115]
	v_mfma_f32_16x16x32_bf16 v[100:103], v[172:175], v[220:223], v[100:103]
	v_mfma_f32_16x16x32_bf16 v[96:99], v[204:207], v[220:223], v[96:99]
	v_mfma_f32_16x16x32_bf16 v[84:87], v[172:175], v[228:231], v[84:87]
	v_mfma_f32_16x16x32_bf16 v[80:83], v[204:207], v[228:231], v[80:83]
	v_mfma_f32_16x16x32_bf16 v[68:71], v[172:175], v[236:239], v[68:71]
	v_mfma_f32_16x16x32_bf16 v[64:67], v[204:207], v[236:239], v[64:67]
	s_barrier
	s_add_i32 s4, s4, s28
	v_lshl_add_u64 v[180:181], v[180:181], 0, s[26:27]
	s_mov_b32 m0, s4
	ds_read_b128 v[208:211], v155 offset:49152
	ds_read_b128 v[212:215], v155 offset:50176
	ds_read_b128 v[216:219], v155 offset:51200
	ds_read_b128 v[220:223], v155 offset:52224
	ds_read_b128 v[224:227], v155 offset:53248
	ds_read_b128 v[228:231], v155 offset:54272
	ds_read_b128 v[232:235], v155 offset:55296
	ds_read_b128 v[236:239], v155 offset:56320
	global_load_lds_dwordx4 v[180:181], off
	s_add_i32 m0, s4, 0x2000
	s_add_u32 s34, s34, 0x40080
	v_lshl_add_u64 v[180:181], v[240:241], 0, s[26:27]
	s_addc_u32 s35, s35, 0
	s_add_i32 s4, s5, s28
	global_load_lds_dwordx4 v[180:181], off
	v_lshl_add_u64 v[180:181], s[34:35], 0, v[144:145]
	s_mov_b32 m0, s4
	s_nop 0
	global_load_lds_dwordx4 v[180:181], off
	v_lshl_add_u64 v[180:181], s[34:35], 0, v[128:129]
	s_add_i32 m0, s4, 0x2000
	s_nop 0
	global_load_lds_dwordx4 v[180:181], off
	v_lshl_add_u64 v[180:181], v[242:243], 0, s[26:27]
	s_mov_b32 m0, s72
	s_nop 0
	global_load_lds_dwordx4 v[180:181], off
	v_lshl_add_u64 v[180:181], v[244:245], 0, s[26:27]
	s_mov_b32 m0, s73
	s_nop 0
	global_load_lds_dwordx4 v[180:181], off
	s_waitcnt vmcnt(8)
	s_waitcnt lgkmcnt(0)
	s_barrier
	s_waitcnt lgkmcnt(0)
	v_mfma_f32_16x16x32_bf16 v[60:63], v[138:141], v[208:211], v[60:63]
	v_mfma_f32_16x16x32_bf16 v[56:59], v[160:163], v[208:211], v[56:59]
	v_mfma_f32_16x16x32_bf16 v[44:47], v[138:141], v[216:219], v[44:47]
	v_mfma_f32_16x16x32_bf16 v[40:43], v[160:163], v[216:219], v[40:43]
	v_mfma_f32_16x16x32_bf16 v[28:31], v[138:141], v[224:227], v[28:31]
	v_mfma_f32_16x16x32_bf16 v[24:27], v[160:163], v[224:227], v[24:27]
	v_mfma_f32_16x16x32_bf16 v[12:15], v[138:141], v[232:235], v[12:15]
	v_mfma_f32_16x16x32_bf16 v[8:11], v[160:163], v[232:235], v[8:11]
	v_mfma_f32_16x16x32_bf16 v[60:63], v[156:159], v[212:215], v[60:63]
	v_mfma_f32_16x16x32_bf16 v[56:59], v[164:167], v[212:215], v[56:59]
	v_mfma_f32_16x16x32_bf16 v[44:47], v[156:159], v[220:223], v[44:47]
	v_mfma_f32_16x16x32_bf16 v[40:43], v[164:167], v[220:223], v[40:43]
	v_mfma_f32_16x16x32_bf16 v[28:31], v[156:159], v[228:231], v[28:31]
	v_mfma_f32_16x16x32_bf16 v[24:27], v[164:167], v[228:231], v[24:27]
	v_mfma_f32_16x16x32_bf16 v[12:15], v[156:159], v[236:239], v[12:15]
	v_mfma_f32_16x16x32_bf16 v[8:11], v[164:167], v[236:239], v[8:11]
	v_mfma_f32_16x16x32_bf16 v[52:55], v[168:171], v[208:211], v[52:55]
	v_mfma_f32_16x16x32_bf16 v[48:51], v[176:179], v[208:211], v[48:51]
	v_mfma_f32_16x16x32_bf16 v[36:39], v[168:171], v[216:219], v[36:39]
	v_mfma_f32_16x16x32_bf16 v[32:35], v[176:179], v[216:219], v[32:35]
	v_mfma_f32_16x16x32_bf16 v[20:23], v[168:171], v[224:227], v[20:23]
	v_mfma_f32_16x16x32_bf16 v[16:19], v[176:179], v[224:227], v[16:19]
	v_mfma_f32_16x16x32_bf16 v[4:7], v[168:171], v[232:235], v[4:7]
	v_mfma_f32_16x16x32_bf16 v[0:3], v[176:179], v[232:235], v[0:3]
	v_mfma_f32_16x16x32_bf16 v[52:55], v[172:175], v[212:215], v[52:55]
	v_mfma_f32_16x16x32_bf16 v[48:51], v[204:207], v[212:215], v[48:51]
	v_mfma_f32_16x16x32_bf16 v[36:39], v[172:175], v[220:223], v[36:39]
	v_mfma_f32_16x16x32_bf16 v[32:35], v[204:207], v[220:223], v[32:35]
	v_mfma_f32_16x16x32_bf16 v[20:23], v[172:175], v[228:231], v[20:23]
	v_mfma_f32_16x16x32_bf16 v[16:19], v[204:207], v[228:231], v[16:19]
	v_mfma_f32_16x16x32_bf16 v[4:7], v[172:175], v[236:239], v[4:7]
	v_mfma_f32_16x16x32_bf16 v[0:3], v[204:207], v[236:239], v[0:3]
	s_barrier
	s_add_i32 s82, s82, 2
	s_add_u32 s62, s62, 0x100
	s_addc_u32 s63, s63, 0
	s_add_u32 s75, s75, 0x100
	s_addc_u32 s79, s79, 0
	s_cmp_gt_u32 s82, 13
	s_cbranch_scc0 .LBB0_311
	s_setprio 0
	v_lshl_add_u32 v140, s2, 8, v142
	v_ashrrev_i32_e32 v141, 31, v140
	v_lshl_add_u64 v[156:157], v[140:141], 4, s[48:49]
	global_load_dwordx4 v[208:211], v[156:157], off
	global_load_dwordx4 v[212:215], v[156:157], off offset:256
	global_load_dwordx4 v[216:219], v[156:157], off offset:512
	global_load_dwordx4 v[220:223], v[156:157], off offset:768
	global_load_dwordx4 v[224:227], v[156:157], off offset:2048
	global_load_dwordx4 v[228:231], v[156:157], off offset:2304
	global_load_dwordx4 v[232:235], v[156:157], off offset:2560
	global_load_dwordx4 v[236:239], v[156:157], off offset:2816
	s_and_b64 vcc, exec, s[50:51]
	s_cbranch_vccz .LBB0_314
	s_barrier

.LBB0_405:
	s_add_u32 s3, s62, 0x100
	v_mov_b32_e32 v0, 0
	s_addc_u32 s28, s63, 0
	s_mov_b32 s29, -2
	s_waitcnt lgkmcnt(0)
	v_mov_b32_e32 v1, v0
	v_mov_b32_e32 v2, v0
	v_mov_b32_e32 v3, v0
	v_mov_b32_e32 v4, v0
	v_mov_b32_e32 v5, v0
	v_mov_b32_e32 v6, v0
	v_mov_b32_e32 v7, v0
	v_mov_b32_e32 v16, v0
	v_mov_b32_e32 v17, v0
	v_mov_b32_e32 v18, v0
	v_mov_b32_e32 v19, v0
	v_mov_b32_e32 v20, v0
	v_mov_b32_e32 v21, v0
	v_mov_b32_e32 v22, v0
	v_mov_b32_e32 v23, v0
	v_mov_b32_e32 v32, v0
	v_mov_b32_e32 v33, v0
	v_mov_b32_e32 v34, v0
	v_mov_b32_e32 v35, v0
	v_mov_b32_e32 v36, v0
	v_mov_b32_e32 v37, v0
	v_mov_b32_e32 v38, v0
	v_mov_b32_e32 v39, v0
	v_mov_b32_e32 v48, v0
	v_mov_b32_e32 v49, v0
	v_mov_b32_e32 v50, v0
	v_mov_b32_e32 v51, v0
	v_mov_b32_e32 v52, v0
	v_mov_b32_e32 v53, v0
	v_mov_b32_e32 v54, v0
	v_mov_b32_e32 v55, v0
	v_mov_b32_e32 v8, v0
	v_mov_b32_e32 v9, v0
	v_mov_b32_e32 v10, v0
	v_mov_b32_e32 v11, v0
	v_mov_b32_e32 v12, v0
	v_mov_b32_e32 v13, v0
	v_mov_b32_e32 v14, v0
	v_mov_b32_e32 v15, v0
	v_mov_b32_e32 v24, v0
	v_mov_b32_e32 v25, v0
	v_mov_b32_e32 v26, v0
	v_mov_b32_e32 v27, v0
	v_mov_b32_e32 v28, v0
	v_mov_b32_e32 v29, v0
	v_mov_b32_e32 v30, v0
	v_mov_b32_e32 v31, v0
	v_mov_b32_e32 v40, v0
	v_mov_b32_e32 v41, v0
	v_mov_b32_e32 v42, v0
	v_mov_b32_e32 v43, v0
	v_mov_b32_e32 v44, v0
	v_mov_b32_e32 v45, v0
	v_mov_b32_e32 v46, v0
	v_mov_b32_e32 v47, v0
	v_mov_b32_e32 v56, v0
	v_mov_b32_e32 v57, v0
	v_mov_b32_e32 v58, v0
	v_mov_b32_e32 v59, v0
	v_mov_b32_e32 v60, v0
	v_mov_b32_e32 v61, v0
	v_mov_b32_e32 v62, v0
	v_mov_b32_e32 v63, v0
	v_mov_b32_e32 v64, v0
	v_mov_b32_e32 v65, v0
	v_mov_b32_e32 v66, v0
	v_mov_b32_e32 v67, v0
	v_mov_b32_e32 v68, v0
	v_mov_b32_e32 v69, v0
	v_mov_b32_e32 v70, v0
	v_mov_b32_e32 v71, v0
	v_mov_b32_e32 v80, v0
	v_mov_b32_e32 v81, v0
	v_mov_b32_e32 v82, v0
	v_mov_b32_e32 v83, v0
	v_mov_b32_e32 v84, v0
	v_mov_b32_e32 v85, v0
	v_mov_b32_e32 v86, v0
	v_mov_b32_e32 v87, v0
	v_mov_b32_e32 v96, v0
	v_mov_b32_e32 v97, v0
	v_mov_b32_e32 v98, v0
	v_mov_b32_e32 v99, v0
	v_mov_b32_e32 v100, v0
	v_mov_b32_e32 v101, v0
	v_mov_b32_e32 v102, v0
	v_mov_b32_e32 v103, v0
	v_mov_b32_e32 v112, v0
	v_mov_b32_e32 v113, v0
	v_mov_b32_e32 v114, v0
	v_mov_b32_e32 v115, v0
	v_mov_b32_e32 v116, v0
	v_mov_b32_e32 v117, v0
	v_mov_b32_e32 v118, v0
	v_mov_b32_e32 v119, v0
	v_mov_b32_e32 v72, v0
	v_mov_b32_e32 v73, v0
	v_mov_b32_e32 v74, v0
	v_mov_b32_e32 v75, v0
	v_mov_b32_e32 v76, v0
	v_mov_b32_e32 v77, v0
	v_mov_b32_e32 v78, v0
	v_mov_b32_e32 v79, v0
	v_mov_b32_e32 v88, v0
	v_mov_b32_e32 v89, v0
	v_mov_b32_e32 v90, v0
	v_mov_b32_e32 v91, v0
	v_mov_b32_e32 v92, v0
	v_mov_b32_e32 v93, v0
	v_mov_b32_e32 v94, v0
	v_mov_b32_e32 v95, v0
	v_mov_b32_e32 v104, v0
	v_mov_b32_e32 v105, v0
	v_mov_b32_e32 v106, v0
	v_mov_b32_e32 v107, v0
	v_mov_b32_e32 v108, v0
	v_mov_b32_e32 v109, v0
	v_mov_b32_e32 v110, v0
	v_mov_b32_e32 v111, v0
	v_mov_b32_e32 v120, v0
	v_mov_b32_e32 v121, v0
	v_mov_b32_e32 v122, v0
	v_mov_b32_e32 v123, v0
	v_mov_b32_e32 v124, v0
	v_mov_b32_e32 v125, v0
	v_mov_b32_e32 v126, v0
	v_mov_b32_e32 v127, v0
	v_readfirstlane_b32 s4, v182
	s_nop 3
	s_cmp_lt_u32 s4, 256
	s_cbranch_scc1 .Lkprio_406
	s_setprio 1
.Lkprio_406:
.LBB0_406:
	s_add_u32 s62, s60, 0x100
	s_addc_u32 s63, s61, 0
	s_add_i32 s4, 0, 0x10000
	s_cmp_eq_u32 s29, 40
	s_cselect_b32 s65, s45, s63
	s_cselect_b32 s64, s44, s62
	v_add_u32_e32 v142, s4, v160
	s_cselect_b32 s35, s59, s28
	s_cselect_b32 s34, s58, s3
	s_add_i32 s5, 0, 0x14000
	ds_read_b128 v[138:141], v142
	ds_read_b128 v[154:157], v142 offset:1024
	ds_read_b128 v[172:175], v142 offset:2048
	ds_read_b128 v[176:179], v142 offset:3072
	v_add_u32_e32 v142, s5, v160
	ds_read_b128 v[204:207], v142
	ds_read_b128 v[208:211], v142 offset:1024
	ds_read_b128 v[212:215], v142 offset:2048
	ds_read_b128 v[216:219], v142 offset:3072
	v_lshl_add_u64 v[142:143], s[60:61], 0, v[134:135]
	s_add_i32 m0, s36, 0xc000
	ds_read_b128 v[220:223], v170
	ds_read_b128 v[224:227], v170 offset:1024
	ds_read_b128 v[228:231], v170 offset:2048
	ds_read_b128 v[232:235], v170 offset:3072
	ds_read_b128 v[236:239], v170 offset:4096
	ds_read_b128 v[240:243], v170 offset:5120
	ds_read_b128 v[244:247], v170 offset:6144
	ds_read_b128 v[248:251], v170 offset:7168
	global_load_lds_dwordx4 v[142:143], off
	v_lshl_add_u64 v[142:143], s[60:61], 0, v[136:137]
	s_add_i32 m0, s36, 0xe000
	s_nop 0
	global_load_lds_dwordx4 v[142:143], off
	s_waitcnt vmcnt(8)
	s_waitcnt lgkmcnt(0)
	s_barrier
	s_waitcnt lgkmcnt(0)
	v_mfma_f32_16x16x32_bf16 v[124:127], v[138:141], v[220:223], v[124:127]
	v_mfma_f32_16x16x32_bf16 v[120:123], v[172:175], v[220:223], v[120:123]
	v_mfma_f32_16x16x32_bf16 v[108:111], v[138:141], v[228:231], v[108:111]
	v_mfma_f32_16x16x32_bf16 v[104:107], v[172:175], v[228:231], v[104:107]
	v_mfma_f32_16x16x32_bf16 v[92:95], v[138:141], v[236:239], v[92:95]
	v_mfma_f32_16x16x32_bf16 v[88:91], v[172:175], v[236:239], v[88:91]
	v_mfma_f32_16x16x32_bf16 v[76:79], v[138:141], v[244:247], v[76:79]
	v_mfma_f32_16x16x32_bf16 v[72:75], v[172:175], v[244:247], v[72:75]
	v_mfma_f32_16x16x32_bf16 v[124:127], v[154:157], v[224:227], v[124:127]
	v_mfma_f32_16x16x32_bf16 v[120:123], v[176:179], v[224:227], v[120:123]
	v_mfma_f32_16x16x32_bf16 v[108:111], v[154:157], v[232:235], v[108:111]
	v_mfma_f32_16x16x32_bf16 v[104:107], v[176:179], v[232:235], v[104:107]
	v_mfma_f32_16x16x32_bf16 v[92:95], v[154:157], v[240:243], v[92:95]
	v_mfma_f32_16x16x32_bf16 v[88:91], v[176:179], v[240:243], v[88:91]
	v_mfma_f32_16x16x32_bf16 v[76:79], v[154:157], v[248:251], v[76:79]
	v_mfma_f32_16x16x32_bf16 v[72:75], v[176:179], v[248:251], v[72:75]
	v_mfma_f32_16x16x32_bf16 v[116:119], v[204:207], v[220:223], v[116:119]
	v_mfma_f32_16x16x32_bf16 v[112:115], v[212:215], v[220:223], v[112:115]
	v_mfma_f32_16x16x32_bf16 v[100:103], v[204:207], v[228:231], v[100:103]
	v_mfma_f32_16x16x32_bf16 v[96:99], v[212:215], v[228:231], v[96:99]
	v_mfma_f32_16x16x32_bf16 v[84:87], v[204:207], v[236:239], v[84:87]
	v_mfma_f32_16x16x32_bf16 v[80:83], v[212:215], v[236:239], v[80:83]
	v_mfma_f32_16x16x32_bf16 v[68:71], v[204:207], v[244:247], v[68:71]
	v_mfma_f32_16x16x32_bf16 v[64:67], v[212:215], v[244:247], v[64:67]
	v_mfma_f32_16x16x32_bf16 v[116:119], v[208:211], v[224:227], v[116:119]
	v_mfma_f32_16x16x32_bf16 v[112:115], v[216:219], v[224:227], v[112:115]
	v_mfma_f32_16x16x32_bf16 v[100:103], v[208:211], v[232:235], v[100:103]
	v_mfma_f32_16x16x32_bf16 v[96:99], v[216:219], v[232:235], v[96:99]
	v_mfma_f32_16x16x32_bf16 v[84:87], v[208:211], v[240:243], v[84:87]
	v_mfma_f32_16x16x32_bf16 v[80:83], v[216:219], v[240:243], v[80:83]
	v_mfma_f32_16x16x32_bf16 v[68:71], v[208:211], v[248:251], v[68:71]
	v_mfma_f32_16x16x32_bf16 v[64:67], v[216:219], v[248:251], v[64:67]
	s_barrier
	s_add_i32 s4, s4, s33
	v_lshl_add_u64 v[142:143], s[34:35], 0, v[128:129]
	s_mov_b32 m0, s4
	ds_read_b128 v[220:223], v170 offset:16384
	ds_read_b128 v[224:227], v170 offset:17408
	ds_read_b128 v[228:231], v170 offset:18432
	ds_read_b128 v[232:235], v170 offset:19456
	ds_read_b128 v[236:239], v170 offset:20480
	ds_read_b128 v[240:243], v170 offset:21504
	ds_read_b128 v[244:247], v170 offset:22528
	ds_read_b128 v[248:251], v170 offset:23552
	global_load_lds_dwordx4 v[142:143], off
	s_add_i32 m0, s4, 0x2000
	s_add_u32 s60, s34, 0xb0000
	v_lshl_add_u64 v[158:159], s[34:35], 0, v[130:131]
	s_addc_u32 s61, s35, 0
	s_add_i32 s4, s5, s33
	global_load_lds_dwordx4 v[158:159], off
	v_lshl_add_u64 v[180:181], s[60:61], 0, v[128:129]
	s_mov_b32 m0, s4
	v_lshl_add_u64 v[202:203], s[64:65], 0, v[130:131]
	global_load_lds_dwordx4 v[180:181], off
	v_lshl_add_u64 v[180:181], s[60:61], 0, v[130:131]
	s_add_i32 m0, s4, 0x2000
	s_nop 0
	global_load_lds_dwordx4 v[180:181], off
	v_lshl_add_u64 v[180:181], s[64:65], 0, v[128:129]
	s_mov_b32 m0, s36
	s_nop 0
	global_load_lds_dwordx4 v[180:181], off
	s_mov_b32 m0, s70
	s_nop 0
	global_load_lds_dwordx4 v[202:203], off
	s_waitcnt vmcnt(8)
	s_waitcnt lgkmcnt(0)
	s_barrier
	s_waitcnt lgkmcnt(0)
	v_mfma_f32_16x16x32_bf16 v[60:63], v[138:141], v[220:223], v[60:63]
	v_mfma_f32_16x16x32_bf16 v[56:59], v[172:175], v[220:223], v[56:59]
	v_mfma_f32_16x16x32_bf16 v[44:47], v[138:141], v[228:231], v[44:47]
	v_mfma_f32_16x16x32_bf16 v[40:43], v[172:175], v[228:231], v[40:43]
	v_mfma_f32_16x16x32_bf16 v[28:31], v[138:141], v[236:239], v[28:31]
	v_mfma_f32_16x16x32_bf16 v[24:27], v[172:175], v[236:239], v[24:27]
	v_mfma_f32_16x16x32_bf16 v[12:15], v[138:141], v[244:247], v[12:15]
	v_mfma_f32_16x16x32_bf16 v[8:11], v[172:175], v[244:247], v[8:11]
	v_mfma_f32_16x16x32_bf16 v[60:63], v[154:157], v[224:227], v[60:63]
	v_mfma_f32_16x16x32_bf16 v[56:59], v[176:179], v[224:227], v[56:59]
	v_mfma_f32_16x16x32_bf16 v[44:47], v[154:157], v[232:235], v[44:47]
	v_mfma_f32_16x16x32_bf16 v[40:43], v[176:179], v[232:235], v[40:43]
	v_mfma_f32_16x16x32_bf16 v[28:31], v[154:157], v[240:243], v[28:31]
	v_mfma_f32_16x16x32_bf16 v[24:27], v[176:179], v[240:243], v[24:27]
	v_mfma_f32_16x16x32_bf16 v[12:15], v[154:157], v[248:251], v[12:15]
	v_mfma_f32_16x16x32_bf16 v[8:11], v[176:179], v[248:251], v[8:11]
	v_mfma_f32_16x16x32_bf16 v[52:55], v[204:207], v[220:223], v[52:55]
	v_mfma_f32_16x16x32_bf16 v[48:51], v[212:215], v[220:223], v[48:51]
	v_mfma_f32_16x16x32_bf16 v[36:39], v[204:207], v[228:231], v[36:39]
	v_mfma_f32_16x16x32_bf16 v[32:35], v[212:215], v[228:231], v[32:35]
	v_mfma_f32_16x16x32_bf16 v[20:23], v[204:207], v[236:239], v[20:23]
	v_mfma_f32_16x16x32_bf16 v[16:19], v[212:215], v[236:239], v[16:19]
	v_mfma_f32_16x16x32_bf16 v[4:7], v[204:207], v[244:247], v[4:7]
	v_mfma_f32_16x16x32_bf16 v[0:3], v[212:215], v[244:247], v[0:3]
	v_mfma_f32_16x16x32_bf16 v[52:55], v[208:211], v[224:227], v[52:55]
	v_mfma_f32_16x16x32_bf16 v[48:51], v[216:219], v[224:227], v[48:51]
	v_mfma_f32_16x16x32_bf16 v[36:39], v[208:211], v[232:235], v[36:39]
	v_mfma_f32_16x16x32_bf16 v[32:35], v[216:219], v[232:235], v[32:35]
	v_mfma_f32_16x16x32_bf16 v[20:23], v[208:211], v[240:243], v[20:23]
	v_mfma_f32_16x16x32_bf16 v[16:19], v[216:219], v[240:243], v[16:19]
	v_mfma_f32_16x16x32_bf16 v[4:7], v[208:211], v[248:251], v[4:7]
	v_mfma_f32_16x16x32_bf16 v[0:3], v[216:219], v[248:251], v[0:3]
	s_barrier
	s_add_i32 s4, 0, 0x18000
	v_add_u32_e32 v144, s4, v160
	s_add_i32 s5, 0, 0x1c000
	ds_read_b128 v[138:141], v144
	ds_read_b128 v[154:157], v144 offset:1024
	ds_read_b128 v[172:175], v144 offset:2048
	ds_read_b128 v[176:179], v144 offset:3072
	v_add_u32_e32 v144, s5, v160
	ds_read_b128 v[204:207], v144
	ds_read_b128 v[208:211], v144 offset:1024
	ds_read_b128 v[212:215], v144 offset:2048
	ds_read_b128 v[216:219], v144 offset:3072
	s_add_u32 s60, s64, 0xb0000
	s_addc_u32 s61, s65, 0
	s_mov_b32 m0, s71
	v_lshl_add_u64 v[252:253], s[60:61], 0, v[128:129]
	ds_read_b128 v[220:223], v170 offset:32768
	ds_read_b128 v[224:227], v170 offset:33792
	ds_read_b128 v[228:231], v170 offset:34816
	ds_read_b128 v[232:235], v170 offset:35840
	ds_read_b128 v[236:239], v170 offset:36864
	ds_read_b128 v[240:243], v170 offset:37888
	ds_read_b128 v[244:247], v170 offset:38912
	ds_read_b128 v[248:251], v170 offset:39936
	global_load_lds_dwordx4 v[252:253], off
	v_lshl_add_u64 v[252:253], s[60:61], 0, v[130:131]
	s_mov_b32 m0, s72
	s_nop 0
	global_load_lds_dwordx4 v[252:253], off
	s_waitcnt vmcnt(8)
	s_waitcnt lgkmcnt(0)
	s_barrier
	s_waitcnt lgkmcnt(0)
	v_mfma_f32_16x16x32_bf16 v[124:127], v[138:141], v[220:223], v[124:127]
	v_mfma_f32_16x16x32_bf16 v[120:123], v[172:175], v[220:223], v[120:123]
	v_mfma_f32_16x16x32_bf16 v[108:111], v[138:141], v[228:231], v[108:111]
	v_mfma_f32_16x16x32_bf16 v[104:107], v[172:175], v[228:231], v[104:107]
	v_mfma_f32_16x16x32_bf16 v[92:95], v[138:141], v[236:239], v[92:95]
	v_mfma_f32_16x16x32_bf16 v[88:91], v[172:175], v[236:239], v[88:91]
	v_mfma_f32_16x16x32_bf16 v[76:79], v[138:141], v[244:247], v[76:79]
	v_mfma_f32_16x16x32_bf16 v[72:75], v[172:175], v[244:247], v[72:75]
	v_mfma_f32_16x16x32_bf16 v[124:127], v[154:157], v[224:227], v[124:127]
	v_mfma_f32_16x16x32_bf16 v[120:123], v[176:179], v[224:227], v[120:123]
	v_mfma_f32_16x16x32_bf16 v[108:111], v[154:157], v[232:235], v[108:111]
	v_mfma_f32_16x16x32_bf16 v[104:107], v[176:179], v[232:235], v[104:107]
	v_mfma_f32_16x16x32_bf16 v[92:95], v[154:157], v[240:243], v[92:95]
	v_mfma_f32_16x16x32_bf16 v[88:91], v[176:179], v[240:243], v[88:91]
	v_mfma_f32_16x16x32_bf16 v[76:79], v[154:157], v[248:251], v[76:79]
	v_mfma_f32_16x16x32_bf16 v[72:75], v[176:179], v[248:251], v[72:75]
	v_mfma_f32_16x16x32_bf16 v[116:119], v[204:207], v[220:223], v[116:119]
	v_mfma_f32_16x16x32_bf16 v[112:115], v[212:215], v[220:223], v[112:115]
	v_mfma_f32_16x16x32_bf16 v[100:103], v[204:207], v[228:231], v[100:103]
	v_mfma_f32_16x16x32_bf16 v[96:99], v[212:215], v[228:231], v[96:99]
	v_mfma_f32_16x16x32_bf16 v[84:87], v[204:207], v[236:239], v[84:87]
	v_mfma_f32_16x16x32_bf16 v[80:83], v[212:215], v[236:239], v[80:83]
	v_mfma_f32_16x16x32_bf16 v[68:71], v[204:207], v[244:247], v[68:71]
	v_mfma_f32_16x16x32_bf16 v[64:67], v[212:215], v[244:247], v[64:67]
	v_mfma_f32_16x16x32_bf16 v[116:119], v[208:211], v[224:227], v[116:119]
	v_mfma_f32_16x16x32_bf16 v[112:115], v[216:219], v[224:227], v[112:115]
	v_mfma_f32_16x16x32_bf16 v[100:103], v[208:211], v[232:235], v[100:103]
	v_mfma_f32_16x16x32_bf16 v[96:99], v[216:219], v[232:235], v[96:99]
	v_mfma_f32_16x16x32_bf16 v[84:87], v[208:211], v[240:243], v[84:87]
	v_mfma_f32_16x16x32_bf16 v[80:83], v[216:219], v[240:243], v[80:83]
	v_mfma_f32_16x16x32_bf16 v[68:71], v[208:211], v[248:251], v[68:71]
	v_mfma_f32_16x16x32_bf16 v[64:67], v[216:219], v[248:251], v[64:67]
	s_barrier
	s_add_i32 s4, s4, s33
	v_lshl_add_u64 v[142:143], v[142:143], 0, s[26:27]
	s_mov_b32 m0, s4
	ds_read_b128 v[220:223], v170 offset:49152
	ds_read_b128 v[224:227], v170 offset:50176
	ds_read_b128 v[228:231], v170 offset:51200
	ds_read_b128 v[232:235], v170 offset:52224
	ds_read_b128 v[236:239], v170 offset:53248
	ds_read_b128 v[240:243], v170 offset:54272
	ds_read_b128 v[244:247], v170 offset:55296
	ds_read_b128 v[248:251], v170 offset:56320
	global_load_lds_dwordx4 v[142:143], off
	s_add_i32 m0, s4, 0x2000
	s_add_u32 s34, s34, 0xb0080
	v_lshl_add_u64 v[142:143], v[158:159], 0, s[26:27]
	s_addc_u32 s35, s35, 0
	s_add_i32 s4, s5, s33
	global_load_lds_dwordx4 v[142:143], off
	v_lshl_add_u64 v[142:143], s[34:35], 0, v[128:129]
	s_mov_b32 m0, s4
	s_nop 0
	global_load_lds_dwordx4 v[142:143], off
	v_lshl_add_u64 v[142:143], s[34:35], 0, v[130:131]
	s_add_i32 m0, s4, 0x2000
	s_nop 0
	global_load_lds_dwordx4 v[142:143], off
	v_lshl_add_u64 v[142:143], v[180:181], 0, s[26:27]
	s_mov_b32 m0, s73
	s_nop 0
	global_load_lds_dwordx4 v[142:143], off
	v_lshl_add_u64 v[142:143], v[202:203], 0, s[26:27]
	s_mov_b32 m0, s74
	s_nop 0
	global_load_lds_dwordx4 v[142:143], off
	s_waitcnt vmcnt(8)
	s_waitcnt lgkmcnt(0)
	s_barrier
	s_waitcnt lgkmcnt(0)
	v_mfma_f32_16x16x32_bf16 v[60:63], v[138:141], v[220:223], v[60:63]
	v_mfma_f32_16x16x32_bf16 v[56:59], v[172:175], v[220:223], v[56:59]
	v_mfma_f32_16x16x32_bf16 v[44:47], v[138:141], v[228:231], v[44:47]
	v_mfma_f32_16x16x32_bf16 v[40:43], v[172:175], v[228:231], v[40:43]
	v_mfma_f32_16x16x32_bf16 v[28:31], v[138:141], v[236:239], v[28:31]
	v_mfma_f32_16x16x32_bf16 v[24:27], v[172:175], v[236:239], v[24:27]
	v_mfma_f32_16x16x32_bf16 v[12:15], v[138:141], v[244:247], v[12:15]
	v_mfma_f32_16x16x32_bf16 v[8:11], v[172:175], v[244:247], v[8:11]
	v_mfma_f32_16x16x32_bf16 v[60:63], v[154:157], v[224:227], v[60:63]
	v_mfma_f32_16x16x32_bf16 v[56:59], v[176:179], v[224:227], v[56:59]
	v_mfma_f32_16x16x32_bf16 v[44:47], v[154:157], v[232:235], v[44:47]
	v_mfma_f32_16x16x32_bf16 v[40:43], v[176:179], v[232:235], v[40:43]
	v_mfma_f32_16x16x32_bf16 v[28:31], v[154:157], v[240:243], v[28:31]
	v_mfma_f32_16x16x32_bf16 v[24:27], v[176:179], v[240:243], v[24:27]
	v_mfma_f32_16x16x32_bf16 v[12:15], v[154:157], v[248:251], v[12:15]
	v_mfma_f32_16x16x32_bf16 v[8:11], v[176:179], v[248:251], v[8:11]
	v_mfma_f32_16x16x32_bf16 v[52:55], v[204:207], v[220:223], v[52:55]
	v_mfma_f32_16x16x32_bf16 v[48:51], v[212:215], v[220:223], v[48:51]
	v_mfma_f32_16x16x32_bf16 v[36:39], v[204:207], v[228:231], v[36:39]
	v_mfma_f32_16x16x32_bf16 v[32:35], v[212:215], v[228:231], v[32:35]
	v_mfma_f32_16x16x32_bf16 v[20:23], v[204:207], v[236:239], v[20:23]
	v_mfma_f32_16x16x32_bf16 v[16:19], v[212:215], v[236:239], v[16:19]
	v_mfma_f32_16x16x32_bf16 v[4:7], v[204:207], v[244:247], v[4:7]
	v_mfma_f32_16x16x32_bf16 v[0:3], v[212:215], v[244:247], v[0:3]
	v_mfma_f32_16x16x32_bf16 v[52:55], v[208:211], v[224:227], v[52:55]
	v_mfma_f32_16x16x32_bf16 v[48:51], v[216:219], v[224:227], v[48:51]
	v_mfma_f32_16x16x32_bf16 v[36:39], v[208:211], v[232:235], v[36:39]
	v_mfma_f32_16x16x32_bf16 v[32:35], v[216:219], v[232:235], v[32:35]
	v_mfma_f32_16x16x32_bf16 v[20:23], v[208:211], v[240:243], v[20:23]
	v_mfma_f32_16x16x32_bf16 v[16:19], v[216:219], v[240:243], v[16:19]
	v_mfma_f32_16x16x32_bf16 v[4:7], v[208:211], v[248:251], v[4:7]
	v_mfma_f32_16x16x32_bf16 v[0:3], v[216:219], v[248:251], v[0:3]
	s_barrier
	s_add_i32 s29, s29, 2
	s_add_u32 s3, s3, 0x100
	s_addc_u32 s28, s28, 0
	s_cmp_gt_u32 s29, 41
	s_mov_b64 s[60:61], s[62:63]
	s_cbranch_scc0 .LBB0_406
	s_setprio 0
	s_and_b64 vcc, exec, s[54:55]
	s_cbranch_vccz .LBB0_409
	s_barrier

.LBB0_455:
	s_add_u32 s28, s60, 0x100
	v_mov_b32_e32 v0, 0
	s_addc_u32 s29, s61, 0
	s_mov_b32 s51, -2
	s_waitcnt lgkmcnt(0)
	v_mov_b32_e32 v1, v0
	v_mov_b32_e32 v2, v0
	v_mov_b32_e32 v3, v0
	v_mov_b32_e32 v4, v0
	v_mov_b32_e32 v5, v0
	v_mov_b32_e32 v6, v0
	v_mov_b32_e32 v7, v0
	v_mov_b32_e32 v16, v0
	v_mov_b32_e32 v17, v0
	v_mov_b32_e32 v18, v0
	v_mov_b32_e32 v19, v0
	v_mov_b32_e32 v20, v0
	v_mov_b32_e32 v21, v0
	v_mov_b32_e32 v22, v0
	v_mov_b32_e32 v23, v0
	v_mov_b32_e32 v32, v0
	v_mov_b32_e32 v33, v0
	v_mov_b32_e32 v34, v0
	v_mov_b32_e32 v35, v0
	v_mov_b32_e32 v36, v0
	v_mov_b32_e32 v37, v0
	v_mov_b32_e32 v38, v0
	v_mov_b32_e32 v39, v0
	v_mov_b32_e32 v48, v0
	v_mov_b32_e32 v49, v0
	v_mov_b32_e32 v50, v0
	v_mov_b32_e32 v51, v0
	v_mov_b32_e32 v52, v0
	v_mov_b32_e32 v53, v0
	v_mov_b32_e32 v54, v0
	v_mov_b32_e32 v55, v0
	v_mov_b32_e32 v8, v0
	v_mov_b32_e32 v9, v0
	v_mov_b32_e32 v10, v0
	v_mov_b32_e32 v11, v0
	v_mov_b32_e32 v12, v0
	v_mov_b32_e32 v13, v0
	v_mov_b32_e32 v14, v0
	v_mov_b32_e32 v15, v0
	v_mov_b32_e32 v24, v0
	v_mov_b32_e32 v25, v0
	v_mov_b32_e32 v26, v0
	v_mov_b32_e32 v27, v0
	v_mov_b32_e32 v28, v0
	v_mov_b32_e32 v29, v0
	v_mov_b32_e32 v30, v0
	v_mov_b32_e32 v31, v0
	v_mov_b32_e32 v40, v0
	v_mov_b32_e32 v41, v0
	v_mov_b32_e32 v42, v0
	v_mov_b32_e32 v43, v0
	v_mov_b32_e32 v44, v0
	v_mov_b32_e32 v45, v0
	v_mov_b32_e32 v46, v0
	v_mov_b32_e32 v47, v0
	v_mov_b32_e32 v56, v0
	v_mov_b32_e32 v57, v0
	v_mov_b32_e32 v58, v0
	v_mov_b32_e32 v59, v0
	v_mov_b32_e32 v60, v0
	v_mov_b32_e32 v61, v0
	v_mov_b32_e32 v62, v0
	v_mov_b32_e32 v63, v0
	v_mov_b32_e32 v64, v0
	v_mov_b32_e32 v65, v0
	v_mov_b32_e32 v66, v0
	v_mov_b32_e32 v67, v0
	v_mov_b32_e32 v68, v0
	v_mov_b32_e32 v69, v0
	v_mov_b32_e32 v70, v0
	v_mov_b32_e32 v71, v0
	v_mov_b32_e32 v80, v0
	v_mov_b32_e32 v81, v0
	v_mov_b32_e32 v82, v0
	v_mov_b32_e32 v83, v0
	v_mov_b32_e32 v84, v0
	v_mov_b32_e32 v85, v0
	v_mov_b32_e32 v86, v0
	v_mov_b32_e32 v87, v0
	v_mov_b32_e32 v96, v0
	v_mov_b32_e32 v97, v0
	v_mov_b32_e32 v98, v0
	v_mov_b32_e32 v99, v0
	v_mov_b32_e32 v100, v0
	v_mov_b32_e32 v101, v0
	v_mov_b32_e32 v102, v0
	v_mov_b32_e32 v103, v0
	v_mov_b32_e32 v112, v0
	v_mov_b32_e32 v113, v0
	v_mov_b32_e32 v114, v0
	v_mov_b32_e32 v115, v0
	v_mov_b32_e32 v116, v0
	v_mov_b32_e32 v117, v0
	v_mov_b32_e32 v118, v0
	v_mov_b32_e32 v119, v0
	v_mov_b32_e32 v72, v0
	v_mov_b32_e32 v73, v0
	v_mov_b32_e32 v74, v0
	v_mov_b32_e32 v75, v0
	v_mov_b32_e32 v76, v0
	v_mov_b32_e32 v77, v0
	v_mov_b32_e32 v78, v0
	v_mov_b32_e32 v79, v0
	v_mov_b32_e32 v88, v0
	v_mov_b32_e32 v89, v0
	v_mov_b32_e32 v90, v0
	v_mov_b32_e32 v91, v0
	v_mov_b32_e32 v92, v0
	v_mov_b32_e32 v93, v0
	v_mov_b32_e32 v94, v0
	v_mov_b32_e32 v95, v0
	v_mov_b32_e32 v104, v0
	v_mov_b32_e32 v105, v0
	v_mov_b32_e32 v106, v0
	v_mov_b32_e32 v107, v0
	v_mov_b32_e32 v108, v0
	v_mov_b32_e32 v109, v0
	v_mov_b32_e32 v110, v0
	v_mov_b32_e32 v111, v0
	v_mov_b32_e32 v120, v0
	v_mov_b32_e32 v121, v0
	v_mov_b32_e32 v122, v0
	v_mov_b32_e32 v123, v0
	v_mov_b32_e32 v124, v0
	v_mov_b32_e32 v125, v0
	v_mov_b32_e32 v126, v0
	v_mov_b32_e32 v127, v0
	v_readfirstlane_b32 s4, v182
	s_nop 3
	s_cmp_lt_u32 s4, 256
	s_cbranch_scc1 .Lkprio_456
	s_setprio 1
.Lkprio_456:
.LBB0_456:
	s_add_u32 s60, s58, 0x100
	s_addc_u32 s61, s59, 0
	s_add_i32 s4, 0, 0x10000
	s_cmp_eq_u32 s51, 40
	s_cselect_b32 s63, s45, s61
	s_cselect_b32 s62, s44, s60
	s_cselect_b32 s35, s47, s29
	s_cselect_b32 s34, s46, s28
	s_add_i32 s5, 0, 0x14000
	v_add_u32_e32 v140, s4, v166
	v_add_u32_e32 v144, s5, v166
	ds_read_b128 v[128:131], v140
	ds_read_b128 v[132:135], v140 offset:1024
	ds_read_b128 v[136:139], v140 offset:2048
	ds_read_b128 v[140:143], v140 offset:3072
	ds_read_b128 v[178:181], v144
	ds_read_b128 v[204:207], v144 offset:1024
	ds_read_b128 v[208:211], v144 offset:2048
	ds_read_b128 v[212:215], v144 offset:3072
	v_lshl_add_u64 v[164:165], s[58:59], 0, v[160:161]
	s_add_i32 m0, s36, 0xc000
	ds_read_b128 v[216:219], v176
	ds_read_b128 v[220:223], v176 offset:1024
	ds_read_b128 v[224:227], v176 offset:2048
	ds_read_b128 v[228:231], v176 offset:3072
	ds_read_b128 v[232:235], v176 offset:4096
	ds_read_b128 v[236:239], v176 offset:5120
	ds_read_b128 v[240:243], v176 offset:6144
	ds_read_b128 v[244:247], v176 offset:7168
	global_load_lds_dwordx4 v[164:165], off
	v_lshl_add_u64 v[164:165], s[58:59], 0, v[162:163]
	s_add_i32 m0, s36, 0xe000
	s_nop 0
	global_load_lds_dwordx4 v[164:165], off
	s_waitcnt vmcnt(8)
	s_waitcnt lgkmcnt(0)
	s_barrier
	s_waitcnt lgkmcnt(0)
	v_mfma_f32_16x16x32_bf16 v[124:127], v[128:131], v[216:219], v[124:127]
	v_mfma_f32_16x16x32_bf16 v[120:123], v[136:139], v[216:219], v[120:123]
	v_mfma_f32_16x16x32_bf16 v[108:111], v[128:131], v[224:227], v[108:111]
	v_mfma_f32_16x16x32_bf16 v[104:107], v[136:139], v[224:227], v[104:107]
	v_mfma_f32_16x16x32_bf16 v[92:95], v[128:131], v[232:235], v[92:95]
	v_mfma_f32_16x16x32_bf16 v[88:91], v[136:139], v[232:235], v[88:91]
	v_mfma_f32_16x16x32_bf16 v[76:79], v[128:131], v[240:243], v[76:79]
	v_mfma_f32_16x16x32_bf16 v[72:75], v[136:139], v[240:243], v[72:75]
	v_mfma_f32_16x16x32_bf16 v[124:127], v[132:135], v[220:223], v[124:127]
	v_mfma_f32_16x16x32_bf16 v[120:123], v[140:143], v[220:223], v[120:123]
	v_mfma_f32_16x16x32_bf16 v[108:111], v[132:135], v[228:231], v[108:111]
	v_mfma_f32_16x16x32_bf16 v[104:107], v[140:143], v[228:231], v[104:107]
	v_mfma_f32_16x16x32_bf16 v[92:95], v[132:135], v[236:239], v[92:95]
	v_mfma_f32_16x16x32_bf16 v[88:91], v[140:143], v[236:239], v[88:91]
	v_mfma_f32_16x16x32_bf16 v[76:79], v[132:135], v[244:247], v[76:79]
	v_mfma_f32_16x16x32_bf16 v[72:75], v[140:143], v[244:247], v[72:75]
	v_mfma_f32_16x16x32_bf16 v[116:119], v[178:181], v[216:219], v[116:119]
	v_mfma_f32_16x16x32_bf16 v[112:115], v[208:211], v[216:219], v[112:115]
	v_mfma_f32_16x16x32_bf16 v[100:103], v[178:181], v[224:227], v[100:103]
	v_mfma_f32_16x16x32_bf16 v[96:99], v[208:211], v[224:227], v[96:99]
	v_mfma_f32_16x16x32_bf16 v[84:87], v[178:181], v[232:235], v[84:87]
	v_mfma_f32_16x16x32_bf16 v[80:83], v[208:211], v[232:235], v[80:83]
	v_mfma_f32_16x16x32_bf16 v[68:71], v[178:181], v[240:243], v[68:71]
	v_mfma_f32_16x16x32_bf16 v[64:67], v[208:211], v[240:243], v[64:67]
	v_mfma_f32_16x16x32_bf16 v[116:119], v[204:207], v[220:223], v[116:119]
	v_mfma_f32_16x16x32_bf16 v[112:115], v[212:215], v[220:223], v[112:115]
	v_mfma_f32_16x16x32_bf16 v[100:103], v[204:207], v[228:231], v[100:103]
	v_mfma_f32_16x16x32_bf16 v[96:99], v[212:215], v[228:231], v[96:99]
	v_mfma_f32_16x16x32_bf16 v[84:87], v[204:207], v[236:239], v[84:87]
	v_mfma_f32_16x16x32_bf16 v[80:83], v[212:215], v[236:239], v[80:83]
	v_mfma_f32_16x16x32_bf16 v[68:71], v[204:207], v[244:247], v[68:71]
	v_mfma_f32_16x16x32_bf16 v[64:67], v[212:215], v[244:247], v[64:67]
	s_barrier
	s_add_i32 s4, s4, s33
	v_lshl_add_u64 v[164:165], s[34:35], 0, v[154:155]
	s_mov_b32 m0, s4
	ds_read_b128 v[216:219], v176 offset:16384
	ds_read_b128 v[220:223], v176 offset:17408
	ds_read_b128 v[224:227], v176 offset:18432
	ds_read_b128 v[228:231], v176 offset:19456
	ds_read_b128 v[232:235], v176 offset:20480
	ds_read_b128 v[236:239], v176 offset:21504
	ds_read_b128 v[240:243], v176 offset:22528
	ds_read_b128 v[244:247], v176 offset:23552
	global_load_lds_dwordx4 v[164:165], off
	s_add_i32 m0, s4, 0x2000
	s_add_u32 s58, s34, 0xb0000
	v_lshl_add_u64 v[248:249], s[34:35], 0, v[156:157]
	s_addc_u32 s59, s35, 0
	s_add_i32 s4, s5, s33
	global_load_lds_dwordx4 v[248:249], off
	v_lshl_add_u64 v[250:251], s[58:59], 0, v[154:155]
	s_mov_b32 m0, s4
	v_lshl_add_u64 v[252:253], s[62:63], 0, v[156:157]
	global_load_lds_dwordx4 v[250:251], off
	v_lshl_add_u64 v[250:251], s[58:59], 0, v[156:157]
	s_add_i32 m0, s4, 0x2000
	s_nop 0
	global_load_lds_dwordx4 v[250:251], off
	v_lshl_add_u64 v[250:251], s[62:63], 0, v[154:155]
	s_mov_b32 m0, s36
	s_nop 0
	global_load_lds_dwordx4 v[250:251], off
	s_mov_b32 m0, s64
	s_nop 0
	global_load_lds_dwordx4 v[252:253], off
	s_waitcnt vmcnt(8)
	s_waitcnt lgkmcnt(0)
	s_barrier
	s_waitcnt lgkmcnt(0)
	v_mfma_f32_16x16x32_bf16 v[60:63], v[128:131], v[216:219], v[60:63]
	v_mfma_f32_16x16x32_bf16 v[56:59], v[136:139], v[216:219], v[56:59]
	v_mfma_f32_16x16x32_bf16 v[44:47], v[128:131], v[224:227], v[44:47]
	v_mfma_f32_16x16x32_bf16 v[40:43], v[136:139], v[224:227], v[40:43]
	v_mfma_f32_16x16x32_bf16 v[28:31], v[128:131], v[232:235], v[28:31]
	v_mfma_f32_16x16x32_bf16 v[24:27], v[136:139], v[232:235], v[24:27]
	v_mfma_f32_16x16x32_bf16 v[12:15], v[128:131], v[240:243], v[12:15]
	v_mfma_f32_16x16x32_bf16 v[8:11], v[136:139], v[240:243], v[8:11]
	v_mfma_f32_16x16x32_bf16 v[60:63], v[132:135], v[220:223], v[60:63]
	v_mfma_f32_16x16x32_bf16 v[56:59], v[140:143], v[220:223], v[56:59]
	v_mfma_f32_16x16x32_bf16 v[44:47], v[132:135], v[228:231], v[44:47]
	v_mfma_f32_16x16x32_bf16 v[40:43], v[140:143], v[228:231], v[40:43]
	v_mfma_f32_16x16x32_bf16 v[28:31], v[132:135], v[236:239], v[28:31]
	v_mfma_f32_16x16x32_bf16 v[24:27], v[140:143], v[236:239], v[24:27]
	v_mfma_f32_16x16x32_bf16 v[12:15], v[132:135], v[244:247], v[12:15]
	v_mfma_f32_16x16x32_bf16 v[8:11], v[140:143], v[244:247], v[8:11]
	v_mfma_f32_16x16x32_bf16 v[52:55], v[178:181], v[216:219], v[52:55]
	v_mfma_f32_16x16x32_bf16 v[48:51], v[208:211], v[216:219], v[48:51]
	v_mfma_f32_16x16x32_bf16 v[36:39], v[178:181], v[224:227], v[36:39]
	v_mfma_f32_16x16x32_bf16 v[32:35], v[208:211], v[224:227], v[32:35]
	v_mfma_f32_16x16x32_bf16 v[20:23], v[178:181], v[232:235], v[20:23]
	v_mfma_f32_16x16x32_bf16 v[16:19], v[208:211], v[232:235], v[16:19]
	v_mfma_f32_16x16x32_bf16 v[4:7], v[178:181], v[240:243], v[4:7]
	v_mfma_f32_16x16x32_bf16 v[0:3], v[208:211], v[240:243], v[0:3]
	v_mfma_f32_16x16x32_bf16 v[52:55], v[204:207], v[220:223], v[52:55]
	v_mfma_f32_16x16x32_bf16 v[48:51], v[212:215], v[220:223], v[48:51]
	v_mfma_f32_16x16x32_bf16 v[36:39], v[204:207], v[228:231], v[36:39]
	v_mfma_f32_16x16x32_bf16 v[32:35], v[212:215], v[228:231], v[32:35]
	v_mfma_f32_16x16x32_bf16 v[20:23], v[204:207], v[236:239], v[20:23]
	v_mfma_f32_16x16x32_bf16 v[16:19], v[212:215], v[236:239], v[16:19]
	v_mfma_f32_16x16x32_bf16 v[4:7], v[204:207], v[244:247], v[4:7]
	v_mfma_f32_16x16x32_bf16 v[0:3], v[212:215], v[244:247], v[0:3]
	s_barrier
	s_add_i32 s4, 0, 0x18000
	s_add_i32 s5, 0, 0x1c000
	v_add_u32_e32 v140, s4, v166
	v_add_u32_e32 v144, s5, v166
	ds_read_b128 v[128:131], v140
	ds_read_b128 v[132:135], v140 offset:1024
	ds_read_b128 v[136:139], v140 offset:2048
	ds_read_b128 v[140:143], v140 offset:3072
	ds_read_b128 v[178:181], v144
	ds_read_b128 v[204:207], v144 offset:1024
	ds_read_b128 v[208:211], v144 offset:2048
	ds_read_b128 v[212:215], v144 offset:3072
	s_add_u32 s58, s62, 0xb0000
	s_addc_u32 s59, s63, 0
	s_mov_b32 m0, s65
	v_lshl_add_u64 v[202:203], s[58:59], 0, v[154:155]
	ds_read_b128 v[216:219], v176 offset:32768
	ds_read_b128 v[220:223], v176 offset:33792
	ds_read_b128 v[224:227], v176 offset:34816
	ds_read_b128 v[228:231], v176 offset:35840
	ds_read_b128 v[232:235], v176 offset:36864
	ds_read_b128 v[236:239], v176 offset:37888
	ds_read_b128 v[240:243], v176 offset:38912
	ds_read_b128 v[244:247], v176 offset:39936
	global_load_lds_dwordx4 v[202:203], off
	v_lshl_add_u64 v[202:203], s[58:59], 0, v[156:157]
	s_mov_b32 m0, s70
	s_nop 0
	global_load_lds_dwordx4 v[202:203], off
	s_waitcnt vmcnt(8)
	s_waitcnt lgkmcnt(0)
	s_barrier
	s_waitcnt lgkmcnt(0)
	v_mfma_f32_16x16x32_bf16 v[124:127], v[128:131], v[216:219], v[124:127]
	v_mfma_f32_16x16x32_bf16 v[120:123], v[136:139], v[216:219], v[120:123]
	v_mfma_f32_16x16x32_bf16 v[108:111], v[128:131], v[224:227], v[108:111]
	v_mfma_f32_16x16x32_bf16 v[104:107], v[136:139], v[224:227], v[104:107]
	v_mfma_f32_16x16x32_bf16 v[92:95], v[128:131], v[232:235], v[92:95]
	v_mfma_f32_16x16x32_bf16 v[88:91], v[136:139], v[232:235], v[88:91]
	v_mfma_f32_16x16x32_bf16 v[76:79], v[128:131], v[240:243], v[76:79]
	v_mfma_f32_16x16x32_bf16 v[72:75], v[136:139], v[240:243], v[72:75]
	v_mfma_f32_16x16x32_bf16 v[124:127], v[132:135], v[220:223], v[124:127]
	v_mfma_f32_16x16x32_bf16 v[120:123], v[140:143], v[220:223], v[120:123]
	v_mfma_f32_16x16x32_bf16 v[108:111], v[132:135], v[228:231], v[108:111]
	v_mfma_f32_16x16x32_bf16 v[104:107], v[140:143], v[228:231], v[104:107]
	v_mfma_f32_16x16x32_bf16 v[92:95], v[132:135], v[236:239], v[92:95]
	v_mfma_f32_16x16x32_bf16 v[88:91], v[140:143], v[236:239], v[88:91]
	v_mfma_f32_16x16x32_bf16 v[76:79], v[132:135], v[244:247], v[76:79]
	v_mfma_f32_16x16x32_bf16 v[72:75], v[140:143], v[244:247], v[72:75]
	v_mfma_f32_16x16x32_bf16 v[116:119], v[178:181], v[216:219], v[116:119]
	v_mfma_f32_16x16x32_bf16 v[112:115], v[208:211], v[216:219], v[112:115]
	v_mfma_f32_16x16x32_bf16 v[100:103], v[178:181], v[224:227], v[100:103]
	v_mfma_f32_16x16x32_bf16 v[96:99], v[208:211], v[224:227], v[96:99]
	v_mfma_f32_16x16x32_bf16 v[84:87], v[178:181], v[232:235], v[84:87]
	v_mfma_f32_16x16x32_bf16 v[80:83], v[208:211], v[232:235], v[80:83]
	v_mfma_f32_16x16x32_bf16 v[68:71], v[178:181], v[240:243], v[68:71]
	v_mfma_f32_16x16x32_bf16 v[64:67], v[208:211], v[240:243], v[64:67]
	v_mfma_f32_16x16x32_bf16 v[116:119], v[204:207], v[220:223], v[116:119]
	v_mfma_f32_16x16x32_bf16 v[112:115], v[212:215], v[220:223], v[112:115]
	v_mfma_f32_16x16x32_bf16 v[100:103], v[204:207], v[228:231], v[100:103]
	v_mfma_f32_16x16x32_bf16 v[96:99], v[212:215], v[228:231], v[96:99]
	v_mfma_f32_16x16x32_bf16 v[84:87], v[204:207], v[236:239], v[84:87]
	v_mfma_f32_16x16x32_bf16 v[80:83], v[212:215], v[236:239], v[80:83]
	v_mfma_f32_16x16x32_bf16 v[68:71], v[204:207], v[244:247], v[68:71]
	v_mfma_f32_16x16x32_bf16 v[64:67], v[212:215], v[244:247], v[64:67]
	s_barrier
	s_add_i32 s4, s4, s33
	v_lshl_add_u64 v[164:165], v[164:165], 0, s[26:27]
	s_mov_b32 m0, s4
	ds_read_b128 v[216:219], v176 offset:49152
	ds_read_b128 v[220:223], v176 offset:50176
	ds_read_b128 v[224:227], v176 offset:51200
	ds_read_b128 v[228:231], v176 offset:52224
	ds_read_b128 v[232:235], v176 offset:53248
	ds_read_b128 v[236:239], v176 offset:54272
	ds_read_b128 v[240:243], v176 offset:55296
	ds_read_b128 v[244:247], v176 offset:56320
	global_load_lds_dwordx4 v[164:165], off
	s_add_i32 m0, s4, 0x2000
	s_add_u32 s34, s34, 0xb0080
	v_lshl_add_u64 v[164:165], v[248:249], 0, s[26:27]
	s_addc_u32 s35, s35, 0
	s_add_i32 s4, s5, s33
	global_load_lds_dwordx4 v[164:165], off
	v_lshl_add_u64 v[164:165], s[34:35], 0, v[154:155]
	s_mov_b32 m0, s4
	s_nop 0
	global_load_lds_dwordx4 v[164:165], off
	v_lshl_add_u64 v[164:165], s[34:35], 0, v[156:157]
	s_add_i32 m0, s4, 0x2000
	s_nop 0
	global_load_lds_dwordx4 v[164:165], off
	v_lshl_add_u64 v[164:165], v[250:251], 0, s[26:27]
	s_mov_b32 m0, s71
	s_nop 0
	global_load_lds_dwordx4 v[164:165], off
	v_lshl_add_u64 v[164:165], v[252:253], 0, s[26:27]
	s_mov_b32 m0, s72
	s_nop 0
	global_load_lds_dwordx4 v[164:165], off
	s_waitcnt vmcnt(8)
	s_waitcnt lgkmcnt(0)
	s_barrier
	s_waitcnt lgkmcnt(0)
	v_mfma_f32_16x16x32_bf16 v[60:63], v[128:131], v[216:219], v[60:63]
	v_mfma_f32_16x16x32_bf16 v[56:59], v[136:139], v[216:219], v[56:59]
	v_mfma_f32_16x16x32_bf16 v[44:47], v[128:131], v[224:227], v[44:47]
	v_mfma_f32_16x16x32_bf16 v[40:43], v[136:139], v[224:227], v[40:43]
	v_mfma_f32_16x16x32_bf16 v[28:31], v[128:131], v[232:235], v[28:31]
	v_mfma_f32_16x16x32_bf16 v[24:27], v[136:139], v[232:235], v[24:27]
	v_mfma_f32_16x16x32_bf16 v[12:15], v[128:131], v[240:243], v[12:15]
	v_mfma_f32_16x16x32_bf16 v[8:11], v[136:139], v[240:243], v[8:11]
	v_mfma_f32_16x16x32_bf16 v[60:63], v[132:135], v[220:223], v[60:63]
	v_mfma_f32_16x16x32_bf16 v[56:59], v[140:143], v[220:223], v[56:59]
	v_mfma_f32_16x16x32_bf16 v[44:47], v[132:135], v[228:231], v[44:47]
	v_mfma_f32_16x16x32_bf16 v[40:43], v[140:143], v[228:231], v[40:43]
	v_mfma_f32_16x16x32_bf16 v[28:31], v[132:135], v[236:239], v[28:31]
	v_mfma_f32_16x16x32_bf16 v[24:27], v[140:143], v[236:239], v[24:27]
	v_mfma_f32_16x16x32_bf16 v[12:15], v[132:135], v[244:247], v[12:15]
	v_mfma_f32_16x16x32_bf16 v[8:11], v[140:143], v[244:247], v[8:11]
	v_mfma_f32_16x16x32_bf16 v[52:55], v[178:181], v[216:219], v[52:55]
	v_mfma_f32_16x16x32_bf16 v[48:51], v[208:211], v[216:219], v[48:51]
	v_mfma_f32_16x16x32_bf16 v[36:39], v[178:181], v[224:227], v[36:39]
	v_mfma_f32_16x16x32_bf16 v[32:35], v[208:211], v[224:227], v[32:35]
	v_mfma_f32_16x16x32_bf16 v[20:23], v[178:181], v[232:235], v[20:23]
	v_mfma_f32_16x16x32_bf16 v[16:19], v[208:211], v[232:235], v[16:19]
	v_mfma_f32_16x16x32_bf16 v[4:7], v[178:181], v[240:243], v[4:7]
	v_mfma_f32_16x16x32_bf16 v[0:3], v[208:211], v[240:243], v[0:3]
	v_mfma_f32_16x16x32_bf16 v[52:55], v[204:207], v[220:223], v[52:55]
	v_mfma_f32_16x16x32_bf16 v[48:51], v[212:215], v[220:223], v[48:51]
	v_mfma_f32_16x16x32_bf16 v[36:39], v[204:207], v[228:231], v[36:39]
	v_mfma_f32_16x16x32_bf16 v[32:35], v[212:215], v[228:231], v[32:35]
	v_mfma_f32_16x16x32_bf16 v[20:23], v[204:207], v[236:239], v[20:23]
	v_mfma_f32_16x16x32_bf16 v[16:19], v[212:215], v[236:239], v[16:19]
	v_mfma_f32_16x16x32_bf16 v[4:7], v[204:207], v[244:247], v[4:7]
	v_mfma_f32_16x16x32_bf16 v[0:3], v[212:215], v[244:247], v[0:3]
	s_barrier
	s_add_i32 s51, s51, 2
	s_add_u32 s28, s28, 0x100
	s_addc_u32 s29, s29, 0
	s_cmp_gt_u32 s51, 41
	s_mov_b64 s[58:59], s[60:61]
	s_cbranch_scc0 .LBB0_456
	s_setprio 0
	s_and_b64 vcc, exec, s[54:55]
	s_cbranch_vccz .LBB0_459
	s_barrier

.LBB0_604:
	s_ashr_i32 s71, s70, 31
	s_lshl_b64 s[34:35], s[70:71], 19
	s_cmp_eq_u32 s30, 0
	s_cselect_b32 s4, s29, s55
	s_cselect_b32 s3, s47, s46
	s_cselect_b32 s5, s53, s29
	s_cselect_b32 s71, s54, s47
	s_add_u32 s72, s4, s34
	s_addc_u32 s73, s3, s35
	s_and_b64 s[34:35], s[40:41], exec
	s_cselect_b32 s3, s73, s1
	s_cselect_b32 s36, s72, s0
	s_ashr_i32 s39, s38, 31
	s_lshl_b64 s[34:35], s[38:39], 19
	s_add_u32 s74, s5, s34
	s_addc_u32 s75, s71, s35
	s_and_b64 s[34:35], s[40:41], exec
	s_cselect_b32 s39, s75, s43
	s_cselect_b32 s71, s74, s42
	s_add_u32 s0, s0, 0x40080
	s_addc_u32 s1, s1, 0
	s_add_u32 s79, s42, 0x100
	v_mov_b32_e32 v0, 0
	s_addc_u32 s84, s43, 0
	s_mov_b32 s88, -2
	v_mov_b32_e32 v1, v0
	v_mov_b32_e32 v2, v0
	v_mov_b32_e32 v3, v0
	v_mov_b32_e32 v4, v0
	v_mov_b32_e32 v5, v0
	v_mov_b32_e32 v6, v0
	v_mov_b32_e32 v7, v0
	v_mov_b32_e32 v8, v0
	v_mov_b32_e32 v9, v0
	v_mov_b32_e32 v10, v0
	v_mov_b32_e32 v11, v0
	v_mov_b32_e32 v16, v0
	v_mov_b32_e32 v17, v0
	v_mov_b32_e32 v18, v0
	v_mov_b32_e32 v19, v0
	v_mov_b32_e32 v24, v0
	v_mov_b32_e32 v25, v0
	v_mov_b32_e32 v26, v0
	v_mov_b32_e32 v27, v0
	v_mov_b32_e32 v32, v0
	v_mov_b32_e32 v33, v0
	v_mov_b32_e32 v34, v0
	v_mov_b32_e32 v35, v0
	v_mov_b32_e32 v40, v0
	v_mov_b32_e32 v41, v0
	v_mov_b32_e32 v42, v0
	v_mov_b32_e32 v43, v0
	v_mov_b32_e32 v48, v0
	v_mov_b32_e32 v49, v0
	v_mov_b32_e32 v50, v0
	v_mov_b32_e32 v51, v0
	v_mov_b32_e32 v12, v0
	v_mov_b32_e32 v13, v0
	v_mov_b32_e32 v14, v0
	v_mov_b32_e32 v15, v0
	v_mov_b32_e32 v20, v0
	v_mov_b32_e32 v21, v0
	v_mov_b32_e32 v22, v0
	v_mov_b32_e32 v23, v0
	v_mov_b32_e32 v28, v0
	v_mov_b32_e32 v29, v0
	v_mov_b32_e32 v30, v0
	v_mov_b32_e32 v31, v0
	v_mov_b32_e32 v36, v0
	v_mov_b32_e32 v37, v0
	v_mov_b32_e32 v38, v0
	v_mov_b32_e32 v39, v0
	v_mov_b32_e32 v44, v0
	v_mov_b32_e32 v45, v0
	v_mov_b32_e32 v46, v0
	v_mov_b32_e32 v47, v0
	v_mov_b32_e32 v52, v0
	v_mov_b32_e32 v53, v0
	v_mov_b32_e32 v54, v0
	v_mov_b32_e32 v55, v0
	v_mov_b32_e32 v56, v0
	v_mov_b32_e32 v57, v0
	v_mov_b32_e32 v58, v0
	v_mov_b32_e32 v59, v0
	v_mov_b32_e32 v60, v0
	v_mov_b32_e32 v61, v0
	v_mov_b32_e32 v62, v0
	v_mov_b32_e32 v63, v0
	v_mov_b32_e32 v64, v0
	v_mov_b32_e32 v65, v0
	v_mov_b32_e32 v66, v0
	v_mov_b32_e32 v67, v0
	v_mov_b32_e32 v68, v0
	v_mov_b32_e32 v69, v0
	v_mov_b32_e32 v70, v0
	v_mov_b32_e32 v71, v0
	v_mov_b32_e32 v72, v0
	v_mov_b32_e32 v73, v0
	v_mov_b32_e32 v74, v0
	v_mov_b32_e32 v75, v0
	v_mov_b32_e32 v80, v0
	v_mov_b32_e32 v81, v0
	v_mov_b32_e32 v82, v0
	v_mov_b32_e32 v83, v0
	v_mov_b32_e32 v88, v0
	v_mov_b32_e32 v89, v0
	v_mov_b32_e32 v90, v0
	v_mov_b32_e32 v91, v0
	v_mov_b32_e32 v96, v0
	v_mov_b32_e32 v97, v0
	v_mov_b32_e32 v98, v0
	v_mov_b32_e32 v99, v0
	v_mov_b32_e32 v104, v0
	v_mov_b32_e32 v105, v0
	v_mov_b32_e32 v106, v0
	v_mov_b32_e32 v107, v0
	v_mov_b32_e32 v116, v0
	v_mov_b32_e32 v117, v0
	v_mov_b32_e32 v118, v0
	v_mov_b32_e32 v119, v0
	v_mov_b32_e32 v76, v0
	v_mov_b32_e32 v77, v0
	v_mov_b32_e32 v78, v0
	v_mov_b32_e32 v79, v0
	v_mov_b32_e32 v84, v0
	v_mov_b32_e32 v85, v0
	v_mov_b32_e32 v86, v0
	v_mov_b32_e32 v87, v0
	v_mov_b32_e32 v92, v0
	v_mov_b32_e32 v93, v0
	v_mov_b32_e32 v94, v0
	v_mov_b32_e32 v95, v0
	v_mov_b32_e32 v100, v0
	v_mov_b32_e32 v101, v0
	v_mov_b32_e32 v102, v0
	v_mov_b32_e32 v103, v0
	v_mov_b32_e32 v108, v0
	v_mov_b32_e32 v109, v0
	v_mov_b32_e32 v110, v0
	v_mov_b32_e32 v111, v0
	v_mov_b32_e32 v112, v0
	v_mov_b32_e32 v113, v0
	v_mov_b32_e32 v114, v0
	v_mov_b32_e32 v115, v0
	v_mov_b32_e32 v120, v0
	v_mov_b32_e32 v121, v0
	v_mov_b32_e32 v122, v0
	v_mov_b32_e32 v123, v0
	v_mov_b32_e32 v124, v0
	v_mov_b32_e32 v125, v0
	v_mov_b32_e32 v126, v0
	v_mov_b32_e32 v127, v0
	v_readfirstlane_b32 s4, v182
	s_nop 3
	s_cmp_lt_u32 s4, 256
	s_cbranch_scc1 .Lkprio_605
	s_setprio 1
.Lkprio_605:
.LBB0_605:
	s_add_u32 s4, s0, 0xfffc0080
	s_addc_u32 s5, s1, -1
	s_add_i32 s89, 0, 0x10000
	s_cmp_eq_u32 s88, 12
	s_cselect_b32 s43, s3, s5
	s_cselect_b32 s42, s36, s4
	s_cselect_b32 s35, s39, s84
	s_cselect_b32 s34, s71, s79
	s_add_i32 s4, 0, 0x14000
	v_add_u32_e32 v140, s89, v203
	v_add_u32_e32 v144, s4, v203
	ds_read_b128 v[128:131], v140
	ds_read_b128 v[132:135], v140 offset:1024
	ds_read_b128 v[136:139], v140 offset:2048
	ds_read_b128 v[140:143], v140 offset:3072
	ds_read_b128 v[168:171], v144
	ds_read_b128 v[172:175], v144 offset:1024
	ds_read_b128 v[176:179], v144 offset:2048
	ds_read_b128 v[206:209], v144 offset:3072
	v_lshl_add_u64 v[180:181], s[0:1], 0, v[164:165]
	s_add_i32 m0, s69, 0xc000
	ds_read_b128 v[210:213], v205
	ds_read_b128 v[214:217], v205 offset:1024
	ds_read_b128 v[218:221], v205 offset:2048
	ds_read_b128 v[222:225], v205 offset:3072
	ds_read_b128 v[226:229], v205 offset:4096
	ds_read_b128 v[230:233], v205 offset:5120
	ds_read_b128 v[234:237], v205 offset:6144
	ds_read_b128 v[238:241], v205 offset:7168
	global_load_lds_dwordx4 v[180:181], off
	v_lshl_add_u64 v[180:181], s[0:1], 0, v[166:167]
	s_add_i32 m0, s69, 0xe000
	s_nop 0
	global_load_lds_dwordx4 v[180:181], off
	s_waitcnt vmcnt(8)
	s_waitcnt lgkmcnt(0)
	s_barrier
	s_waitcnt lgkmcnt(0)
	v_mfma_f32_16x16x32_bf16 v[124:127], v[128:131], v[210:213], v[124:127]
	v_mfma_f32_16x16x32_bf16 v[120:123], v[136:139], v[210:213], v[120:123]
	v_mfma_f32_16x16x32_bf16 v[112:115], v[128:131], v[218:221], v[112:115]
	v_mfma_f32_16x16x32_bf16 v[108:111], v[136:139], v[218:221], v[108:111]
	v_mfma_f32_16x16x32_bf16 v[100:103], v[128:131], v[226:229], v[100:103]
	v_mfma_f32_16x16x32_bf16 v[92:95], v[136:139], v[226:229], v[92:95]
	v_mfma_f32_16x16x32_bf16 v[84:87], v[128:131], v[234:237], v[84:87]
	v_mfma_f32_16x16x32_bf16 v[76:79], v[136:139], v[234:237], v[76:79]
	v_mfma_f32_16x16x32_bf16 v[124:127], v[132:135], v[214:217], v[124:127]
	v_mfma_f32_16x16x32_bf16 v[120:123], v[140:143], v[214:217], v[120:123]
	v_mfma_f32_16x16x32_bf16 v[112:115], v[132:135], v[222:225], v[112:115]
	v_mfma_f32_16x16x32_bf16 v[108:111], v[140:143], v[222:225], v[108:111]
	v_mfma_f32_16x16x32_bf16 v[100:103], v[132:135], v[230:233], v[100:103]
	v_mfma_f32_16x16x32_bf16 v[92:95], v[140:143], v[230:233], v[92:95]
	v_mfma_f32_16x16x32_bf16 v[84:87], v[132:135], v[238:241], v[84:87]
	v_mfma_f32_16x16x32_bf16 v[76:79], v[140:143], v[238:241], v[76:79]
	v_mfma_f32_16x16x32_bf16 v[116:119], v[168:171], v[210:213], v[116:119]
	v_mfma_f32_16x16x32_bf16 v[104:107], v[176:179], v[210:213], v[104:107]
	v_mfma_f32_16x16x32_bf16 v[96:99], v[168:171], v[218:221], v[96:99]
	v_mfma_f32_16x16x32_bf16 v[88:91], v[176:179], v[218:221], v[88:91]
	v_mfma_f32_16x16x32_bf16 v[80:83], v[168:171], v[226:229], v[80:83]
	v_mfma_f32_16x16x32_bf16 v[72:75], v[176:179], v[226:229], v[72:75]
	v_mfma_f32_16x16x32_bf16 v[68:71], v[168:171], v[234:237], v[68:71]
	v_mfma_f32_16x16x32_bf16 v[64:67], v[176:179], v[234:237], v[64:67]
	v_mfma_f32_16x16x32_bf16 v[116:119], v[172:175], v[214:217], v[116:119]
	v_mfma_f32_16x16x32_bf16 v[104:107], v[206:209], v[214:217], v[104:107]
	v_mfma_f32_16x16x32_bf16 v[96:99], v[172:175], v[222:225], v[96:99]
	v_mfma_f32_16x16x32_bf16 v[88:91], v[206:209], v[222:225], v[88:91]
	v_mfma_f32_16x16x32_bf16 v[80:83], v[172:175], v[230:233], v[80:83]
	v_mfma_f32_16x16x32_bf16 v[72:75], v[206:209], v[230:233], v[72:75]
	v_mfma_f32_16x16x32_bf16 v[68:71], v[172:175], v[238:241], v[68:71]
	v_mfma_f32_16x16x32_bf16 v[64:67], v[206:209], v[238:241], v[64:67]
	s_barrier
	s_add_i32 s5, s89, s28
	v_lshl_add_u64 v[180:181], s[34:35], 0, v[156:157]
	s_mov_b32 m0, s5
	ds_read_b128 v[210:213], v205 offset:16384
	ds_read_b128 v[214:217], v205 offset:17408
	ds_read_b128 v[218:221], v205 offset:18432
	ds_read_b128 v[222:225], v205 offset:19456
	ds_read_b128 v[226:229], v205 offset:20480
	ds_read_b128 v[230:233], v205 offset:21504
	ds_read_b128 v[234:237], v205 offset:22528
	ds_read_b128 v[238:241], v205 offset:23552
	global_load_lds_dwordx4 v[180:181], off
	s_add_i32 m0, s5, 0x2000
	s_add_u32 s90, s34, 0x40000
	v_lshl_add_u64 v[242:243], s[34:35], 0, v[160:161]
	s_addc_u32 s91, s35, 0
	s_add_i32 s4, s4, s28
	global_load_lds_dwordx4 v[242:243], off
	v_lshl_add_u64 v[244:245], s[90:91], 0, v[156:157]
	s_mov_b32 m0, s4
	v_lshl_add_u64 v[246:247], s[42:43], 0, v[158:159]
	global_load_lds_dwordx4 v[244:245], off
	v_lshl_add_u64 v[244:245], s[90:91], 0, v[160:161]
	s_add_i32 m0, s4, 0x2000
	s_nop 0
	global_load_lds_dwordx4 v[244:245], off
	v_lshl_add_u64 v[244:245], s[42:43], 0, v[154:155]
	s_mov_b32 m0, s69
	s_nop 0
	global_load_lds_dwordx4 v[244:245], off
	s_mov_b32 m0, s62
	s_nop 0
	global_load_lds_dwordx4 v[246:247], off
	s_waitcnt vmcnt(8)
	s_waitcnt lgkmcnt(0)
	s_barrier
	s_waitcnt lgkmcnt(0)
	v_mfma_f32_16x16x32_bf16 v[60:63], v[128:131], v[210:213], v[60:63]
	v_mfma_f32_16x16x32_bf16 v[56:59], v[136:139], v[210:213], v[56:59]
	v_mfma_f32_16x16x32_bf16 v[52:55], v[128:131], v[218:221], v[52:55]
	v_mfma_f32_16x16x32_bf16 v[44:47], v[136:139], v[218:221], v[44:47]
	v_mfma_f32_16x16x32_bf16 v[36:39], v[128:131], v[226:229], v[36:39]
	v_mfma_f32_16x16x32_bf16 v[28:31], v[136:139], v[226:229], v[28:31]
	v_mfma_f32_16x16x32_bf16 v[20:23], v[128:131], v[234:237], v[20:23]
	v_mfma_f32_16x16x32_bf16 v[12:15], v[136:139], v[234:237], v[12:15]
	v_mfma_f32_16x16x32_bf16 v[60:63], v[132:135], v[214:217], v[60:63]
	v_mfma_f32_16x16x32_bf16 v[56:59], v[140:143], v[214:217], v[56:59]
	v_mfma_f32_16x16x32_bf16 v[52:55], v[132:135], v[222:225], v[52:55]
	v_mfma_f32_16x16x32_bf16 v[44:47], v[140:143], v[222:225], v[44:47]
	v_mfma_f32_16x16x32_bf16 v[36:39], v[132:135], v[230:233], v[36:39]
	v_mfma_f32_16x16x32_bf16 v[28:31], v[140:143], v[230:233], v[28:31]
	v_mfma_f32_16x16x32_bf16 v[20:23], v[132:135], v[238:241], v[20:23]
	v_mfma_f32_16x16x32_bf16 v[12:15], v[140:143], v[238:241], v[12:15]
	v_mfma_f32_16x16x32_bf16 v[48:51], v[168:171], v[210:213], v[48:51]
	v_mfma_f32_16x16x32_bf16 v[40:43], v[176:179], v[210:213], v[40:43]
	v_mfma_f32_16x16x32_bf16 v[32:35], v[168:171], v[218:221], v[32:35]
	v_mfma_f32_16x16x32_bf16 v[24:27], v[176:179], v[218:221], v[24:27]
	v_mfma_f32_16x16x32_bf16 v[16:19], v[168:171], v[226:229], v[16:19]
	v_mfma_f32_16x16x32_bf16 v[8:11], v[176:179], v[226:229], v[8:11]
	v_mfma_f32_16x16x32_bf16 v[4:7], v[168:171], v[234:237], v[4:7]
	v_mfma_f32_16x16x32_bf16 v[0:3], v[176:179], v[234:237], v[0:3]
	v_mfma_f32_16x16x32_bf16 v[48:51], v[172:175], v[214:217], v[48:51]
	v_mfma_f32_16x16x32_bf16 v[40:43], v[206:209], v[214:217], v[40:43]
	v_mfma_f32_16x16x32_bf16 v[32:35], v[172:175], v[222:225], v[32:35]
	v_mfma_f32_16x16x32_bf16 v[24:27], v[206:209], v[222:225], v[24:27]
	v_mfma_f32_16x16x32_bf16 v[16:19], v[172:175], v[230:233], v[16:19]
	v_mfma_f32_16x16x32_bf16 v[8:11], v[206:209], v[230:233], v[8:11]
	v_mfma_f32_16x16x32_bf16 v[4:7], v[172:175], v[238:241], v[4:7]
	v_mfma_f32_16x16x32_bf16 v[0:3], v[206:209], v[238:241], v[0:3]
	s_barrier
	s_add_i32 s4, 0, 0x18000
	s_add_i32 s5, 0, 0x1c000
	v_add_u32_e32 v140, s4, v203
	v_add_u32_e32 v144, s5, v203
	ds_read_b128 v[128:131], v140
	ds_read_b128 v[132:135], v140 offset:1024
	ds_read_b128 v[136:139], v140 offset:2048
	ds_read_b128 v[140:143], v140 offset:3072
	ds_read_b128 v[168:171], v144
	ds_read_b128 v[172:175], v144 offset:1024
	ds_read_b128 v[176:179], v144 offset:2048
	ds_read_b128 v[206:209], v144 offset:3072
	s_add_u32 s42, s42, 0x40000
	s_addc_u32 s43, s43, 0
	s_mov_b32 m0, s63
	v_lshl_add_u64 v[248:249], s[42:43], 0, v[154:155]
	ds_read_b128 v[210:213], v205 offset:32768
	ds_read_b128 v[214:217], v205 offset:33792
	ds_read_b128 v[218:221], v205 offset:34816
	ds_read_b128 v[222:225], v205 offset:35840
	ds_read_b128 v[226:229], v205 offset:36864
	ds_read_b128 v[230:233], v205 offset:37888
	ds_read_b128 v[234:237], v205 offset:38912
	ds_read_b128 v[238:241], v205 offset:39936
	global_load_lds_dwordx4 v[248:249], off
	v_lshl_add_u64 v[248:249], s[42:43], 0, v[158:159]
	s_mov_b32 m0, s50
	s_nop 0
	global_load_lds_dwordx4 v[248:249], off
	s_waitcnt vmcnt(8)
	s_waitcnt lgkmcnt(0)
	s_barrier
	s_waitcnt lgkmcnt(0)
	v_mfma_f32_16x16x32_bf16 v[124:127], v[128:131], v[210:213], v[124:127]
	v_mfma_f32_16x16x32_bf16 v[120:123], v[136:139], v[210:213], v[120:123]
	v_mfma_f32_16x16x32_bf16 v[112:115], v[128:131], v[218:221], v[112:115]
	v_mfma_f32_16x16x32_bf16 v[108:111], v[136:139], v[218:221], v[108:111]
	v_mfma_f32_16x16x32_bf16 v[100:103], v[128:131], v[226:229], v[100:103]
	v_mfma_f32_16x16x32_bf16 v[92:95], v[136:139], v[226:229], v[92:95]
	v_mfma_f32_16x16x32_bf16 v[84:87], v[128:131], v[234:237], v[84:87]
	v_mfma_f32_16x16x32_bf16 v[76:79], v[136:139], v[234:237], v[76:79]
	v_mfma_f32_16x16x32_bf16 v[124:127], v[132:135], v[214:217], v[124:127]
	v_mfma_f32_16x16x32_bf16 v[120:123], v[140:143], v[214:217], v[120:123]
	v_mfma_f32_16x16x32_bf16 v[112:115], v[132:135], v[222:225], v[112:115]
	v_mfma_f32_16x16x32_bf16 v[108:111], v[140:143], v[222:225], v[108:111]
	v_mfma_f32_16x16x32_bf16 v[100:103], v[132:135], v[230:233], v[100:103]
	v_mfma_f32_16x16x32_bf16 v[92:95], v[140:143], v[230:233], v[92:95]
	v_mfma_f32_16x16x32_bf16 v[84:87], v[132:135], v[238:241], v[84:87]
	v_mfma_f32_16x16x32_bf16 v[76:79], v[140:143], v[238:241], v[76:79]
	v_mfma_f32_16x16x32_bf16 v[116:119], v[168:171], v[210:213], v[116:119]
	v_mfma_f32_16x16x32_bf16 v[104:107], v[176:179], v[210:213], v[104:107]
	v_mfma_f32_16x16x32_bf16 v[96:99], v[168:171], v[218:221], v[96:99]
	v_mfma_f32_16x16x32_bf16 v[88:91], v[176:179], v[218:221], v[88:91]
	v_mfma_f32_16x16x32_bf16 v[80:83], v[168:171], v[226:229], v[80:83]
	v_mfma_f32_16x16x32_bf16 v[72:75], v[176:179], v[226:229], v[72:75]
	v_mfma_f32_16x16x32_bf16 v[68:71], v[168:171], v[234:237], v[68:71]
	v_mfma_f32_16x16x32_bf16 v[64:67], v[176:179], v[234:237], v[64:67]
	v_mfma_f32_16x16x32_bf16 v[116:119], v[172:175], v[214:217], v[116:119]
	v_mfma_f32_16x16x32_bf16 v[104:107], v[206:209], v[214:217], v[104:107]
	v_mfma_f32_16x16x32_bf16 v[96:99], v[172:175], v[222:225], v[96:99]
	v_mfma_f32_16x16x32_bf16 v[88:91], v[206:209], v[222:225], v[88:91]
	v_mfma_f32_16x16x32_bf16 v[80:83], v[172:175], v[230:233], v[80:83]
	v_mfma_f32_16x16x32_bf16 v[72:75], v[206:209], v[230:233], v[72:75]
	v_mfma_f32_16x16x32_bf16 v[68:71], v[172:175], v[238:241], v[68:71]
	v_mfma_f32_16x16x32_bf16 v[64:67], v[206:209], v[238:241], v[64:67]
	s_barrier
	s_add_i32 s4, s4, s28
	v_lshl_add_u64 v[180:181], v[180:181], 0, s[26:27]
	s_mov_b32 m0, s4
	ds_read_b128 v[210:213], v205 offset:49152
	ds_read_b128 v[214:217], v205 offset:50176
	ds_read_b128 v[218:221], v205 offset:51200
	ds_read_b128 v[222:225], v205 offset:52224
	ds_read_b128 v[226:229], v205 offset:53248
	ds_read_b128 v[230:233], v205 offset:54272
	ds_read_b128 v[234:237], v205 offset:55296
	ds_read_b128 v[238:241], v205 offset:56320
	global_load_lds_dwordx4 v[180:181], off
	s_add_i32 m0, s4, 0x2000
	s_add_u32 s34, s34, 0x40080
	v_lshl_add_u64 v[180:181], v[242:243], 0, s[26:27]
	s_addc_u32 s35, s35, 0
	s_add_i32 s4, s5, s28
	global_load_lds_dwordx4 v[180:181], off
	v_lshl_add_u64 v[180:181], s[34:35], 0, v[156:157]
	s_mov_b32 m0, s4
	s_nop 0
	global_load_lds_dwordx4 v[180:181], off
	v_lshl_add_u64 v[180:181], s[34:35], 0, v[160:161]
	s_add_i32 m0, s4, 0x2000
	s_nop 0
	global_load_lds_dwordx4 v[180:181], off
	v_lshl_add_u64 v[180:181], v[244:245], 0, s[26:27]
	s_mov_b32 m0, s51
	s_nop 0
	global_load_lds_dwordx4 v[180:181], off
	v_lshl_add_u64 v[180:181], v[246:247], 0, s[26:27]
	s_mov_b32 m0, s64
	s_nop 0
	global_load_lds_dwordx4 v[180:181], off
	s_waitcnt vmcnt(8)
	s_waitcnt lgkmcnt(0)
	s_barrier
	s_waitcnt lgkmcnt(0)
	v_mfma_f32_16x16x32_bf16 v[60:63], v[128:131], v[210:213], v[60:63]
	v_mfma_f32_16x16x32_bf16 v[56:59], v[136:139], v[210:213], v[56:59]
	v_mfma_f32_16x16x32_bf16 v[52:55], v[128:131], v[218:221], v[52:55]
	v_mfma_f32_16x16x32_bf16 v[44:47], v[136:139], v[218:221], v[44:47]
	v_mfma_f32_16x16x32_bf16 v[36:39], v[128:131], v[226:229], v[36:39]
	v_mfma_f32_16x16x32_bf16 v[28:31], v[136:139], v[226:229], v[28:31]
	v_mfma_f32_16x16x32_bf16 v[20:23], v[128:131], v[234:237], v[20:23]
	v_mfma_f32_16x16x32_bf16 v[12:15], v[136:139], v[234:237], v[12:15]
	v_mfma_f32_16x16x32_bf16 v[60:63], v[132:135], v[214:217], v[60:63]
	v_mfma_f32_16x16x32_bf16 v[56:59], v[140:143], v[214:217], v[56:59]
	v_mfma_f32_16x16x32_bf16 v[52:55], v[132:135], v[222:225], v[52:55]
	v_mfma_f32_16x16x32_bf16 v[44:47], v[140:143], v[222:225], v[44:47]
	v_mfma_f32_16x16x32_bf16 v[36:39], v[132:135], v[230:233], v[36:39]
	v_mfma_f32_16x16x32_bf16 v[28:31], v[140:143], v[230:233], v[28:31]
	v_mfma_f32_16x16x32_bf16 v[20:23], v[132:135], v[238:241], v[20:23]
	v_mfma_f32_16x16x32_bf16 v[12:15], v[140:143], v[238:241], v[12:15]
	v_mfma_f32_16x16x32_bf16 v[48:51], v[168:171], v[210:213], v[48:51]
	v_mfma_f32_16x16x32_bf16 v[40:43], v[176:179], v[210:213], v[40:43]
	v_mfma_f32_16x16x32_bf16 v[32:35], v[168:171], v[218:221], v[32:35]
	v_mfma_f32_16x16x32_bf16 v[24:27], v[176:179], v[218:221], v[24:27]
	v_mfma_f32_16x16x32_bf16 v[16:19], v[168:171], v[226:229], v[16:19]
	v_mfma_f32_16x16x32_bf16 v[8:11], v[176:179], v[226:229], v[8:11]
	v_mfma_f32_16x16x32_bf16 v[4:7], v[168:171], v[234:237], v[4:7]
	v_mfma_f32_16x16x32_bf16 v[0:3], v[176:179], v[234:237], v[0:3]
	v_mfma_f32_16x16x32_bf16 v[48:51], v[172:175], v[214:217], v[48:51]
	v_mfma_f32_16x16x32_bf16 v[40:43], v[206:209], v[214:217], v[40:43]
	v_mfma_f32_16x16x32_bf16 v[32:35], v[172:175], v[222:225], v[32:35]
	v_mfma_f32_16x16x32_bf16 v[24:27], v[206:209], v[222:225], v[24:27]
	v_mfma_f32_16x16x32_bf16 v[16:19], v[172:175], v[230:233], v[16:19]
	v_mfma_f32_16x16x32_bf16 v[8:11], v[206:209], v[230:233], v[8:11]
	v_mfma_f32_16x16x32_bf16 v[4:7], v[172:175], v[238:241], v[4:7]
	v_mfma_f32_16x16x32_bf16 v[0:3], v[206:209], v[238:241], v[0:3]
	s_barrier
	s_add_i32 s88, s88, 2
	s_add_u32 s0, s0, 0x100
	s_addc_u32 s1, s1, 0
	s_add_u32 s79, s79, 0x100
	s_addc_u32 s84, s84, 0
	s_cmp_gt_u32 s88, 13
	s_cbranch_scc0 .LBB0_605
	s_setprio 0
	s_and_b64 vcc, exec, s[66:67]
	s_cbranch_vccz .LBB0_608
	s_barrier

.LBB0_1004:
	s_ashr_i32 s47, s46, 31
	s_lshl_b64 s[4:5], s[46:47], 18
	s_add_u32 s48, s33, s4
	s_addc_u32 s49, s36, s5
	s_and_b64 s[4:5], s[38:39], exec
	s_cselect_b32 s29, s49, s55
	s_cselect_b32 s47, s48, s54
	s_ashr_i32 s45, s44, 31
	s_lshl_b64 s[4:5], s[44:45], 18
	s_add_u32 s50, s60, s4
	s_addc_u32 s51, s61, s5
	s_and_b64 s[4:5], s[38:39], exec
	s_cselect_b32 s45, s51, s59
	s_cselect_b32 s68, s50, s58
	s_add_u32 s54, s54, 0x20080
	s_addc_u32 s55, s55, 0
	s_add_u32 s69, s58, 0x100
	v_mov_b32_e32 v4, 0
	s_addc_u32 s70, s59, 0
	s_mov_b32 s71, -2
	v_mov_b32_e32 v5, v4
	v_mov_b32_e32 v6, v4
	v_mov_b32_e32 v7, v4
	v_mov_b32_e32 v0, v4
	v_mov_b32_e32 v1, v4
	v_mov_b32_e32 v2, v4
	v_mov_b32_e32 v3, v4
	v_mov_b32_e32 v20, v4
	v_mov_b32_e32 v21, v4
	v_mov_b32_e32 v22, v4
	v_mov_b32_e32 v23, v4
	v_mov_b32_e32 v16, v4
	v_mov_b32_e32 v17, v4
	v_mov_b32_e32 v18, v4
	v_mov_b32_e32 v19, v4
	v_mov_b32_e32 v36, v4
	v_mov_b32_e32 v37, v4
	v_mov_b32_e32 v38, v4
	v_mov_b32_e32 v39, v4
	v_mov_b32_e32 v32, v4
	v_mov_b32_e32 v33, v4
	v_mov_b32_e32 v34, v4
	v_mov_b32_e32 v35, v4
	v_mov_b32_e32 v52, v4
	v_mov_b32_e32 v53, v4
	v_mov_b32_e32 v54, v4
	v_mov_b32_e32 v55, v4
	v_mov_b32_e32 v48, v4
	v_mov_b32_e32 v49, v4
	v_mov_b32_e32 v50, v4
	v_mov_b32_e32 v51, v4
	v_mov_b32_e32 v12, v4
	v_mov_b32_e32 v13, v4
	v_mov_b32_e32 v14, v4
	v_mov_b32_e32 v15, v4
	v_mov_b32_e32 v8, v4
	v_mov_b32_e32 v9, v4
	v_mov_b32_e32 v10, v4
	v_mov_b32_e32 v11, v4
	v_mov_b32_e32 v28, v4
	v_mov_b32_e32 v29, v4
	v_mov_b32_e32 v30, v4
	v_mov_b32_e32 v31, v4
	v_mov_b32_e32 v24, v4
	v_mov_b32_e32 v25, v4
	v_mov_b32_e32 v26, v4
	v_mov_b32_e32 v27, v4
	v_mov_b32_e32 v44, v4
	v_mov_b32_e32 v45, v4
	v_mov_b32_e32 v46, v4
	v_mov_b32_e32 v47, v4
	v_mov_b32_e32 v40, v4
	v_mov_b32_e32 v41, v4
	v_mov_b32_e32 v42, v4
	v_mov_b32_e32 v43, v4
	v_mov_b32_e32 v60, v4
	v_mov_b32_e32 v61, v4
	v_mov_b32_e32 v62, v4
	v_mov_b32_e32 v63, v4
	v_mov_b32_e32 v56, v4
	v_mov_b32_e32 v57, v4
	v_mov_b32_e32 v58, v4
	v_mov_b32_e32 v59, v4
	v_mov_b32_e32 v68, v4
	v_mov_b32_e32 v69, v4
	v_mov_b32_e32 v70, v4
	v_mov_b32_e32 v71, v4
	v_mov_b32_e32 v64, v4
	v_mov_b32_e32 v65, v4
	v_mov_b32_e32 v66, v4
	v_mov_b32_e32 v67, v4
	v_mov_b32_e32 v84, v4
	v_mov_b32_e32 v85, v4
	v_mov_b32_e32 v86, v4
	v_mov_b32_e32 v87, v4
	v_mov_b32_e32 v80, v4
	v_mov_b32_e32 v81, v4
	v_mov_b32_e32 v82, v4
	v_mov_b32_e32 v83, v4
	v_mov_b32_e32 v100, v4
	v_mov_b32_e32 v101, v4
	v_mov_b32_e32 v102, v4
	v_mov_b32_e32 v103, v4
	v_mov_b32_e32 v96, v4
	v_mov_b32_e32 v97, v4
	v_mov_b32_e32 v98, v4
	v_mov_b32_e32 v99, v4
	v_mov_b32_e32 v116, v4
	v_mov_b32_e32 v117, v4
	v_mov_b32_e32 v118, v4
	v_mov_b32_e32 v119, v4
	v_mov_b32_e32 v112, v4
	v_mov_b32_e32 v113, v4
	v_mov_b32_e32 v114, v4
	v_mov_b32_e32 v115, v4
	v_mov_b32_e32 v76, v4
	v_mov_b32_e32 v77, v4
	v_mov_b32_e32 v78, v4
	v_mov_b32_e32 v79, v4
	v_mov_b32_e32 v72, v4
	v_mov_b32_e32 v73, v4
	v_mov_b32_e32 v74, v4
	v_mov_b32_e32 v75, v4
	v_mov_b32_e32 v92, v4
	v_mov_b32_e32 v93, v4
	v_mov_b32_e32 v94, v4
	v_mov_b32_e32 v95, v4
	v_mov_b32_e32 v88, v4
	v_mov_b32_e32 v89, v4
	v_mov_b32_e32 v90, v4
	v_mov_b32_e32 v91, v4
	v_mov_b32_e32 v108, v4
	v_mov_b32_e32 v109, v4
	v_mov_b32_e32 v110, v4
	v_mov_b32_e32 v111, v4
	v_mov_b32_e32 v104, v4
	v_mov_b32_e32 v105, v4
	v_mov_b32_e32 v106, v4
	v_mov_b32_e32 v107, v4
	v_mov_b32_e32 v124, v4
	v_mov_b32_e32 v125, v4
	v_mov_b32_e32 v126, v4
	v_mov_b32_e32 v127, v4
	v_mov_b32_e32 v120, v4
	v_mov_b32_e32 v121, v4
	v_mov_b32_e32 v122, v4
	v_mov_b32_e32 v123, v4
	v_readfirstlane_b32 s4, v182
	s_nop 3
	s_cmp_lt_u32 s4, 256
	s_cbranch_scc1 .Lkprio_1005
	s_setprio 1
.Lkprio_1005:
.LBB0_1005:
	s_add_u32 s4, s54, 0xfffe0080
	s_addc_u32 s5, s55, -1
	s_add_i32 s72, 0, 0x10000
	s_cmp_eq_u32 s71, 4
	s_cselect_b32 s59, s29, s5
	s_cselect_b32 s58, s47, s4
	v_add_u32_e32 v138, s72, v141
	s_cselect_b32 s35, s45, s70
	s_cselect_b32 s34, s68, s69
	s_add_i32 s73, 0, 0x14000
	ds_read_b128 v[154:157], v138
	ds_read_b128 v[158:161], v138 offset:1024
	ds_read_b128 v[162:165], v138 offset:2048
	ds_read_b128 v[166:169], v138 offset:3072
	v_add_u32_e32 v138, s73, v141
	ds_read_b128 v[170:173], v138
	ds_read_b128 v[174:177], v138 offset:1024
	ds_read_b128 v[178:181], v138 offset:2048
	ds_read_b128 v[204:207], v138 offset:3072
	v_lshl_add_u64 v[138:139], s[54:55], 0, v[134:135]
	s_add_i32 m0, s53, 0xc000
	ds_read_b128 v[208:211], v143
	ds_read_b128 v[212:215], v143 offset:1024
	ds_read_b128 v[216:219], v143 offset:2048
	ds_read_b128 v[220:223], v143 offset:3072
	ds_read_b128 v[224:227], v143 offset:4096
	ds_read_b128 v[228:231], v143 offset:5120
	ds_read_b128 v[232:235], v143 offset:6144
	ds_read_b128 v[236:239], v143 offset:7168
	global_load_lds_dwordx4 v[138:139], off
	v_lshl_add_u64 v[138:139], s[54:55], 0, v[136:137]
	s_add_i32 m0, s53, 0xe000
	s_nop 0
	global_load_lds_dwordx4 v[138:139], off
	s_waitcnt vmcnt(8)
	s_waitcnt lgkmcnt(0)
	s_barrier
	s_waitcnt lgkmcnt(0)
	v_mfma_f32_16x16x32_bf16 v[120:123], v[154:157], v[208:211], v[120:123]
	v_mfma_f32_16x16x32_bf16 v[124:127], v[162:165], v[208:211], v[124:127]
	v_mfma_f32_16x16x32_bf16 v[104:107], v[154:157], v[216:219], v[104:107]
	v_mfma_f32_16x16x32_bf16 v[108:111], v[162:165], v[216:219], v[108:111]
	v_mfma_f32_16x16x32_bf16 v[88:91], v[154:157], v[224:227], v[88:91]
	v_mfma_f32_16x16x32_bf16 v[92:95], v[162:165], v[224:227], v[92:95]
	v_mfma_f32_16x16x32_bf16 v[72:75], v[154:157], v[232:235], v[72:75]
	v_mfma_f32_16x16x32_bf16 v[76:79], v[162:165], v[232:235], v[76:79]
	v_mfma_f32_16x16x32_bf16 v[120:123], v[158:161], v[212:215], v[120:123]
	v_mfma_f32_16x16x32_bf16 v[124:127], v[166:169], v[212:215], v[124:127]
	v_mfma_f32_16x16x32_bf16 v[104:107], v[158:161], v[220:223], v[104:107]
	v_mfma_f32_16x16x32_bf16 v[108:111], v[166:169], v[220:223], v[108:111]
	v_mfma_f32_16x16x32_bf16 v[88:91], v[158:161], v[228:231], v[88:91]
	v_mfma_f32_16x16x32_bf16 v[92:95], v[166:169], v[228:231], v[92:95]
	v_mfma_f32_16x16x32_bf16 v[72:75], v[158:161], v[236:239], v[72:75]
	v_mfma_f32_16x16x32_bf16 v[76:79], v[166:169], v[236:239], v[76:79]
	v_mfma_f32_16x16x32_bf16 v[112:115], v[170:173], v[208:211], v[112:115]
	v_mfma_f32_16x16x32_bf16 v[116:119], v[178:181], v[208:211], v[116:119]
	v_mfma_f32_16x16x32_bf16 v[96:99], v[170:173], v[216:219], v[96:99]
	v_mfma_f32_16x16x32_bf16 v[100:103], v[178:181], v[216:219], v[100:103]
	v_mfma_f32_16x16x32_bf16 v[80:83], v[170:173], v[224:227], v[80:83]
	v_mfma_f32_16x16x32_bf16 v[84:87], v[178:181], v[224:227], v[84:87]
	v_mfma_f32_16x16x32_bf16 v[64:67], v[170:173], v[232:235], v[64:67]
	v_mfma_f32_16x16x32_bf16 v[68:71], v[178:181], v[232:235], v[68:71]
	v_mfma_f32_16x16x32_bf16 v[112:115], v[174:177], v[212:215], v[112:115]
	v_mfma_f32_16x16x32_bf16 v[116:119], v[204:207], v[212:215], v[116:119]
	v_mfma_f32_16x16x32_bf16 v[96:99], v[174:177], v[220:223], v[96:99]
	v_mfma_f32_16x16x32_bf16 v[100:103], v[204:207], v[220:223], v[100:103]
	v_mfma_f32_16x16x32_bf16 v[80:83], v[174:177], v[228:231], v[80:83]
	v_mfma_f32_16x16x32_bf16 v[84:87], v[204:207], v[228:231], v[84:87]
	v_mfma_f32_16x16x32_bf16 v[64:67], v[174:177], v[236:239], v[64:67]
	v_mfma_f32_16x16x32_bf16 v[68:71], v[204:207], v[236:239], v[68:71]
	s_barrier
	s_add_i32 s4, s72, s30
	v_lshl_add_u64 v[138:139], s[34:35], 0, v[144:145]
	s_mov_b32 m0, s4
	ds_read_b128 v[208:211], v143 offset:16384
	ds_read_b128 v[212:215], v143 offset:17408
	ds_read_b128 v[216:219], v143 offset:18432
	ds_read_b128 v[220:223], v143 offset:19456
	ds_read_b128 v[224:227], v143 offset:20480
	ds_read_b128 v[228:231], v143 offset:21504
	ds_read_b128 v[232:235], v143 offset:22528
	ds_read_b128 v[236:239], v143 offset:23552
	global_load_lds_dwordx4 v[138:139], off
	s_add_i32 m0, s4, 0x2000
	s_add_u32 s4, s34, 0x20000
	v_lshl_add_u64 v[202:203], s[34:35], 0, v[132:133]
	s_addc_u32 s5, s35, 0
	s_add_i32 s72, s73, s30
	global_load_lds_dwordx4 v[202:203], off
	v_lshl_add_u64 v[240:241], s[4:5], 0, v[144:145]
	s_mov_b32 m0, s72
	v_lshl_add_u64 v[242:243], s[58:59], 0, v[130:131]
	global_load_lds_dwordx4 v[240:241], off
	v_lshl_add_u64 v[240:241], s[4:5], 0, v[132:133]
	s_add_i32 m0, s72, 0x2000
	s_nop 0
	global_load_lds_dwordx4 v[240:241], off
	v_lshl_add_u64 v[240:241], s[58:59], 0, v[128:129]
	s_mov_b32 m0, s53
	s_nop 0
	global_load_lds_dwordx4 v[240:241], off
	s_mov_b32 m0, s62
	s_nop 0
	global_load_lds_dwordx4 v[242:243], off
	s_waitcnt vmcnt(8)
	s_waitcnt lgkmcnt(0)
	s_barrier
	s_waitcnt lgkmcnt(0)
	v_mfma_f32_16x16x32_bf16 v[56:59], v[154:157], v[208:211], v[56:59]
	v_mfma_f32_16x16x32_bf16 v[60:63], v[162:165], v[208:211], v[60:63]
	v_mfma_f32_16x16x32_bf16 v[40:43], v[154:157], v[216:219], v[40:43]
	v_mfma_f32_16x16x32_bf16 v[44:47], v[162:165], v[216:219], v[44:47]
	v_mfma_f32_16x16x32_bf16 v[24:27], v[154:157], v[224:227], v[24:27]
	v_mfma_f32_16x16x32_bf16 v[28:31], v[162:165], v[224:227], v[28:31]
	v_mfma_f32_16x16x32_bf16 v[8:11], v[154:157], v[232:235], v[8:11]
	v_mfma_f32_16x16x32_bf16 v[12:15], v[162:165], v[232:235], v[12:15]
	v_mfma_f32_16x16x32_bf16 v[56:59], v[158:161], v[212:215], v[56:59]
	v_mfma_f32_16x16x32_bf16 v[60:63], v[166:169], v[212:215], v[60:63]
	v_mfma_f32_16x16x32_bf16 v[40:43], v[158:161], v[220:223], v[40:43]
	v_mfma_f32_16x16x32_bf16 v[44:47], v[166:169], v[220:223], v[44:47]
	v_mfma_f32_16x16x32_bf16 v[24:27], v[158:161], v[228:231], v[24:27]
	v_mfma_f32_16x16x32_bf16 v[28:31], v[166:169], v[228:231], v[28:31]
	v_mfma_f32_16x16x32_bf16 v[8:11], v[158:161], v[236:239], v[8:11]
	v_mfma_f32_16x16x32_bf16 v[12:15], v[166:169], v[236:239], v[12:15]
	v_mfma_f32_16x16x32_bf16 v[48:51], v[170:173], v[208:211], v[48:51]
	v_mfma_f32_16x16x32_bf16 v[52:55], v[178:181], v[208:211], v[52:55]
	v_mfma_f32_16x16x32_bf16 v[32:35], v[170:173], v[216:219], v[32:35]
	v_mfma_f32_16x16x32_bf16 v[36:39], v[178:181], v[216:219], v[36:39]
	v_mfma_f32_16x16x32_bf16 v[16:19], v[170:173], v[224:227], v[16:19]
	v_mfma_f32_16x16x32_bf16 v[20:23], v[178:181], v[224:227], v[20:23]
	v_mfma_f32_16x16x32_bf16 v[0:3], v[170:173], v[232:235], v[0:3]
	v_mfma_f32_16x16x32_bf16 v[4:7], v[178:181], v[232:235], v[4:7]
	v_mfma_f32_16x16x32_bf16 v[48:51], v[174:177], v[212:215], v[48:51]
	v_mfma_f32_16x16x32_bf16 v[52:55], v[204:207], v[212:215], v[52:55]
	v_mfma_f32_16x16x32_bf16 v[32:35], v[174:177], v[220:223], v[32:35]
	v_mfma_f32_16x16x32_bf16 v[36:39], v[204:207], v[220:223], v[36:39]
	v_mfma_f32_16x16x32_bf16 v[16:19], v[174:177], v[228:231], v[16:19]
	v_mfma_f32_16x16x32_bf16 v[20:23], v[204:207], v[228:231], v[20:23]
	v_mfma_f32_16x16x32_bf16 v[0:3], v[174:177], v[236:239], v[0:3]
	v_mfma_f32_16x16x32_bf16 v[4:7], v[204:207], v[236:239], v[4:7]
	s_barrier
	s_add_i32 s72, 0, 0x18000
	s_add_i32 s73, 0, 0x1c000
	v_add_u32_e32 v166, s72, v141
	v_add_u32_e32 v204, s73, v141
	ds_read_b128 v[154:157], v166
	ds_read_b128 v[158:161], v166 offset:1024
	ds_read_b128 v[162:165], v166 offset:2048
	ds_read_b128 v[166:169], v166 offset:3072
	ds_read_b128 v[170:173], v204
	ds_read_b128 v[174:177], v204 offset:1024
	ds_read_b128 v[178:181], v204 offset:2048
	ds_read_b128 v[204:207], v204 offset:3072
	s_add_u32 s4, s58, 0x20000
	s_addc_u32 s5, s59, 0
	s_mov_b32 m0, s63
	v_lshl_add_u64 v[244:245], s[4:5], 0, v[128:129]
	ds_read_b128 v[208:211], v143 offset:32768
	ds_read_b128 v[212:215], v143 offset:33792
	ds_read_b128 v[216:219], v143 offset:34816
	ds_read_b128 v[220:223], v143 offset:35840
	ds_read_b128 v[224:227], v143 offset:36864
	ds_read_b128 v[228:231], v143 offset:37888
	ds_read_b128 v[232:235], v143 offset:38912
	ds_read_b128 v[236:239], v143 offset:39936
	global_load_lds_dwordx4 v[244:245], off
	v_lshl_add_u64 v[244:245], s[4:5], 0, v[130:131]
	s_mov_b32 m0, s64
	s_nop 0
	global_load_lds_dwordx4 v[244:245], off
	s_waitcnt vmcnt(8)
	s_waitcnt lgkmcnt(0)
	s_barrier
	s_waitcnt lgkmcnt(0)
	v_mfma_f32_16x16x32_bf16 v[120:123], v[154:157], v[208:211], v[120:123]
	v_mfma_f32_16x16x32_bf16 v[124:127], v[162:165], v[208:211], v[124:127]
	v_mfma_f32_16x16x32_bf16 v[104:107], v[154:157], v[216:219], v[104:107]
	v_mfma_f32_16x16x32_bf16 v[108:111], v[162:165], v[216:219], v[108:111]
	v_mfma_f32_16x16x32_bf16 v[88:91], v[154:157], v[224:227], v[88:91]
	v_mfma_f32_16x16x32_bf16 v[92:95], v[162:165], v[224:227], v[92:95]
	v_mfma_f32_16x16x32_bf16 v[72:75], v[154:157], v[232:235], v[72:75]
	v_mfma_f32_16x16x32_bf16 v[76:79], v[162:165], v[232:235], v[76:79]
	v_mfma_f32_16x16x32_bf16 v[120:123], v[158:161], v[212:215], v[120:123]
	v_mfma_f32_16x16x32_bf16 v[124:127], v[166:169], v[212:215], v[124:127]
	v_mfma_f32_16x16x32_bf16 v[104:107], v[158:161], v[220:223], v[104:107]
	v_mfma_f32_16x16x32_bf16 v[108:111], v[166:169], v[220:223], v[108:111]
	v_mfma_f32_16x16x32_bf16 v[88:91], v[158:161], v[228:231], v[88:91]
	v_mfma_f32_16x16x32_bf16 v[92:95], v[166:169], v[228:231], v[92:95]
	v_mfma_f32_16x16x32_bf16 v[72:75], v[158:161], v[236:239], v[72:75]
	v_mfma_f32_16x16x32_bf16 v[76:79], v[166:169], v[236:239], v[76:79]
	v_mfma_f32_16x16x32_bf16 v[112:115], v[170:173], v[208:211], v[112:115]
	v_mfma_f32_16x16x32_bf16 v[116:119], v[178:181], v[208:211], v[116:119]
	v_mfma_f32_16x16x32_bf16 v[96:99], v[170:173], v[216:219], v[96:99]
	v_mfma_f32_16x16x32_bf16 v[100:103], v[178:181], v[216:219], v[100:103]
	v_mfma_f32_16x16x32_bf16 v[80:83], v[170:173], v[224:227], v[80:83]
	v_mfma_f32_16x16x32_bf16 v[84:87], v[178:181], v[224:227], v[84:87]
	v_mfma_f32_16x16x32_bf16 v[64:67], v[170:173], v[232:235], v[64:67]
	v_mfma_f32_16x16x32_bf16 v[68:71], v[178:181], v[232:235], v[68:71]
	v_mfma_f32_16x16x32_bf16 v[112:115], v[174:177], v[212:215], v[112:115]
	v_mfma_f32_16x16x32_bf16 v[116:119], v[204:207], v[212:215], v[116:119]
	v_mfma_f32_16x16x32_bf16 v[96:99], v[174:177], v[220:223], v[96:99]
	v_mfma_f32_16x16x32_bf16 v[100:103], v[204:207], v[220:223], v[100:103]
	v_mfma_f32_16x16x32_bf16 v[80:83], v[174:177], v[228:231], v[80:83]
	v_mfma_f32_16x16x32_bf16 v[84:87], v[204:207], v[228:231], v[84:87]
	v_mfma_f32_16x16x32_bf16 v[64:67], v[174:177], v[236:239], v[64:67]
	v_mfma_f32_16x16x32_bf16 v[68:71], v[204:207], v[236:239], v[68:71]
	s_barrier
	s_add_i32 s4, s72, s30
	v_lshl_add_u64 v[138:139], v[138:139], 0, s[26:27]
	s_mov_b32 m0, s4
	ds_read_b128 v[208:211], v143 offset:49152
	ds_read_b128 v[212:215], v143 offset:50176
	ds_read_b128 v[216:219], v143 offset:51200
	ds_read_b128 v[220:223], v143 offset:52224
	ds_read_b128 v[224:227], v143 offset:53248
	ds_read_b128 v[228:231], v143 offset:54272
	ds_read_b128 v[232:235], v143 offset:55296
	ds_read_b128 v[236:239], v143 offset:56320
	global_load_lds_dwordx4 v[138:139], off
	s_add_i32 m0, s4, 0x2000
	s_add_u32 s4, s34, 0x20080
	v_lshl_add_u64 v[138:139], v[202:203], 0, s[26:27]
	s_addc_u32 s5, s35, 0
	s_add_i32 s34, s73, s30
	global_load_lds_dwordx4 v[138:139], off
	v_lshl_add_u64 v[138:139], s[4:5], 0, v[144:145]
	s_mov_b32 m0, s34
	s_nop 0
	global_load_lds_dwordx4 v[138:139], off
	v_lshl_add_u64 v[138:139], s[4:5], 0, v[132:133]
	s_add_i32 m0, s34, 0x2000
	s_nop 0
	global_load_lds_dwordx4 v[138:139], off
	v_lshl_add_u64 v[138:139], v[240:241], 0, s[26:27]
	s_mov_b32 m0, s65
	s_nop 0
	global_load_lds_dwordx4 v[138:139], off
	v_lshl_add_u64 v[138:139], v[242:243], 0, s[26:27]
	s_mov_b32 m0, s66
	s_nop 0
	global_load_lds_dwordx4 v[138:139], off
	s_waitcnt vmcnt(8)
	s_waitcnt lgkmcnt(0)
	s_barrier
	s_waitcnt lgkmcnt(0)
	v_mfma_f32_16x16x32_bf16 v[56:59], v[154:157], v[208:211], v[56:59]
	v_mfma_f32_16x16x32_bf16 v[60:63], v[162:165], v[208:211], v[60:63]
	v_mfma_f32_16x16x32_bf16 v[40:43], v[154:157], v[216:219], v[40:43]
	v_mfma_f32_16x16x32_bf16 v[44:47], v[162:165], v[216:219], v[44:47]
	v_mfma_f32_16x16x32_bf16 v[24:27], v[154:157], v[224:227], v[24:27]
	v_mfma_f32_16x16x32_bf16 v[28:31], v[162:165], v[224:227], v[28:31]
	v_mfma_f32_16x16x32_bf16 v[8:11], v[154:157], v[232:235], v[8:11]
	v_mfma_f32_16x16x32_bf16 v[12:15], v[162:165], v[232:235], v[12:15]
	v_mfma_f32_16x16x32_bf16 v[56:59], v[158:161], v[212:215], v[56:59]
	v_mfma_f32_16x16x32_bf16 v[60:63], v[166:169], v[212:215], v[60:63]
	v_mfma_f32_16x16x32_bf16 v[40:43], v[158:161], v[220:223], v[40:43]
	v_mfma_f32_16x16x32_bf16 v[44:47], v[166:169], v[220:223], v[44:47]
	v_mfma_f32_16x16x32_bf16 v[24:27], v[158:161], v[228:231], v[24:27]
	v_mfma_f32_16x16x32_bf16 v[28:31], v[166:169], v[228:231], v[28:31]
	v_mfma_f32_16x16x32_bf16 v[8:11], v[158:161], v[236:239], v[8:11]
	v_mfma_f32_16x16x32_bf16 v[12:15], v[166:169], v[236:239], v[12:15]
	v_mfma_f32_16x16x32_bf16 v[48:51], v[170:173], v[208:211], v[48:51]
	v_mfma_f32_16x16x32_bf16 v[52:55], v[178:181], v[208:211], v[52:55]
	v_mfma_f32_16x16x32_bf16 v[32:35], v[170:173], v[216:219], v[32:35]
	v_mfma_f32_16x16x32_bf16 v[36:39], v[178:181], v[216:219], v[36:39]
	v_mfma_f32_16x16x32_bf16 v[16:19], v[170:173], v[224:227], v[16:19]
	v_mfma_f32_16x16x32_bf16 v[20:23], v[178:181], v[224:227], v[20:23]
	v_mfma_f32_16x16x32_bf16 v[0:3], v[170:173], v[232:235], v[0:3]
	v_mfma_f32_16x16x32_bf16 v[4:7], v[178:181], v[232:235], v[4:7]
	v_mfma_f32_16x16x32_bf16 v[48:51], v[174:177], v[212:215], v[48:51]
	v_mfma_f32_16x16x32_bf16 v[52:55], v[204:207], v[212:215], v[52:55]
	v_mfma_f32_16x16x32_bf16 v[32:35], v[174:177], v[220:223], v[32:35]
	v_mfma_f32_16x16x32_bf16 v[36:39], v[204:207], v[220:223], v[36:39]
	v_mfma_f32_16x16x32_bf16 v[16:19], v[174:177], v[228:231], v[16:19]
	v_mfma_f32_16x16x32_bf16 v[20:23], v[204:207], v[228:231], v[20:23]
	v_mfma_f32_16x16x32_bf16 v[0:3], v[174:177], v[236:239], v[0:3]
	v_mfma_f32_16x16x32_bf16 v[4:7], v[204:207], v[236:239], v[4:7]
	s_barrier
	s_add_i32 s71, s71, 2
	s_add_u32 s54, s54, 0x100
	s_addc_u32 s55, s55, 0
	s_add_u32 s69, s69, 0x100
	s_addc_u32 s70, s70, 0
	s_cmp_gt_u32 s71, 5
	s_cbranch_scc0 .LBB0_1005
	s_setprio 0
	v_readlane_b32 s68, v255, 7
	s_and_b64 vcc, exec, s[42:43]
	v_readlane_b32 s69, v255, 8
	s_cbranch_vccz .LBB0_1008
	s_barrier

.LBB0_1092:
	s_ashr_i32 s51, s50, 31
	s_lshl_b64 s[4:5], s[50:51], 18
	s_add_u32 s52, s29, s4
	s_addc_u32 s53, s30, s5
	s_and_b64 s[4:5], s[38:39], exec
	s_cselect_b32 s33, s53, s59
	s_cselect_b32 s36, s52, s58
	s_ashr_i32 s49, s48, 31
	s_lshl_b64 s[4:5], s[48:49], 18
	s_add_u32 s54, s62, s4
	s_addc_u32 s55, s63, s5
	s_and_b64 s[4:5], s[38:39], exec
	s_cselect_b32 s49, s55, s61
	s_cselect_b32 s51, s54, s60
	s_add_u32 s58, s58, 0x20080
	s_addc_u32 s59, s59, 0
	s_add_u32 s71, s60, 0x100
	v_mov_b32_e32 v0, 0
	s_addc_u32 s72, s61, 0
	s_mov_b32 s73, -2
	v_mov_b32_e32 v1, v0
	v_mov_b32_e32 v2, v0
	v_mov_b32_e32 v3, v0
	v_mov_b32_e32 v4, v0
	v_mov_b32_e32 v5, v0
	v_mov_b32_e32 v6, v0
	v_mov_b32_e32 v7, v0
	v_mov_b32_e32 v16, v0
	v_mov_b32_e32 v17, v0
	v_mov_b32_e32 v18, v0
	v_mov_b32_e32 v19, v0
	v_mov_b32_e32 v20, v0
	v_mov_b32_e32 v21, v0
	v_mov_b32_e32 v22, v0
	v_mov_b32_e32 v23, v0
	v_mov_b32_e32 v32, v0
	v_mov_b32_e32 v33, v0
	v_mov_b32_e32 v34, v0
	v_mov_b32_e32 v35, v0
	v_mov_b32_e32 v36, v0
	v_mov_b32_e32 v37, v0
	v_mov_b32_e32 v38, v0
	v_mov_b32_e32 v39, v0
	v_mov_b32_e32 v48, v0
	v_mov_b32_e32 v49, v0
	v_mov_b32_e32 v50, v0
	v_mov_b32_e32 v51, v0
	v_mov_b32_e32 v52, v0
	v_mov_b32_e32 v53, v0
	v_mov_b32_e32 v54, v0
	v_mov_b32_e32 v55, v0
	v_mov_b32_e32 v8, v0
	v_mov_b32_e32 v9, v0
	v_mov_b32_e32 v10, v0
	v_mov_b32_e32 v11, v0
	v_mov_b32_e32 v12, v0
	v_mov_b32_e32 v13, v0
	v_mov_b32_e32 v14, v0
	v_mov_b32_e32 v15, v0
	v_mov_b32_e32 v24, v0
	v_mov_b32_e32 v25, v0
	v_mov_b32_e32 v26, v0
	v_mov_b32_e32 v27, v0
	v_mov_b32_e32 v28, v0
	v_mov_b32_e32 v29, v0
	v_mov_b32_e32 v30, v0
	v_mov_b32_e32 v31, v0
	v_mov_b32_e32 v40, v0
	v_mov_b32_e32 v41, v0
	v_mov_b32_e32 v42, v0
	v_mov_b32_e32 v43, v0
	v_mov_b32_e32 v44, v0
	v_mov_b32_e32 v45, v0
	v_mov_b32_e32 v46, v0
	v_mov_b32_e32 v47, v0
	v_mov_b32_e32 v56, v0
	v_mov_b32_e32 v57, v0
	v_mov_b32_e32 v58, v0
	v_mov_b32_e32 v59, v0
	v_mov_b32_e32 v60, v0
	v_mov_b32_e32 v61, v0
	v_mov_b32_e32 v62, v0
	v_mov_b32_e32 v63, v0
	v_mov_b32_e32 v64, v0
	v_mov_b32_e32 v65, v0
	v_mov_b32_e32 v66, v0
	v_mov_b32_e32 v67, v0
	v_mov_b32_e32 v68, v0
	v_mov_b32_e32 v69, v0
	v_mov_b32_e32 v70, v0
	v_mov_b32_e32 v71, v0
	v_mov_b32_e32 v80, v0
	v_mov_b32_e32 v81, v0
	v_mov_b32_e32 v82, v0
	v_mov_b32_e32 v83, v0
	v_mov_b32_e32 v84, v0
	v_mov_b32_e32 v85, v0
	v_mov_b32_e32 v86, v0
	v_mov_b32_e32 v87, v0
	v_mov_b32_e32 v96, v0
	v_mov_b32_e32 v97, v0
	v_mov_b32_e32 v98, v0
	v_mov_b32_e32 v99, v0
	v_mov_b32_e32 v100, v0
	v_mov_b32_e32 v101, v0
	v_mov_b32_e32 v102, v0
	v_mov_b32_e32 v103, v0
	v_mov_b32_e32 v112, v0
	v_mov_b32_e32 v113, v0
	v_mov_b32_e32 v114, v0
	v_mov_b32_e32 v115, v0
	v_mov_b32_e32 v116, v0
	v_mov_b32_e32 v117, v0
	v_mov_b32_e32 v118, v0
	v_mov_b32_e32 v119, v0
	v_mov_b32_e32 v72, v0
	v_mov_b32_e32 v73, v0
	v_mov_b32_e32 v74, v0
	v_mov_b32_e32 v75, v0
	v_mov_b32_e32 v76, v0
	v_mov_b32_e32 v77, v0
	v_mov_b32_e32 v78, v0
	v_mov_b32_e32 v79, v0
	v_mov_b32_e32 v88, v0
	v_mov_b32_e32 v89, v0
	v_mov_b32_e32 v90, v0
	v_mov_b32_e32 v91, v0
	v_mov_b32_e32 v92, v0
	v_mov_b32_e32 v93, v0
	v_mov_b32_e32 v94, v0
	v_mov_b32_e32 v95, v0
	v_mov_b32_e32 v104, v0
	v_mov_b32_e32 v105, v0
	v_mov_b32_e32 v106, v0
	v_mov_b32_e32 v107, v0
	v_mov_b32_e32 v108, v0
	v_mov_b32_e32 v109, v0
	v_mov_b32_e32 v110, v0
	v_mov_b32_e32 v111, v0
	v_mov_b32_e32 v120, v0
	v_mov_b32_e32 v121, v0
	v_mov_b32_e32 v122, v0
	v_mov_b32_e32 v123, v0
	v_mov_b32_e32 v124, v0
	v_mov_b32_e32 v125, v0
	v_mov_b32_e32 v126, v0
	v_mov_b32_e32 v127, v0
	v_readfirstlane_b32 s4, v182
	s_nop 3
	s_cmp_lt_u32 s4, 256
	s_cbranch_scc1 .Lkprio_1093
	s_setprio 1
.Lkprio_1093:
.LBB0_1093:
	s_add_u32 s4, s58, 0xfffe0080
	s_addc_u32 s5, s59, -1
	s_add_i32 s74, 0, 0x10000
	s_cmp_eq_u32 s73, 4
	s_cselect_b32 s61, s33, s5
	s_cselect_b32 s60, s36, s4
	s_cselect_b32 s35, s49, s72
	s_cselect_b32 s34, s51, s71
	s_add_i32 s75, 0, 0x14000
	v_add_u32_e32 v164, s74, v143
	v_add_u32_e32 v180, s75, v143
	ds_read_b128 v[138:141], v164
	ds_read_b128 v[156:159], v164 offset:1024
	ds_read_b128 v[160:163], v164 offset:2048
	ds_read_b128 v[164:167], v164 offset:3072
	ds_read_b128 v[168:171], v180
	ds_read_b128 v[172:175], v180 offset:1024
	ds_read_b128 v[176:179], v180 offset:2048
	ds_read_b128 v[204:207], v180 offset:3072
	v_lshl_add_u64 v[180:181], s[58:59], 0, v[134:135]
	s_add_i32 m0, s64, 0xc000
	ds_read_b128 v[208:211], v155
	ds_read_b128 v[212:215], v155 offset:1024
	ds_read_b128 v[216:219], v155 offset:2048
	ds_read_b128 v[220:223], v155 offset:3072
	ds_read_b128 v[224:227], v155 offset:4096
	ds_read_b128 v[228:231], v155 offset:5120
	ds_read_b128 v[232:235], v155 offset:6144
	ds_read_b128 v[236:239], v155 offset:7168
	global_load_lds_dwordx4 v[180:181], off
	v_lshl_add_u64 v[180:181], s[58:59], 0, v[136:137]
	s_add_i32 m0, s64, 0xe000
	s_nop 0
	global_load_lds_dwordx4 v[180:181], off
	s_waitcnt vmcnt(8)
	s_waitcnt lgkmcnt(0)
	s_barrier
	s_waitcnt lgkmcnt(0)
	v_mfma_f32_16x16x32_bf16 v[124:127], v[138:141], v[208:211], v[124:127]
	v_mfma_f32_16x16x32_bf16 v[120:123], v[160:163], v[208:211], v[120:123]
	v_mfma_f32_16x16x32_bf16 v[108:111], v[138:141], v[216:219], v[108:111]
	v_mfma_f32_16x16x32_bf16 v[104:107], v[160:163], v[216:219], v[104:107]
	v_mfma_f32_16x16x32_bf16 v[92:95], v[138:141], v[224:227], v[92:95]
	v_mfma_f32_16x16x32_bf16 v[88:91], v[160:163], v[224:227], v[88:91]
	v_mfma_f32_16x16x32_bf16 v[76:79], v[138:141], v[232:235], v[76:79]
	v_mfma_f32_16x16x32_bf16 v[72:75], v[160:163], v[232:235], v[72:75]
	v_mfma_f32_16x16x32_bf16 v[124:127], v[156:159], v[212:215], v[124:127]
	v_mfma_f32_16x16x32_bf16 v[120:123], v[164:167], v[212:215], v[120:123]
	v_mfma_f32_16x16x32_bf16 v[108:111], v[156:159], v[220:223], v[108:111]
	v_mfma_f32_16x16x32_bf16 v[104:107], v[164:167], v[220:223], v[104:107]
	v_mfma_f32_16x16x32_bf16 v[92:95], v[156:159], v[228:231], v[92:95]
	v_mfma_f32_16x16x32_bf16 v[88:91], v[164:167], v[228:231], v[88:91]
	v_mfma_f32_16x16x32_bf16 v[76:79], v[156:159], v[236:239], v[76:79]
	v_mfma_f32_16x16x32_bf16 v[72:75], v[164:167], v[236:239], v[72:75]
	v_mfma_f32_16x16x32_bf16 v[116:119], v[168:171], v[208:211], v[116:119]
	v_mfma_f32_16x16x32_bf16 v[112:115], v[176:179], v[208:211], v[112:115]
	v_mfma_f32_16x16x32_bf16 v[100:103], v[168:171], v[216:219], v[100:103]
	v_mfma_f32_16x16x32_bf16 v[96:99], v[176:179], v[216:219], v[96:99]
	v_mfma_f32_16x16x32_bf16 v[84:87], v[168:171], v[224:227], v[84:87]
	v_mfma_f32_16x16x32_bf16 v[80:83], v[176:179], v[224:227], v[80:83]
	v_mfma_f32_16x16x32_bf16 v[68:71], v[168:171], v[232:235], v[68:71]
	v_mfma_f32_16x16x32_bf16 v[64:67], v[176:179], v[232:235], v[64:67]
	v_mfma_f32_16x16x32_bf16 v[116:119], v[172:175], v[212:215], v[116:119]
	v_mfma_f32_16x16x32_bf16 v[112:115], v[204:207], v[212:215], v[112:115]
	v_mfma_f32_16x16x32_bf16 v[100:103], v[172:175], v[220:223], v[100:103]
	v_mfma_f32_16x16x32_bf16 v[96:99], v[204:207], v[220:223], v[96:99]
	v_mfma_f32_16x16x32_bf16 v[84:87], v[172:175], v[228:231], v[84:87]
	v_mfma_f32_16x16x32_bf16 v[80:83], v[204:207], v[228:231], v[80:83]
	v_mfma_f32_16x16x32_bf16 v[68:71], v[172:175], v[236:239], v[68:71]
	v_mfma_f32_16x16x32_bf16 v[64:67], v[204:207], v[236:239], v[64:67]
	s_barrier
	s_add_i32 s4, s74, s28
	v_lshl_add_u64 v[180:181], s[34:35], 0, v[144:145]
	s_mov_b32 m0, s4
	ds_read_b128 v[208:211], v155 offset:16384
	ds_read_b128 v[212:215], v155 offset:17408
	ds_read_b128 v[216:219], v155 offset:18432
	ds_read_b128 v[220:223], v155 offset:19456
	ds_read_b128 v[224:227], v155 offset:20480
	ds_read_b128 v[228:231], v155 offset:21504
	ds_read_b128 v[232:235], v155 offset:22528
	ds_read_b128 v[236:239], v155 offset:23552
	global_load_lds_dwordx4 v[180:181], off
	s_add_i32 m0, s4, 0x2000
	s_add_u32 s4, s34, 0x20000
	v_lshl_add_u64 v[202:203], s[34:35], 0, v[132:133]
	s_addc_u32 s5, s35, 0
	s_add_i32 s74, s75, s28
	global_load_lds_dwordx4 v[202:203], off
	v_lshl_add_u64 v[240:241], s[4:5], 0, v[144:145]
	s_mov_b32 m0, s74
	v_lshl_add_u64 v[242:243], s[60:61], 0, v[130:131]
	global_load_lds_dwordx4 v[240:241], off
	v_lshl_add_u64 v[240:241], s[4:5], 0, v[132:133]
	s_add_i32 m0, s74, 0x2000
	s_nop 0
	global_load_lds_dwordx4 v[240:241], off
	v_lshl_add_u64 v[240:241], s[60:61], 0, v[128:129]
	s_mov_b32 m0, s64
	s_nop 0
	global_load_lds_dwordx4 v[240:241], off
	s_mov_b32 m0, s65
	s_nop 0
	global_load_lds_dwordx4 v[242:243], off
	s_waitcnt vmcnt(8)
	s_waitcnt lgkmcnt(0)
	s_barrier
	s_waitcnt lgkmcnt(0)
	v_mfma_f32_16x16x32_bf16 v[60:63], v[138:141], v[208:211], v[60:63]
	v_mfma_f32_16x16x32_bf16 v[56:59], v[160:163], v[208:211], v[56:59]
	v_mfma_f32_16x16x32_bf16 v[44:47], v[138:141], v[216:219], v[44:47]
	v_mfma_f32_16x16x32_bf16 v[40:43], v[160:163], v[216:219], v[40:43]
	v_mfma_f32_16x16x32_bf16 v[28:31], v[138:141], v[224:227], v[28:31]
	v_mfma_f32_16x16x32_bf16 v[24:27], v[160:163], v[224:227], v[24:27]
	v_mfma_f32_16x16x32_bf16 v[12:15], v[138:141], v[232:235], v[12:15]
	v_mfma_f32_16x16x32_bf16 v[8:11], v[160:163], v[232:235], v[8:11]
	v_mfma_f32_16x16x32_bf16 v[60:63], v[156:159], v[212:215], v[60:63]
	v_mfma_f32_16x16x32_bf16 v[56:59], v[164:167], v[212:215], v[56:59]
	v_mfma_f32_16x16x32_bf16 v[44:47], v[156:159], v[220:223], v[44:47]
	v_mfma_f32_16x16x32_bf16 v[40:43], v[164:167], v[220:223], v[40:43]
	v_mfma_f32_16x16x32_bf16 v[28:31], v[156:159], v[228:231], v[28:31]
	v_mfma_f32_16x16x32_bf16 v[24:27], v[164:167], v[228:231], v[24:27]
	v_mfma_f32_16x16x32_bf16 v[12:15], v[156:159], v[236:239], v[12:15]
	v_mfma_f32_16x16x32_bf16 v[8:11], v[164:167], v[236:239], v[8:11]
	v_mfma_f32_16x16x32_bf16 v[52:55], v[168:171], v[208:211], v[52:55]
	v_mfma_f32_16x16x32_bf16 v[48:51], v[176:179], v[208:211], v[48:51]
	v_mfma_f32_16x16x32_bf16 v[36:39], v[168:171], v[216:219], v[36:39]
	v_mfma_f32_16x16x32_bf16 v[32:35], v[176:179], v[216:219], v[32:35]
	v_mfma_f32_16x16x32_bf16 v[20:23], v[168:171], v[224:227], v[20:23]
	v_mfma_f32_16x16x32_bf16 v[16:19], v[176:179], v[224:227], v[16:19]
	v_mfma_f32_16x16x32_bf16 v[4:7], v[168:171], v[232:235], v[4:7]
	v_mfma_f32_16x16x32_bf16 v[0:3], v[176:179], v[232:235], v[0:3]
	v_mfma_f32_16x16x32_bf16 v[52:55], v[172:175], v[212:215], v[52:55]
	v_mfma_f32_16x16x32_bf16 v[48:51], v[204:207], v[212:215], v[48:51]
	v_mfma_f32_16x16x32_bf16 v[36:39], v[172:175], v[220:223], v[36:39]
	v_mfma_f32_16x16x32_bf16 v[32:35], v[204:207], v[220:223], v[32:35]
	v_mfma_f32_16x16x32_bf16 v[20:23], v[172:175], v[228:231], v[20:23]
	v_mfma_f32_16x16x32_bf16 v[16:19], v[204:207], v[228:231], v[16:19]
	v_mfma_f32_16x16x32_bf16 v[4:7], v[172:175], v[236:239], v[4:7]
	v_mfma_f32_16x16x32_bf16 v[0:3], v[204:207], v[236:239], v[0:3]
	s_barrier
	s_add_i32 s74, 0, 0x18000
	s_add_i32 s75, 0, 0x1c000
	v_add_u32_e32 v164, s74, v143
	v_add_u32_e32 v204, s75, v143
	ds_read_b128 v[138:141], v164
	ds_read_b128 v[156:159], v164 offset:1024
	ds_read_b128 v[160:163], v164 offset:2048
	ds_read_b128 v[164:167], v164 offset:3072
	ds_read_b128 v[168:171], v204
	ds_read_b128 v[172:175], v204 offset:1024
	ds_read_b128 v[176:179], v204 offset:2048
	ds_read_b128 v[204:207], v204 offset:3072
	s_add_u32 s4, s60, 0x20000
	s_addc_u32 s5, s61, 0
	s_mov_b32 m0, s66
	v_lshl_add_u64 v[244:245], s[4:5], 0, v[128:129]
	ds_read_b128 v[208:211], v155 offset:32768
	ds_read_b128 v[212:215], v155 offset:33792
	ds_read_b128 v[216:219], v155 offset:34816
	ds_read_b128 v[220:223], v155 offset:35840
	ds_read_b128 v[224:227], v155 offset:36864
	ds_read_b128 v[228:231], v155 offset:37888
	ds_read_b128 v[232:235], v155 offset:38912
	ds_read_b128 v[236:239], v155 offset:39936
	global_load_lds_dwordx4 v[244:245], off
	v_lshl_add_u64 v[244:245], s[4:5], 0, v[130:131]
	s_mov_b32 m0, s67
	s_nop 0
	global_load_lds_dwordx4 v[244:245], off
	s_waitcnt vmcnt(8)
	s_waitcnt lgkmcnt(0)
	s_barrier
	s_waitcnt lgkmcnt(0)
	v_mfma_f32_16x16x32_bf16 v[124:127], v[138:141], v[208:211], v[124:127]
	v_mfma_f32_16x16x32_bf16 v[120:123], v[160:163], v[208:211], v[120:123]
	v_mfma_f32_16x16x32_bf16 v[108:111], v[138:141], v[216:219], v[108:111]
	v_mfma_f32_16x16x32_bf16 v[104:107], v[160:163], v[216:219], v[104:107]
	v_mfma_f32_16x16x32_bf16 v[92:95], v[138:141], v[224:227], v[92:95]
	v_mfma_f32_16x16x32_bf16 v[88:91], v[160:163], v[224:227], v[88:91]
	v_mfma_f32_16x16x32_bf16 v[76:79], v[138:141], v[232:235], v[76:79]
	v_mfma_f32_16x16x32_bf16 v[72:75], v[160:163], v[232:235], v[72:75]
	v_mfma_f32_16x16x32_bf16 v[124:127], v[156:159], v[212:215], v[124:127]
	v_mfma_f32_16x16x32_bf16 v[120:123], v[164:167], v[212:215], v[120:123]
	v_mfma_f32_16x16x32_bf16 v[108:111], v[156:159], v[220:223], v[108:111]
	v_mfma_f32_16x16x32_bf16 v[104:107], v[164:167], v[220:223], v[104:107]
	v_mfma_f32_16x16x32_bf16 v[92:95], v[156:159], v[228:231], v[92:95]
	v_mfma_f32_16x16x32_bf16 v[88:91], v[164:167], v[228:231], v[88:91]
	v_mfma_f32_16x16x32_bf16 v[76:79], v[156:159], v[236:239], v[76:79]
	v_mfma_f32_16x16x32_bf16 v[72:75], v[164:167], v[236:239], v[72:75]
	v_mfma_f32_16x16x32_bf16 v[116:119], v[168:171], v[208:211], v[116:119]
	v_mfma_f32_16x16x32_bf16 v[112:115], v[176:179], v[208:211], v[112:115]
	v_mfma_f32_16x16x32_bf16 v[100:103], v[168:171], v[216:219], v[100:103]
	v_mfma_f32_16x16x32_bf16 v[96:99], v[176:179], v[216:219], v[96:99]
	v_mfma_f32_16x16x32_bf16 v[84:87], v[168:171], v[224:227], v[84:87]
	v_mfma_f32_16x16x32_bf16 v[80:83], v[176:179], v[224:227], v[80:83]
	v_mfma_f32_16x16x32_bf16 v[68:71], v[168:171], v[232:235], v[68:71]
	v_mfma_f32_16x16x32_bf16 v[64:67], v[176:179], v[232:235], v[64:67]
	v_mfma_f32_16x16x32_bf16 v[116:119], v[172:175], v[212:215], v[116:119]
	v_mfma_f32_16x16x32_bf16 v[112:115], v[204:207], v[212:215], v[112:115]
	v_mfma_f32_16x16x32_bf16 v[100:103], v[172:175], v[220:223], v[100:103]
	v_mfma_f32_16x16x32_bf16 v[96:99], v[204:207], v[220:223], v[96:99]
	v_mfma_f32_16x16x32_bf16 v[84:87], v[172:175], v[228:231], v[84:87]
	v_mfma_f32_16x16x32_bf16 v[80:83], v[204:207], v[228:231], v[80:83]
	v_mfma_f32_16x16x32_bf16 v[68:71], v[172:175], v[236:239], v[68:71]
	v_mfma_f32_16x16x32_bf16 v[64:67], v[204:207], v[236:239], v[64:67]
	s_barrier
	s_add_i32 s4, s74, s28
	v_lshl_add_u64 v[180:181], v[180:181], 0, s[26:27]
	s_mov_b32 m0, s4
	ds_read_b128 v[208:211], v155 offset:49152
	ds_read_b128 v[212:215], v155 offset:50176
	ds_read_b128 v[216:219], v155 offset:51200
	ds_read_b128 v[220:223], v155 offset:52224
	ds_read_b128 v[224:227], v155 offset:53248
	ds_read_b128 v[228:231], v155 offset:54272
	ds_read_b128 v[232:235], v155 offset:55296
	ds_read_b128 v[236:239], v155 offset:56320
	global_load_lds_dwordx4 v[180:181], off
	s_add_i32 m0, s4, 0x2000
	s_add_u32 s4, s34, 0x20080
	v_lshl_add_u64 v[180:181], v[202:203], 0, s[26:27]
	s_addc_u32 s5, s35, 0
	s_add_i32 s34, s75, s28
	global_load_lds_dwordx4 v[180:181], off
	v_lshl_add_u64 v[180:181], s[4:5], 0, v[144:145]
	s_mov_b32 m0, s34
	s_nop 0
	global_load_lds_dwordx4 v[180:181], off
	v_lshl_add_u64 v[180:181], s[4:5], 0, v[132:133]
	s_add_i32 m0, s34, 0x2000
	s_nop 0
	global_load_lds_dwordx4 v[180:181], off
	v_lshl_add_u64 v[180:181], v[240:241], 0, s[26:27]
	s_mov_b32 m0, s68
	s_nop 0
	global_load_lds_dwordx4 v[180:181], off
	v_lshl_add_u64 v[180:181], v[242:243], 0, s[26:27]
	s_mov_b32 m0, s69
	s_nop 0
	global_load_lds_dwordx4 v[180:181], off
	s_waitcnt vmcnt(8)
	s_waitcnt lgkmcnt(0)
	s_barrier
	s_waitcnt lgkmcnt(0)
	v_mfma_f32_16x16x32_bf16 v[60:63], v[138:141], v[208:211], v[60:63]
	v_mfma_f32_16x16x32_bf16 v[56:59], v[160:163], v[208:211], v[56:59]
	v_mfma_f32_16x16x32_bf16 v[44:47], v[138:141], v[216:219], v[44:47]
	v_mfma_f32_16x16x32_bf16 v[40:43], v[160:163], v[216:219], v[40:43]
	v_mfma_f32_16x16x32_bf16 v[28:31], v[138:141], v[224:227], v[28:31]
	v_mfma_f32_16x16x32_bf16 v[24:27], v[160:163], v[224:227], v[24:27]
	v_mfma_f32_16x16x32_bf16 v[12:15], v[138:141], v[232:235], v[12:15]
	v_mfma_f32_16x16x32_bf16 v[8:11], v[160:163], v[232:235], v[8:11]
	v_mfma_f32_16x16x32_bf16 v[60:63], v[156:159], v[212:215], v[60:63]
	v_mfma_f32_16x16x32_bf16 v[56:59], v[164:167], v[212:215], v[56:59]
	v_mfma_f32_16x16x32_bf16 v[44:47], v[156:159], v[220:223], v[44:47]
	v_mfma_f32_16x16x32_bf16 v[40:43], v[164:167], v[220:223], v[40:43]
	v_mfma_f32_16x16x32_bf16 v[28:31], v[156:159], v[228:231], v[28:31]
	v_mfma_f32_16x16x32_bf16 v[24:27], v[164:167], v[228:231], v[24:27]
	v_mfma_f32_16x16x32_bf16 v[12:15], v[156:159], v[236:239], v[12:15]
	v_mfma_f32_16x16x32_bf16 v[8:11], v[164:167], v[236:239], v[8:11]
	v_mfma_f32_16x16x32_bf16 v[52:55], v[168:171], v[208:211], v[52:55]
	v_mfma_f32_16x16x32_bf16 v[48:51], v[176:179], v[208:211], v[48:51]
	v_mfma_f32_16x16x32_bf16 v[36:39], v[168:171], v[216:219], v[36:39]
	v_mfma_f32_16x16x32_bf16 v[32:35], v[176:179], v[216:219], v[32:35]
	v_mfma_f32_16x16x32_bf16 v[20:23], v[168:171], v[224:227], v[20:23]
	v_mfma_f32_16x16x32_bf16 v[16:19], v[176:179], v[224:227], v[16:19]
	v_mfma_f32_16x16x32_bf16 v[4:7], v[168:171], v[232:235], v[4:7]
	v_mfma_f32_16x16x32_bf16 v[0:3], v[176:179], v[232:235], v[0:3]
	v_mfma_f32_16x16x32_bf16 v[52:55], v[172:175], v[212:215], v[52:55]
	v_mfma_f32_16x16x32_bf16 v[48:51], v[204:207], v[212:215], v[48:51]
	v_mfma_f32_16x16x32_bf16 v[36:39], v[172:175], v[220:223], v[36:39]
	v_mfma_f32_16x16x32_bf16 v[32:35], v[204:207], v[220:223], v[32:35]
	v_mfma_f32_16x16x32_bf16 v[20:23], v[172:175], v[228:231], v[20:23]
	v_mfma_f32_16x16x32_bf16 v[16:19], v[204:207], v[228:231], v[16:19]
	v_mfma_f32_16x16x32_bf16 v[4:7], v[172:175], v[236:239], v[4:7]
	v_mfma_f32_16x16x32_bf16 v[0:3], v[204:207], v[236:239], v[0:3]
	s_barrier
	s_add_i32 s73, s73, 2
	s_add_u32 s58, s58, 0x100
	s_addc_u32 s59, s59, 0
	s_add_u32 s71, s71, 0x100
	s_addc_u32 s72, s72, 0
	s_cmp_gt_u32 s73, 5
	s_cbranch_scc0 .LBB0_1093
	s_setprio 0
	s_and_b64 vcc, exec, s[46:47]
	s_cbranch_vccz .LBB0_1096
	s_barrier

.LBB0_1116:
	s_ashr_i32 s49, s48, 31
	s_lshl_b64 s[4:5], s[48:49], 18
	s_add_u32 s50, s30, s4
	s_addc_u32 s51, s60, s5
	s_and_b64 s[4:5], s[38:39], exec
	s_cselect_b32 s33, s51, s55
	s_cselect_b32 s36, s50, s54
	s_ashr_i32 s47, s46, 31
	s_lshl_b64 s[4:5], s[46:47], 18
	s_add_u32 s52, s61, s4
	s_addc_u32 s53, s62, s5
	s_and_b64 s[4:5], s[38:39], exec
	s_cselect_b32 s47, s53, s59
	s_cselect_b32 s49, s52, s58
	s_add_u32 s54, s54, 0x20080
	s_addc_u32 s55, s55, 0
	s_add_u32 s71, s58, 0x100
	v_mov_b32_e32 v0, 0
	s_addc_u32 s72, s59, 0
	s_mov_b32 s73, -2
	v_mov_b32_e32 v1, v0
	v_mov_b32_e32 v2, v0
	v_mov_b32_e32 v3, v0
	v_mov_b32_e32 v4, v0
	v_mov_b32_e32 v5, v0
	v_mov_b32_e32 v6, v0
	v_mov_b32_e32 v7, v0
	v_mov_b32_e32 v16, v0
	v_mov_b32_e32 v17, v0
	v_mov_b32_e32 v18, v0
	v_mov_b32_e32 v19, v0
	v_mov_b32_e32 v20, v0
	v_mov_b32_e32 v21, v0
	v_mov_b32_e32 v22, v0
	v_mov_b32_e32 v23, v0
	v_mov_b32_e32 v32, v0
	v_mov_b32_e32 v33, v0
	v_mov_b32_e32 v34, v0
	v_mov_b32_e32 v35, v0
	v_mov_b32_e32 v36, v0
	v_mov_b32_e32 v37, v0
	v_mov_b32_e32 v38, v0
	v_mov_b32_e32 v39, v0
	v_mov_b32_e32 v48, v0
	v_mov_b32_e32 v49, v0
	v_mov_b32_e32 v50, v0
	v_mov_b32_e32 v51, v0
	v_mov_b32_e32 v52, v0
	v_mov_b32_e32 v53, v0
	v_mov_b32_e32 v54, v0
	v_mov_b32_e32 v55, v0
	v_mov_b32_e32 v8, v0
	v_mov_b32_e32 v9, v0
	v_mov_b32_e32 v10, v0
	v_mov_b32_e32 v11, v0
	v_mov_b32_e32 v12, v0
	v_mov_b32_e32 v13, v0
	v_mov_b32_e32 v14, v0
	v_mov_b32_e32 v15, v0
	v_mov_b32_e32 v24, v0
	v_mov_b32_e32 v25, v0
	v_mov_b32_e32 v26, v0
	v_mov_b32_e32 v27, v0
	v_mov_b32_e32 v28, v0
	v_mov_b32_e32 v29, v0
	v_mov_b32_e32 v30, v0
	v_mov_b32_e32 v31, v0
	v_mov_b32_e32 v40, v0
	v_mov_b32_e32 v41, v0
	v_mov_b32_e32 v42, v0
	v_mov_b32_e32 v43, v0
	v_mov_b32_e32 v44, v0
	v_mov_b32_e32 v45, v0
	v_mov_b32_e32 v46, v0
	v_mov_b32_e32 v47, v0
	v_mov_b32_e32 v56, v0
	v_mov_b32_e32 v57, v0
	v_mov_b32_e32 v58, v0
	v_mov_b32_e32 v59, v0
	v_mov_b32_e32 v60, v0
	v_mov_b32_e32 v61, v0
	v_mov_b32_e32 v62, v0
	v_mov_b32_e32 v63, v0
	v_mov_b32_e32 v64, v0
	v_mov_b32_e32 v65, v0
	v_mov_b32_e32 v66, v0
	v_mov_b32_e32 v67, v0
	v_mov_b32_e32 v68, v0
	v_mov_b32_e32 v69, v0
	v_mov_b32_e32 v70, v0
	v_mov_b32_e32 v71, v0
	v_mov_b32_e32 v80, v0
	v_mov_b32_e32 v81, v0
	v_mov_b32_e32 v82, v0
	v_mov_b32_e32 v83, v0
	v_mov_b32_e32 v84, v0
	v_mov_b32_e32 v85, v0
	v_mov_b32_e32 v86, v0
	v_mov_b32_e32 v87, v0
	v_mov_b32_e32 v96, v0
	v_mov_b32_e32 v97, v0
	v_mov_b32_e32 v98, v0
	v_mov_b32_e32 v99, v0
	v_mov_b32_e32 v100, v0
	v_mov_b32_e32 v101, v0
	v_mov_b32_e32 v102, v0
	v_mov_b32_e32 v103, v0
	v_mov_b32_e32 v112, v0
	v_mov_b32_e32 v113, v0
	v_mov_b32_e32 v114, v0
	v_mov_b32_e32 v115, v0
	v_mov_b32_e32 v116, v0
	v_mov_b32_e32 v117, v0
	v_mov_b32_e32 v118, v0
	v_mov_b32_e32 v119, v0
	v_mov_b32_e32 v72, v0
	v_mov_b32_e32 v73, v0
	v_mov_b32_e32 v74, v0
	v_mov_b32_e32 v75, v0
	v_mov_b32_e32 v76, v0
	v_mov_b32_e32 v77, v0
	v_mov_b32_e32 v78, v0
	v_mov_b32_e32 v79, v0
	v_mov_b32_e32 v88, v0
	v_mov_b32_e32 v89, v0
	v_mov_b32_e32 v90, v0
	v_mov_b32_e32 v91, v0
	v_mov_b32_e32 v92, v0
	v_mov_b32_e32 v93, v0
	v_mov_b32_e32 v94, v0
	v_mov_b32_e32 v95, v0
	v_mov_b32_e32 v104, v0
	v_mov_b32_e32 v105, v0
	v_mov_b32_e32 v106, v0
	v_mov_b32_e32 v107, v0
	v_mov_b32_e32 v108, v0
	v_mov_b32_e32 v109, v0
	v_mov_b32_e32 v110, v0
	v_mov_b32_e32 v111, v0
	v_mov_b32_e32 v120, v0
	v_mov_b32_e32 v121, v0
	v_mov_b32_e32 v122, v0
	v_mov_b32_e32 v123, v0
	v_mov_b32_e32 v124, v0
	v_mov_b32_e32 v125, v0
	v_mov_b32_e32 v126, v0
	v_mov_b32_e32 v127, v0
	v_readfirstlane_b32 s4, v182
	s_nop 3
	s_cmp_lt_u32 s4, 256
	s_cbranch_scc1 .Lkprio_1117
	s_setprio 1
.Lkprio_1117:
.LBB0_1117:
	s_add_u32 s4, s54, 0xfffe0080
	s_addc_u32 s5, s55, -1
	s_add_i32 s74, 0, 0x10000
	s_cmp_eq_u32 s73, 4
	s_cselect_b32 s59, s33, s5
	s_cselect_b32 s58, s36, s4
	s_cselect_b32 s35, s47, s72
	s_cselect_b32 s34, s49, s71
	s_add_i32 s75, 0, 0x14000
	v_add_u32_e32 v164, s74, v143
	v_add_u32_e32 v180, s75, v143
	ds_read_b128 v[138:141], v164
	ds_read_b128 v[156:159], v164 offset:1024
	ds_read_b128 v[160:163], v164 offset:2048
	ds_read_b128 v[164:167], v164 offset:3072
	ds_read_b128 v[168:171], v180
	ds_read_b128 v[172:175], v180 offset:1024
	ds_read_b128 v[176:179], v180 offset:2048
	ds_read_b128 v[204:207], v180 offset:3072
	v_lshl_add_u64 v[180:181], s[54:55], 0, v[134:135]
	s_add_i32 m0, s64, 0xc000
	ds_read_b128 v[208:211], v155
	ds_read_b128 v[212:215], v155 offset:1024
	ds_read_b128 v[216:219], v155 offset:2048
	ds_read_b128 v[220:223], v155 offset:3072
	ds_read_b128 v[224:227], v155 offset:4096
	ds_read_b128 v[228:231], v155 offset:5120
	ds_read_b128 v[232:235], v155 offset:6144
	ds_read_b128 v[236:239], v155 offset:7168
	global_load_lds_dwordx4 v[180:181], off
	v_lshl_add_u64 v[180:181], s[54:55], 0, v[136:137]
	s_add_i32 m0, s64, 0xe000
	s_nop 0
	global_load_lds_dwordx4 v[180:181], off
	s_waitcnt vmcnt(8)
	s_waitcnt lgkmcnt(0)
	s_barrier
	s_waitcnt lgkmcnt(0)
	v_mfma_f32_16x16x32_bf16 v[124:127], v[138:141], v[208:211], v[124:127]
	v_mfma_f32_16x16x32_bf16 v[120:123], v[160:163], v[208:211], v[120:123]
	v_mfma_f32_16x16x32_bf16 v[108:111], v[138:141], v[216:219], v[108:111]
	v_mfma_f32_16x16x32_bf16 v[104:107], v[160:163], v[216:219], v[104:107]
	v_mfma_f32_16x16x32_bf16 v[92:95], v[138:141], v[224:227], v[92:95]
	v_mfma_f32_16x16x32_bf16 v[88:91], v[160:163], v[224:227], v[88:91]
	v_mfma_f32_16x16x32_bf16 v[76:79], v[138:141], v[232:235], v[76:79]
	v_mfma_f32_16x16x32_bf16 v[72:75], v[160:163], v[232:235], v[72:75]
	v_mfma_f32_16x16x32_bf16 v[124:127], v[156:159], v[212:215], v[124:127]
	v_mfma_f32_16x16x32_bf16 v[120:123], v[164:167], v[212:215], v[120:123]
	v_mfma_f32_16x16x32_bf16 v[108:111], v[156:159], v[220:223], v[108:111]
	v_mfma_f32_16x16x32_bf16 v[104:107], v[164:167], v[220:223], v[104:107]
	v_mfma_f32_16x16x32_bf16 v[92:95], v[156:159], v[228:231], v[92:95]
	v_mfma_f32_16x16x32_bf16 v[88:91], v[164:167], v[228:231], v[88:91]
	v_mfma_f32_16x16x32_bf16 v[76:79], v[156:159], v[236:239], v[76:79]
	v_mfma_f32_16x16x32_bf16 v[72:75], v[164:167], v[236:239], v[72:75]
	v_mfma_f32_16x16x32_bf16 v[116:119], v[168:171], v[208:211], v[116:119]
	v_mfma_f32_16x16x32_bf16 v[112:115], v[176:179], v[208:211], v[112:115]
	v_mfma_f32_16x16x32_bf16 v[100:103], v[168:171], v[216:219], v[100:103]
	v_mfma_f32_16x16x32_bf16 v[96:99], v[176:179], v[216:219], v[96:99]
	v_mfma_f32_16x16x32_bf16 v[84:87], v[168:171], v[224:227], v[84:87]
	v_mfma_f32_16x16x32_bf16 v[80:83], v[176:179], v[224:227], v[80:83]
	v_mfma_f32_16x16x32_bf16 v[68:71], v[168:171], v[232:235], v[68:71]
	v_mfma_f32_16x16x32_bf16 v[64:67], v[176:179], v[232:235], v[64:67]
	v_mfma_f32_16x16x32_bf16 v[116:119], v[172:175], v[212:215], v[116:119]
	v_mfma_f32_16x16x32_bf16 v[112:115], v[204:207], v[212:215], v[112:115]
	v_mfma_f32_16x16x32_bf16 v[100:103], v[172:175], v[220:223], v[100:103]
	v_mfma_f32_16x16x32_bf16 v[96:99], v[204:207], v[220:223], v[96:99]
	v_mfma_f32_16x16x32_bf16 v[84:87], v[172:175], v[228:231], v[84:87]
	v_mfma_f32_16x16x32_bf16 v[80:83], v[204:207], v[228:231], v[80:83]
	v_mfma_f32_16x16x32_bf16 v[68:71], v[172:175], v[236:239], v[68:71]
	v_mfma_f32_16x16x32_bf16 v[64:67], v[204:207], v[236:239], v[64:67]
	s_barrier
	s_add_i32 s4, s74, s63
	v_lshl_add_u64 v[180:181], s[34:35], 0, v[144:145]
	s_mov_b32 m0, s4
	ds_read_b128 v[208:211], v155 offset:16384
	ds_read_b128 v[212:215], v155 offset:17408
	ds_read_b128 v[216:219], v155 offset:18432
	ds_read_b128 v[220:223], v155 offset:19456
	ds_read_b128 v[224:227], v155 offset:20480
	ds_read_b128 v[228:231], v155 offset:21504
	ds_read_b128 v[232:235], v155 offset:22528
	ds_read_b128 v[236:239], v155 offset:23552
	global_load_lds_dwordx4 v[180:181], off
	s_add_i32 m0, s4, 0x2000
	s_add_u32 s4, s34, 0x20000
	v_lshl_add_u64 v[202:203], s[34:35], 0, v[132:133]
	s_addc_u32 s5, s35, 0
	s_add_i32 s74, s75, s63
	global_load_lds_dwordx4 v[202:203], off
	v_lshl_add_u64 v[240:241], s[4:5], 0, v[144:145]
	s_mov_b32 m0, s74
	v_lshl_add_u64 v[242:243], s[58:59], 0, v[130:131]
	global_load_lds_dwordx4 v[240:241], off
	v_lshl_add_u64 v[240:241], s[4:5], 0, v[132:133]
	s_add_i32 m0, s74, 0x2000
	s_nop 0
	global_load_lds_dwordx4 v[240:241], off
	v_lshl_add_u64 v[240:241], s[58:59], 0, v[128:129]
	s_mov_b32 m0, s64
	s_nop 0
	global_load_lds_dwordx4 v[240:241], off
	s_mov_b32 m0, s65
	s_nop 0
	global_load_lds_dwordx4 v[242:243], off
	s_waitcnt vmcnt(8)
	s_waitcnt lgkmcnt(0)
	s_barrier
	s_waitcnt lgkmcnt(0)
	v_mfma_f32_16x16x32_bf16 v[60:63], v[138:141], v[208:211], v[60:63]
	v_mfma_f32_16x16x32_bf16 v[56:59], v[160:163], v[208:211], v[56:59]
	v_mfma_f32_16x16x32_bf16 v[44:47], v[138:141], v[216:219], v[44:47]
	v_mfma_f32_16x16x32_bf16 v[40:43], v[160:163], v[216:219], v[40:43]
	v_mfma_f32_16x16x32_bf16 v[28:31], v[138:141], v[224:227], v[28:31]
	v_mfma_f32_16x16x32_bf16 v[24:27], v[160:163], v[224:227], v[24:27]
	v_mfma_f32_16x16x32_bf16 v[12:15], v[138:141], v[232:235], v[12:15]
	v_mfma_f32_16x16x32_bf16 v[8:11], v[160:163], v[232:235], v[8:11]
	v_mfma_f32_16x16x32_bf16 v[60:63], v[156:159], v[212:215], v[60:63]
	v_mfma_f32_16x16x32_bf16 v[56:59], v[164:167], v[212:215], v[56:59]
	v_mfma_f32_16x16x32_bf16 v[44:47], v[156:159], v[220:223], v[44:47]
	v_mfma_f32_16x16x32_bf16 v[40:43], v[164:167], v[220:223], v[40:43]
	v_mfma_f32_16x16x32_bf16 v[28:31], v[156:159], v[228:231], v[28:31]
	v_mfma_f32_16x16x32_bf16 v[24:27], v[164:167], v[228:231], v[24:27]
	v_mfma_f32_16x16x32_bf16 v[12:15], v[156:159], v[236:239], v[12:15]
	v_mfma_f32_16x16x32_bf16 v[8:11], v[164:167], v[236:239], v[8:11]
	v_mfma_f32_16x16x32_bf16 v[52:55], v[168:171], v[208:211], v[52:55]
	v_mfma_f32_16x16x32_bf16 v[48:51], v[176:179], v[208:211], v[48:51]
	v_mfma_f32_16x16x32_bf16 v[36:39], v[168:171], v[216:219], v[36:39]
	v_mfma_f32_16x16x32_bf16 v[32:35], v[176:179], v[216:219], v[32:35]
	v_mfma_f32_16x16x32_bf16 v[20:23], v[168:171], v[224:227], v[20:23]
	v_mfma_f32_16x16x32_bf16 v[16:19], v[176:179], v[224:227], v[16:19]
	v_mfma_f32_16x16x32_bf16 v[4:7], v[168:171], v[232:235], v[4:7]
	v_mfma_f32_16x16x32_bf16 v[0:3], v[176:179], v[232:235], v[0:3]
	v_mfma_f32_16x16x32_bf16 v[52:55], v[172:175], v[212:215], v[52:55]
	v_mfma_f32_16x16x32_bf16 v[48:51], v[204:207], v[212:215], v[48:51]
	v_mfma_f32_16x16x32_bf16 v[36:39], v[172:175], v[220:223], v[36:39]
	v_mfma_f32_16x16x32_bf16 v[32:35], v[204:207], v[220:223], v[32:35]
	v_mfma_f32_16x16x32_bf16 v[20:23], v[172:175], v[228:231], v[20:23]
	v_mfma_f32_16x16x32_bf16 v[16:19], v[204:207], v[228:231], v[16:19]
	v_mfma_f32_16x16x32_bf16 v[4:7], v[172:175], v[236:239], v[4:7]
	v_mfma_f32_16x16x32_bf16 v[0:3], v[204:207], v[236:239], v[0:3]
	s_barrier
	s_add_i32 s74, 0, 0x18000
	s_add_i32 s75, 0, 0x1c000
	v_add_u32_e32 v164, s74, v143
	v_add_u32_e32 v204, s75, v143
	ds_read_b128 v[138:141], v164
	ds_read_b128 v[156:159], v164 offset:1024
	ds_read_b128 v[160:163], v164 offset:2048
	ds_read_b128 v[164:167], v164 offset:3072
	ds_read_b128 v[168:171], v204
	ds_read_b128 v[172:175], v204 offset:1024
	ds_read_b128 v[176:179], v204 offset:2048
	ds_read_b128 v[204:207], v204 offset:3072
	s_add_u32 s4, s58, 0x20000
	s_addc_u32 s5, s59, 0
	s_mov_b32 m0, s66
	v_lshl_add_u64 v[244:245], s[4:5], 0, v[128:129]
	ds_read_b128 v[208:211], v155 offset:32768
	ds_read_b128 v[212:215], v155 offset:33792
	ds_read_b128 v[216:219], v155 offset:34816
	ds_read_b128 v[220:223], v155 offset:35840
	ds_read_b128 v[224:227], v155 offset:36864
	ds_read_b128 v[228:231], v155 offset:37888
	ds_read_b128 v[232:235], v155 offset:38912
	ds_read_b128 v[236:239], v155 offset:39936
	global_load_lds_dwordx4 v[244:245], off
	v_lshl_add_u64 v[244:245], s[4:5], 0, v[130:131]
	s_mov_b32 m0, s67
	s_nop 0
	global_load_lds_dwordx4 v[244:245], off
	s_waitcnt vmcnt(8)
	s_waitcnt lgkmcnt(0)
	s_barrier
	s_waitcnt lgkmcnt(0)
	v_mfma_f32_16x16x32_bf16 v[124:127], v[138:141], v[208:211], v[124:127]
	v_mfma_f32_16x16x32_bf16 v[120:123], v[160:163], v[208:211], v[120:123]
	v_mfma_f32_16x16x32_bf16 v[108:111], v[138:141], v[216:219], v[108:111]
	v_mfma_f32_16x16x32_bf16 v[104:107], v[160:163], v[216:219], v[104:107]
	v_mfma_f32_16x16x32_bf16 v[92:95], v[138:141], v[224:227], v[92:95]
	v_mfma_f32_16x16x32_bf16 v[88:91], v[160:163], v[224:227], v[88:91]
	v_mfma_f32_16x16x32_bf16 v[76:79], v[138:141], v[232:235], v[76:79]
	v_mfma_f32_16x16x32_bf16 v[72:75], v[160:163], v[232:235], v[72:75]
	v_mfma_f32_16x16x32_bf16 v[124:127], v[156:159], v[212:215], v[124:127]
	v_mfma_f32_16x16x32_bf16 v[120:123], v[164:167], v[212:215], v[120:123]
	v_mfma_f32_16x16x32_bf16 v[108:111], v[156:159], v[220:223], v[108:111]
	v_mfma_f32_16x16x32_bf16 v[104:107], v[164:167], v[220:223], v[104:107]
	v_mfma_f32_16x16x32_bf16 v[92:95], v[156:159], v[228:231], v[92:95]
	v_mfma_f32_16x16x32_bf16 v[88:91], v[164:167], v[228:231], v[88:91]
	v_mfma_f32_16x16x32_bf16 v[76:79], v[156:159], v[236:239], v[76:79]
	v_mfma_f32_16x16x32_bf16 v[72:75], v[164:167], v[236:239], v[72:75]
	v_mfma_f32_16x16x32_bf16 v[116:119], v[168:171], v[208:211], v[116:119]
	v_mfma_f32_16x16x32_bf16 v[112:115], v[176:179], v[208:211], v[112:115]
	v_mfma_f32_16x16x32_bf16 v[100:103], v[168:171], v[216:219], v[100:103]
	v_mfma_f32_16x16x32_bf16 v[96:99], v[176:179], v[216:219], v[96:99]
	v_mfma_f32_16x16x32_bf16 v[84:87], v[168:171], v[224:227], v[84:87]
	v_mfma_f32_16x16x32_bf16 v[80:83], v[176:179], v[224:227], v[80:83]
	v_mfma_f32_16x16x32_bf16 v[68:71], v[168:171], v[232:235], v[68:71]
	v_mfma_f32_16x16x32_bf16 v[64:67], v[176:179], v[232:235], v[64:67]
	v_mfma_f32_16x16x32_bf16 v[116:119], v[172:175], v[212:215], v[116:119]
	v_mfma_f32_16x16x32_bf16 v[112:115], v[204:207], v[212:215], v[112:115]
	v_mfma_f32_16x16x32_bf16 v[100:103], v[172:175], v[220:223], v[100:103]
	v_mfma_f32_16x16x32_bf16 v[96:99], v[204:207], v[220:223], v[96:99]
	v_mfma_f32_16x16x32_bf16 v[84:87], v[172:175], v[228:231], v[84:87]
	v_mfma_f32_16x16x32_bf16 v[80:83], v[204:207], v[228:231], v[80:83]
	v_mfma_f32_16x16x32_bf16 v[68:71], v[172:175], v[236:239], v[68:71]
	v_mfma_f32_16x16x32_bf16 v[64:67], v[204:207], v[236:239], v[64:67]
	s_barrier
	s_add_i32 s4, s74, s63
	v_lshl_add_u64 v[180:181], v[180:181], 0, s[26:27]
	s_mov_b32 m0, s4
	ds_read_b128 v[208:211], v155 offset:49152
	ds_read_b128 v[212:215], v155 offset:50176
	ds_read_b128 v[216:219], v155 offset:51200
	ds_read_b128 v[220:223], v155 offset:52224
	ds_read_b128 v[224:227], v155 offset:53248
	ds_read_b128 v[228:231], v155 offset:54272
	ds_read_b128 v[232:235], v155 offset:55296
	ds_read_b128 v[236:239], v155 offset:56320
	global_load_lds_dwordx4 v[180:181], off
	s_add_i32 m0, s4, 0x2000
	s_add_u32 s4, s34, 0x20080
	v_lshl_add_u64 v[180:181], v[202:203], 0, s[26:27]
	s_addc_u32 s5, s35, 0
	s_add_i32 s34, s75, s63
	global_load_lds_dwordx4 v[180:181], off
	v_lshl_add_u64 v[180:181], s[4:5], 0, v[144:145]
	s_mov_b32 m0, s34
	s_nop 0
	global_load_lds_dwordx4 v[180:181], off
	v_lshl_add_u64 v[180:181], s[4:5], 0, v[132:133]
	s_add_i32 m0, s34, 0x2000
	s_nop 0
	global_load_lds_dwordx4 v[180:181], off
	v_lshl_add_u64 v[180:181], v[240:241], 0, s[26:27]
	s_mov_b32 m0, s68
	s_nop 0
	global_load_lds_dwordx4 v[180:181], off
	v_lshl_add_u64 v[180:181], v[242:243], 0, s[26:27]
	s_mov_b32 m0, s69
	s_nop 0
	global_load_lds_dwordx4 v[180:181], off
	s_waitcnt vmcnt(8)
	s_waitcnt lgkmcnt(0)
	s_barrier
	s_waitcnt lgkmcnt(0)
	v_mfma_f32_16x16x32_bf16 v[60:63], v[138:141], v[208:211], v[60:63]
	v_mfma_f32_16x16x32_bf16 v[56:59], v[160:163], v[208:211], v[56:59]
	v_mfma_f32_16x16x32_bf16 v[44:47], v[138:141], v[216:219], v[44:47]
	v_mfma_f32_16x16x32_bf16 v[40:43], v[160:163], v[216:219], v[40:43]
	v_mfma_f32_16x16x32_bf16 v[28:31], v[138:141], v[224:227], v[28:31]
	v_mfma_f32_16x16x32_bf16 v[24:27], v[160:163], v[224:227], v[24:27]
	v_mfma_f32_16x16x32_bf16 v[12:15], v[138:141], v[232:235], v[12:15]
	v_mfma_f32_16x16x32_bf16 v[8:11], v[160:163], v[232:235], v[8:11]
	v_mfma_f32_16x16x32_bf16 v[60:63], v[156:159], v[212:215], v[60:63]
	v_mfma_f32_16x16x32_bf16 v[56:59], v[164:167], v[212:215], v[56:59]
	v_mfma_f32_16x16x32_bf16 v[44:47], v[156:159], v[220:223], v[44:47]
	v_mfma_f32_16x16x32_bf16 v[40:43], v[164:167], v[220:223], v[40:43]
	v_mfma_f32_16x16x32_bf16 v[28:31], v[156:159], v[228:231], v[28:31]
	v_mfma_f32_16x16x32_bf16 v[24:27], v[164:167], v[228:231], v[24:27]
	v_mfma_f32_16x16x32_bf16 v[12:15], v[156:159], v[236:239], v[12:15]
	v_mfma_f32_16x16x32_bf16 v[8:11], v[164:167], v[236:239], v[8:11]
	v_mfma_f32_16x16x32_bf16 v[52:55], v[168:171], v[208:211], v[52:55]
	v_mfma_f32_16x16x32_bf16 v[48:51], v[176:179], v[208:211], v[48:51]
	v_mfma_f32_16x16x32_bf16 v[36:39], v[168:171], v[216:219], v[36:39]
	v_mfma_f32_16x16x32_bf16 v[32:35], v[176:179], v[216:219], v[32:35]
	v_mfma_f32_16x16x32_bf16 v[20:23], v[168:171], v[224:227], v[20:23]
	v_mfma_f32_16x16x32_bf16 v[16:19], v[176:179], v[224:227], v[16:19]
	v_mfma_f32_16x16x32_bf16 v[4:7], v[168:171], v[232:235], v[4:7]
	v_mfma_f32_16x16x32_bf16 v[0:3], v[176:179], v[232:235], v[0:3]
	v_mfma_f32_16x16x32_bf16 v[52:55], v[172:175], v[212:215], v[52:55]
	v_mfma_f32_16x16x32_bf16 v[48:51], v[204:207], v[212:215], v[48:51]
	v_mfma_f32_16x16x32_bf16 v[36:39], v[172:175], v[220:223], v[36:39]
	v_mfma_f32_16x16x32_bf16 v[32:35], v[204:207], v[220:223], v[32:35]
	v_mfma_f32_16x16x32_bf16 v[20:23], v[172:175], v[228:231], v[20:23]
	v_mfma_f32_16x16x32_bf16 v[16:19], v[204:207], v[228:231], v[16:19]
	v_mfma_f32_16x16x32_bf16 v[4:7], v[172:175], v[236:239], v[4:7]
	v_mfma_f32_16x16x32_bf16 v[0:3], v[204:207], v[236:239], v[0:3]
	s_barrier
	s_add_i32 s73, s73, 2
	s_add_u32 s54, s54, 0x100
	s_addc_u32 s55, s55, 0
	s_add_u32 s71, s71, 0x100
	s_addc_u32 s72, s72, 0
	s_cmp_gt_u32 s73, 5
	s_cbranch_scc0 .LBB0_1117
	s_setprio 0
	s_and_b64 vcc, exec, s[44:45]
	s_cbranch_vccz .LBB0_1120
	s_barrier

.LBB0_1206:
	s_ashr_i32 s53, s52, 31
	s_lshl_b64 s[4:5], s[52:53], 19
	s_add_u32 s3, s36, s4
	s_addc_u32 s28, s68, s5
	s_and_b64 s[4:5], s[42:43], exec
	s_cselect_b32 s55, s28, s61
	s_cselect_b32 s54, s3, s60
	s_ashr_i32 s51, s50, 31
	s_lshl_b64 s[4:5], s[50:51], 19
	s_add_u32 s3, s66, s4
	s_addc_u32 s28, s67, s5
	s_and_b64 s[4:5], s[42:43], exec
	s_cselect_b32 s59, s28, s63
	s_cselect_b32 s58, s3, s62
	s_add_u32 s3, s62, 0x100
	v_mov_b32_e32 v0, 0
	s_addc_u32 s28, s63, 0
	s_mov_b32 s29, -2
	s_waitcnt lgkmcnt(0)
	v_mov_b32_e32 v1, v0
	v_mov_b32_e32 v2, v0
	v_mov_b32_e32 v3, v0
	v_mov_b32_e32 v4, v0
	v_mov_b32_e32 v5, v0
	v_mov_b32_e32 v6, v0
	v_mov_b32_e32 v7, v0
	v_mov_b32_e32 v16, v0
	v_mov_b32_e32 v17, v0
	v_mov_b32_e32 v18, v0
	v_mov_b32_e32 v19, v0
	v_mov_b32_e32 v20, v0
	v_mov_b32_e32 v21, v0
	v_mov_b32_e32 v22, v0
	v_mov_b32_e32 v23, v0
	v_mov_b32_e32 v32, v0
	v_mov_b32_e32 v33, v0
	v_mov_b32_e32 v34, v0
	v_mov_b32_e32 v35, v0
	v_mov_b32_e32 v36, v0
	v_mov_b32_e32 v37, v0
	v_mov_b32_e32 v38, v0
	v_mov_b32_e32 v39, v0
	v_mov_b32_e32 v48, v0
	v_mov_b32_e32 v49, v0
	v_mov_b32_e32 v50, v0
	v_mov_b32_e32 v51, v0
	v_mov_b32_e32 v52, v0
	v_mov_b32_e32 v53, v0
	v_mov_b32_e32 v54, v0
	v_mov_b32_e32 v55, v0
	v_mov_b32_e32 v8, v0
	v_mov_b32_e32 v9, v0
	v_mov_b32_e32 v10, v0
	v_mov_b32_e32 v11, v0
	v_mov_b32_e32 v12, v0
	v_mov_b32_e32 v13, v0
	v_mov_b32_e32 v14, v0
	v_mov_b32_e32 v15, v0
	v_mov_b32_e32 v24, v0
	v_mov_b32_e32 v25, v0
	v_mov_b32_e32 v26, v0
	v_mov_b32_e32 v27, v0
	v_mov_b32_e32 v28, v0
	v_mov_b32_e32 v29, v0
	v_mov_b32_e32 v30, v0
	v_mov_b32_e32 v31, v0
	v_mov_b32_e32 v40, v0
	v_mov_b32_e32 v41, v0
	v_mov_b32_e32 v42, v0
	v_mov_b32_e32 v43, v0
	v_mov_b32_e32 v44, v0
	v_mov_b32_e32 v45, v0
	v_mov_b32_e32 v46, v0
	v_mov_b32_e32 v47, v0
	v_mov_b32_e32 v56, v0
	v_mov_b32_e32 v57, v0
	v_mov_b32_e32 v58, v0
	v_mov_b32_e32 v59, v0
	v_mov_b32_e32 v60, v0
	v_mov_b32_e32 v61, v0
	v_mov_b32_e32 v62, v0
	v_mov_b32_e32 v63, v0
	v_mov_b32_e32 v64, v0
	v_mov_b32_e32 v65, v0
	v_mov_b32_e32 v66, v0
	v_mov_b32_e32 v67, v0
	v_mov_b32_e32 v68, v0
	v_mov_b32_e32 v69, v0
	v_mov_b32_e32 v70, v0
	v_mov_b32_e32 v71, v0
	v_mov_b32_e32 v80, v0
	v_mov_b32_e32 v81, v0
	v_mov_b32_e32 v82, v0
	v_mov_b32_e32 v83, v0
	v_mov_b32_e32 v84, v0
	v_mov_b32_e32 v85, v0
	v_mov_b32_e32 v86, v0
	v_mov_b32_e32 v87, v0
	v_mov_b32_e32 v96, v0
	v_mov_b32_e32 v97, v0
	v_mov_b32_e32 v98, v0
	v_mov_b32_e32 v99, v0
	v_mov_b32_e32 v100, v0
	v_mov_b32_e32 v101, v0
	v_mov_b32_e32 v102, v0
	v_mov_b32_e32 v103, v0
	v_mov_b32_e32 v112, v0
	v_mov_b32_e32 v113, v0
	v_mov_b32_e32 v114, v0
	v_mov_b32_e32 v115, v0
	v_mov_b32_e32 v116, v0
	v_mov_b32_e32 v117, v0
	v_mov_b32_e32 v118, v0
	v_mov_b32_e32 v119, v0
	v_mov_b32_e32 v72, v0
	v_mov_b32_e32 v73, v0
	v_mov_b32_e32 v74, v0
	v_mov_b32_e32 v75, v0
	v_mov_b32_e32 v76, v0
	v_mov_b32_e32 v77, v0
	v_mov_b32_e32 v78, v0
	v_mov_b32_e32 v79, v0
	v_mov_b32_e32 v88, v0
	v_mov_b32_e32 v89, v0
	v_mov_b32_e32 v90, v0
	v_mov_b32_e32 v91, v0
	v_mov_b32_e32 v92, v0
	v_mov_b32_e32 v93, v0
	v_mov_b32_e32 v94, v0
	v_mov_b32_e32 v95, v0
	v_mov_b32_e32 v104, v0
	v_mov_b32_e32 v105, v0
	v_mov_b32_e32 v106, v0
	v_mov_b32_e32 v107, v0
	v_mov_b32_e32 v108, v0
	v_mov_b32_e32 v109, v0
	v_mov_b32_e32 v110, v0
	v_mov_b32_e32 v111, v0
	v_mov_b32_e32 v120, v0
	v_mov_b32_e32 v121, v0
	v_mov_b32_e32 v122, v0
	v_mov_b32_e32 v123, v0
	v_mov_b32_e32 v124, v0
	v_mov_b32_e32 v125, v0
	v_mov_b32_e32 v126, v0
	v_mov_b32_e32 v127, v0
	v_readfirstlane_b32 s4, v182
	s_nop 3
	s_cmp_lt_u32 s4, 256
	s_cbranch_scc1 .Lkprio_1207
	s_setprio 1
.Lkprio_1207:
.LBB0_1207:
	s_add_u32 s62, s60, 0x100
	s_addc_u32 s63, s61, 0
	s_add_i32 s4, 0, 0x10000
	s_cmp_eq_u32 s29, 12
	s_cselect_b32 s65, s55, s63
	s_cselect_b32 s64, s54, s62
	v_add_u32_e32 v142, s4, v160
	s_cselect_b32 s35, s59, s28
	s_cselect_b32 s34, s58, s3
	s_add_i32 s45, 0, 0x14000
	ds_read_b128 v[138:141], v142
	ds_read_b128 v[154:157], v142 offset:1024
	ds_read_b128 v[172:175], v142 offset:2048
	ds_read_b128 v[176:179], v142 offset:3072
	v_add_u32_e32 v142, s45, v160
	ds_read_b128 v[204:207], v142
	ds_read_b128 v[208:211], v142 offset:1024
	ds_read_b128 v[212:215], v142 offset:2048
	ds_read_b128 v[216:219], v142 offset:3072
	v_lshl_add_u64 v[142:143], s[60:61], 0, v[134:135]
	s_add_i32 m0, s69, 0xc000
	ds_read_b128 v[220:223], v170
	ds_read_b128 v[224:227], v170 offset:1024
	ds_read_b128 v[228:231], v170 offset:2048
	ds_read_b128 v[232:235], v170 offset:3072
	ds_read_b128 v[236:239], v170 offset:4096
	ds_read_b128 v[240:243], v170 offset:5120
	ds_read_b128 v[244:247], v170 offset:6144
	ds_read_b128 v[248:251], v170 offset:7168
	global_load_lds_dwordx4 v[142:143], off
	v_lshl_add_u64 v[142:143], s[60:61], 0, v[136:137]
	s_add_i32 m0, s69, 0xe000
	s_nop 0
	global_load_lds_dwordx4 v[142:143], off
	s_waitcnt vmcnt(8)
	s_waitcnt lgkmcnt(0)
	s_barrier
	s_waitcnt lgkmcnt(0)
	v_mfma_f32_16x16x32_bf16 v[124:127], v[138:141], v[220:223], v[124:127]
	v_mfma_f32_16x16x32_bf16 v[120:123], v[172:175], v[220:223], v[120:123]
	v_mfma_f32_16x16x32_bf16 v[108:111], v[138:141], v[228:231], v[108:111]
	v_mfma_f32_16x16x32_bf16 v[104:107], v[172:175], v[228:231], v[104:107]
	v_mfma_f32_16x16x32_bf16 v[92:95], v[138:141], v[236:239], v[92:95]
	v_mfma_f32_16x16x32_bf16 v[88:91], v[172:175], v[236:239], v[88:91]
	v_mfma_f32_16x16x32_bf16 v[76:79], v[138:141], v[244:247], v[76:79]
	v_mfma_f32_16x16x32_bf16 v[72:75], v[172:175], v[244:247], v[72:75]
	v_mfma_f32_16x16x32_bf16 v[124:127], v[154:157], v[224:227], v[124:127]
	v_mfma_f32_16x16x32_bf16 v[120:123], v[176:179], v[224:227], v[120:123]
	v_mfma_f32_16x16x32_bf16 v[108:111], v[154:157], v[232:235], v[108:111]
	v_mfma_f32_16x16x32_bf16 v[104:107], v[176:179], v[232:235], v[104:107]
	v_mfma_f32_16x16x32_bf16 v[92:95], v[154:157], v[240:243], v[92:95]
	v_mfma_f32_16x16x32_bf16 v[88:91], v[176:179], v[240:243], v[88:91]
	v_mfma_f32_16x16x32_bf16 v[76:79], v[154:157], v[248:251], v[76:79]
	v_mfma_f32_16x16x32_bf16 v[72:75], v[176:179], v[248:251], v[72:75]
	v_mfma_f32_16x16x32_bf16 v[116:119], v[204:207], v[220:223], v[116:119]
	v_mfma_f32_16x16x32_bf16 v[112:115], v[212:215], v[220:223], v[112:115]
	v_mfma_f32_16x16x32_bf16 v[100:103], v[204:207], v[228:231], v[100:103]
	v_mfma_f32_16x16x32_bf16 v[96:99], v[212:215], v[228:231], v[96:99]
	v_mfma_f32_16x16x32_bf16 v[84:87], v[204:207], v[236:239], v[84:87]
	v_mfma_f32_16x16x32_bf16 v[80:83], v[212:215], v[236:239], v[80:83]
	v_mfma_f32_16x16x32_bf16 v[68:71], v[204:207], v[244:247], v[68:71]
	v_mfma_f32_16x16x32_bf16 v[64:67], v[212:215], v[244:247], v[64:67]
	v_mfma_f32_16x16x32_bf16 v[116:119], v[208:211], v[224:227], v[116:119]
	v_mfma_f32_16x16x32_bf16 v[112:115], v[216:219], v[224:227], v[112:115]
	v_mfma_f32_16x16x32_bf16 v[100:103], v[208:211], v[232:235], v[100:103]
	v_mfma_f32_16x16x32_bf16 v[96:99], v[216:219], v[232:235], v[96:99]
	v_mfma_f32_16x16x32_bf16 v[84:87], v[208:211], v[240:243], v[84:87]
	v_mfma_f32_16x16x32_bf16 v[80:83], v[216:219], v[240:243], v[80:83]
	v_mfma_f32_16x16x32_bf16 v[68:71], v[208:211], v[248:251], v[68:71]
	v_mfma_f32_16x16x32_bf16 v[64:67], v[216:219], v[248:251], v[64:67]
	s_barrier
	s_add_i32 s4, s4, s33
	v_lshl_add_u64 v[142:143], s[34:35], 0, v[128:129]
	s_mov_b32 m0, s4
	ds_read_b128 v[220:223], v170 offset:16384
	ds_read_b128 v[224:227], v170 offset:17408
	ds_read_b128 v[228:231], v170 offset:18432
	ds_read_b128 v[232:235], v170 offset:19456
	ds_read_b128 v[236:239], v170 offset:20480
	ds_read_b128 v[240:243], v170 offset:21504
	ds_read_b128 v[244:247], v170 offset:22528
	ds_read_b128 v[248:251], v170 offset:23552
	global_load_lds_dwordx4 v[142:143], off
	s_add_i32 m0, s4, 0x2000
	s_add_u32 s4, s34, 0x40000
	v_lshl_add_u64 v[158:159], s[34:35], 0, v[130:131]
	s_addc_u32 s5, s35, 0
	s_add_i32 s45, s45, s33
	global_load_lds_dwordx4 v[158:159], off
	v_lshl_add_u64 v[180:181], s[4:5], 0, v[128:129]
	s_mov_b32 m0, s45
	v_lshl_add_u64 v[202:203], s[64:65], 0, v[130:131]
	global_load_lds_dwordx4 v[180:181], off
	v_lshl_add_u64 v[180:181], s[4:5], 0, v[130:131]
	s_add_i32 m0, s45, 0x2000
	s_nop 0
	global_load_lds_dwordx4 v[180:181], off
	v_lshl_add_u64 v[180:181], s[64:65], 0, v[128:129]
	s_mov_b32 m0, s69
	s_nop 0
	global_load_lds_dwordx4 v[180:181], off
	s_mov_b32 m0, s70
	s_nop 0
	global_load_lds_dwordx4 v[202:203], off
	s_waitcnt vmcnt(8)
	s_waitcnt lgkmcnt(0)
	s_barrier
	s_waitcnt lgkmcnt(0)
	v_mfma_f32_16x16x32_bf16 v[60:63], v[138:141], v[220:223], v[60:63]
	v_mfma_f32_16x16x32_bf16 v[56:59], v[172:175], v[220:223], v[56:59]
	v_mfma_f32_16x16x32_bf16 v[44:47], v[138:141], v[228:231], v[44:47]
	v_mfma_f32_16x16x32_bf16 v[40:43], v[172:175], v[228:231], v[40:43]
	v_mfma_f32_16x16x32_bf16 v[28:31], v[138:141], v[236:239], v[28:31]
	v_mfma_f32_16x16x32_bf16 v[24:27], v[172:175], v[236:239], v[24:27]
	v_mfma_f32_16x16x32_bf16 v[12:15], v[138:141], v[244:247], v[12:15]
	v_mfma_f32_16x16x32_bf16 v[8:11], v[172:175], v[244:247], v[8:11]
	v_mfma_f32_16x16x32_bf16 v[60:63], v[154:157], v[224:227], v[60:63]
	v_mfma_f32_16x16x32_bf16 v[56:59], v[176:179], v[224:227], v[56:59]
	v_mfma_f32_16x16x32_bf16 v[44:47], v[154:157], v[232:235], v[44:47]
	v_mfma_f32_16x16x32_bf16 v[40:43], v[176:179], v[232:235], v[40:43]
	v_mfma_f32_16x16x32_bf16 v[28:31], v[154:157], v[240:243], v[28:31]
	v_mfma_f32_16x16x32_bf16 v[24:27], v[176:179], v[240:243], v[24:27]
	v_mfma_f32_16x16x32_bf16 v[12:15], v[154:157], v[248:251], v[12:15]
	v_mfma_f32_16x16x32_bf16 v[8:11], v[176:179], v[248:251], v[8:11]
	v_mfma_f32_16x16x32_bf16 v[52:55], v[204:207], v[220:223], v[52:55]
	v_mfma_f32_16x16x32_bf16 v[48:51], v[212:215], v[220:223], v[48:51]
	v_mfma_f32_16x16x32_bf16 v[36:39], v[204:207], v[228:231], v[36:39]
	v_mfma_f32_16x16x32_bf16 v[32:35], v[212:215], v[228:231], v[32:35]
	v_mfma_f32_16x16x32_bf16 v[20:23], v[204:207], v[236:239], v[20:23]
	v_mfma_f32_16x16x32_bf16 v[16:19], v[212:215], v[236:239], v[16:19]
	v_mfma_f32_16x16x32_bf16 v[4:7], v[204:207], v[244:247], v[4:7]
	v_mfma_f32_16x16x32_bf16 v[0:3], v[212:215], v[244:247], v[0:3]
	v_mfma_f32_16x16x32_bf16 v[52:55], v[208:211], v[224:227], v[52:55]
	v_mfma_f32_16x16x32_bf16 v[48:51], v[216:219], v[224:227], v[48:51]
	v_mfma_f32_16x16x32_bf16 v[36:39], v[208:211], v[232:235], v[36:39]
	v_mfma_f32_16x16x32_bf16 v[32:35], v[216:219], v[232:235], v[32:35]
	v_mfma_f32_16x16x32_bf16 v[20:23], v[208:211], v[240:243], v[20:23]
	v_mfma_f32_16x16x32_bf16 v[16:19], v[216:219], v[240:243], v[16:19]
	v_mfma_f32_16x16x32_bf16 v[4:7], v[208:211], v[248:251], v[4:7]
	v_mfma_f32_16x16x32_bf16 v[0:3], v[216:219], v[248:251], v[0:3]
	s_barrier
	s_add_i32 s45, 0, 0x18000
	v_add_u32_e32 v144, s45, v160
	s_add_i32 s51, 0, 0x1c000
	ds_read_b128 v[138:141], v144
	ds_read_b128 v[154:157], v144 offset:1024
	ds_read_b128 v[172:175], v144 offset:2048
	ds_read_b128 v[176:179], v144 offset:3072
	v_add_u32_e32 v144, s51, v160
	ds_read_b128 v[204:207], v144
	ds_read_b128 v[208:211], v144 offset:1024
	ds_read_b128 v[212:215], v144 offset:2048
	ds_read_b128 v[216:219], v144 offset:3072
	s_add_u32 s4, s64, 0x40000
	s_addc_u32 s5, s65, 0
	s_mov_b32 m0, s71
	v_lshl_add_u64 v[252:253], s[4:5], 0, v[128:129]
	ds_read_b128 v[220:223], v170 offset:32768
	ds_read_b128 v[224:227], v170 offset:33792
	ds_read_b128 v[228:231], v170 offset:34816
	ds_read_b128 v[232:235], v170 offset:35840
	ds_read_b128 v[236:239], v170 offset:36864
	ds_read_b128 v[240:243], v170 offset:37888
	ds_read_b128 v[244:247], v170 offset:38912
	ds_read_b128 v[248:251], v170 offset:39936
	global_load_lds_dwordx4 v[252:253], off
	v_lshl_add_u64 v[252:253], s[4:5], 0, v[130:131]
	s_mov_b32 m0, s72
	s_nop 0
	global_load_lds_dwordx4 v[252:253], off
	s_waitcnt vmcnt(8)
	s_waitcnt lgkmcnt(0)
	s_barrier
	s_waitcnt lgkmcnt(0)
	v_mfma_f32_16x16x32_bf16 v[124:127], v[138:141], v[220:223], v[124:127]
	v_mfma_f32_16x16x32_bf16 v[120:123], v[172:175], v[220:223], v[120:123]
	v_mfma_f32_16x16x32_bf16 v[108:111], v[138:141], v[228:231], v[108:111]
	v_mfma_f32_16x16x32_bf16 v[104:107], v[172:175], v[228:231], v[104:107]
	v_mfma_f32_16x16x32_bf16 v[92:95], v[138:141], v[236:239], v[92:95]
	v_mfma_f32_16x16x32_bf16 v[88:91], v[172:175], v[236:239], v[88:91]
	v_mfma_f32_16x16x32_bf16 v[76:79], v[138:141], v[244:247], v[76:79]
	v_mfma_f32_16x16x32_bf16 v[72:75], v[172:175], v[244:247], v[72:75]
	v_mfma_f32_16x16x32_bf16 v[124:127], v[154:157], v[224:227], v[124:127]
	v_mfma_f32_16x16x32_bf16 v[120:123], v[176:179], v[224:227], v[120:123]
	v_mfma_f32_16x16x32_bf16 v[108:111], v[154:157], v[232:235], v[108:111]
	v_mfma_f32_16x16x32_bf16 v[104:107], v[176:179], v[232:235], v[104:107]
	v_mfma_f32_16x16x32_bf16 v[92:95], v[154:157], v[240:243], v[92:95]
	v_mfma_f32_16x16x32_bf16 v[88:91], v[176:179], v[240:243], v[88:91]
	v_mfma_f32_16x16x32_bf16 v[76:79], v[154:157], v[248:251], v[76:79]
	v_mfma_f32_16x16x32_bf16 v[72:75], v[176:179], v[248:251], v[72:75]
	v_mfma_f32_16x16x32_bf16 v[116:119], v[204:207], v[220:223], v[116:119]
	v_mfma_f32_16x16x32_bf16 v[112:115], v[212:215], v[220:223], v[112:115]
	v_mfma_f32_16x16x32_bf16 v[100:103], v[204:207], v[228:231], v[100:103]
	v_mfma_f32_16x16x32_bf16 v[96:99], v[212:215], v[228:231], v[96:99]
	v_mfma_f32_16x16x32_bf16 v[84:87], v[204:207], v[236:239], v[84:87]
	v_mfma_f32_16x16x32_bf16 v[80:83], v[212:215], v[236:239], v[80:83]
	v_mfma_f32_16x16x32_bf16 v[68:71], v[204:207], v[244:247], v[68:71]
	v_mfma_f32_16x16x32_bf16 v[64:67], v[212:215], v[244:247], v[64:67]
	v_mfma_f32_16x16x32_bf16 v[116:119], v[208:211], v[224:227], v[116:119]
	v_mfma_f32_16x16x32_bf16 v[112:115], v[216:219], v[224:227], v[112:115]
	v_mfma_f32_16x16x32_bf16 v[100:103], v[208:211], v[232:235], v[100:103]
	v_mfma_f32_16x16x32_bf16 v[96:99], v[216:219], v[232:235], v[96:99]
	v_mfma_f32_16x16x32_bf16 v[84:87], v[208:211], v[240:243], v[84:87]
	v_mfma_f32_16x16x32_bf16 v[80:83], v[216:219], v[240:243], v[80:83]
	v_mfma_f32_16x16x32_bf16 v[68:71], v[208:211], v[248:251], v[68:71]
	v_mfma_f32_16x16x32_bf16 v[64:67], v[216:219], v[248:251], v[64:67]
	s_barrier
	s_add_i32 s4, s45, s33
	v_lshl_add_u64 v[142:143], v[142:143], 0, s[26:27]
	s_mov_b32 m0, s4
	ds_read_b128 v[220:223], v170 offset:49152
	ds_read_b128 v[224:227], v170 offset:50176
	ds_read_b128 v[228:231], v170 offset:51200
	ds_read_b128 v[232:235], v170 offset:52224
	ds_read_b128 v[236:239], v170 offset:53248
	ds_read_b128 v[240:243], v170 offset:54272
	ds_read_b128 v[244:247], v170 offset:55296
	ds_read_b128 v[248:251], v170 offset:56320
	global_load_lds_dwordx4 v[142:143], off
	s_add_i32 m0, s4, 0x2000
	s_add_u32 s4, s34, 0x40080
	v_lshl_add_u64 v[142:143], v[158:159], 0, s[26:27]
	s_addc_u32 s5, s35, 0
	s_add_i32 s34, s51, s33
	global_load_lds_dwordx4 v[142:143], off
	v_lshl_add_u64 v[142:143], s[4:5], 0, v[128:129]
	s_mov_b32 m0, s34
	s_nop 0
	global_load_lds_dwordx4 v[142:143], off
	v_lshl_add_u64 v[142:143], s[4:5], 0, v[130:131]
	s_add_i32 m0, s34, 0x2000
	s_nop 0
	global_load_lds_dwordx4 v[142:143], off
	v_lshl_add_u64 v[142:143], v[180:181], 0, s[26:27]
	s_mov_b32 m0, s73
	s_nop 0
	global_load_lds_dwordx4 v[142:143], off
	v_lshl_add_u64 v[142:143], v[202:203], 0, s[26:27]
	s_mov_b32 m0, s74
	s_nop 0
	global_load_lds_dwordx4 v[142:143], off
	s_waitcnt vmcnt(8)
	s_waitcnt lgkmcnt(0)
	s_barrier
	s_waitcnt lgkmcnt(0)
	v_mfma_f32_16x16x32_bf16 v[60:63], v[138:141], v[220:223], v[60:63]
	v_mfma_f32_16x16x32_bf16 v[56:59], v[172:175], v[220:223], v[56:59]
	v_mfma_f32_16x16x32_bf16 v[44:47], v[138:141], v[228:231], v[44:47]
	v_mfma_f32_16x16x32_bf16 v[40:43], v[172:175], v[228:231], v[40:43]
	v_mfma_f32_16x16x32_bf16 v[28:31], v[138:141], v[236:239], v[28:31]
	v_mfma_f32_16x16x32_bf16 v[24:27], v[172:175], v[236:239], v[24:27]
	v_mfma_f32_16x16x32_bf16 v[12:15], v[138:141], v[244:247], v[12:15]
	v_mfma_f32_16x16x32_bf16 v[8:11], v[172:175], v[244:247], v[8:11]
	v_mfma_f32_16x16x32_bf16 v[60:63], v[154:157], v[224:227], v[60:63]
	v_mfma_f32_16x16x32_bf16 v[56:59], v[176:179], v[224:227], v[56:59]
	v_mfma_f32_16x16x32_bf16 v[44:47], v[154:157], v[232:235], v[44:47]
	v_mfma_f32_16x16x32_bf16 v[40:43], v[176:179], v[232:235], v[40:43]
	v_mfma_f32_16x16x32_bf16 v[28:31], v[154:157], v[240:243], v[28:31]
	v_mfma_f32_16x16x32_bf16 v[24:27], v[176:179], v[240:243], v[24:27]
	v_mfma_f32_16x16x32_bf16 v[12:15], v[154:157], v[248:251], v[12:15]
	v_mfma_f32_16x16x32_bf16 v[8:11], v[176:179], v[248:251], v[8:11]
	v_mfma_f32_16x16x32_bf16 v[52:55], v[204:207], v[220:223], v[52:55]
	v_mfma_f32_16x16x32_bf16 v[48:51], v[212:215], v[220:223], v[48:51]
	v_mfma_f32_16x16x32_bf16 v[36:39], v[204:207], v[228:231], v[36:39]
	v_mfma_f32_16x16x32_bf16 v[32:35], v[212:215], v[228:231], v[32:35]
	v_mfma_f32_16x16x32_bf16 v[20:23], v[204:207], v[236:239], v[20:23]
	v_mfma_f32_16x16x32_bf16 v[16:19], v[212:215], v[236:239], v[16:19]
	v_mfma_f32_16x16x32_bf16 v[4:7], v[204:207], v[244:247], v[4:7]
	v_mfma_f32_16x16x32_bf16 v[0:3], v[212:215], v[244:247], v[0:3]
	v_mfma_f32_16x16x32_bf16 v[52:55], v[208:211], v[224:227], v[52:55]
	v_mfma_f32_16x16x32_bf16 v[48:51], v[216:219], v[224:227], v[48:51]
	v_mfma_f32_16x16x32_bf16 v[36:39], v[208:211], v[232:235], v[36:39]
	v_mfma_f32_16x16x32_bf16 v[32:35], v[216:219], v[232:235], v[32:35]
	v_mfma_f32_16x16x32_bf16 v[20:23], v[208:211], v[240:243], v[20:23]
	v_mfma_f32_16x16x32_bf16 v[16:19], v[216:219], v[240:243], v[16:19]
	v_mfma_f32_16x16x32_bf16 v[4:7], v[208:211], v[248:251], v[4:7]
	v_mfma_f32_16x16x32_bf16 v[0:3], v[216:219], v[248:251], v[0:3]
	s_barrier
	s_add_i32 s29, s29, 2
	s_add_u32 s3, s3, 0x100
	s_addc_u32 s28, s28, 0
	s_cmp_gt_u32 s29, 13
	s_mov_b64 s[60:61], s[62:63]
	s_cbranch_scc0 .LBB0_1207
	s_setprio 0
	s_and_b64 vcc, exec, s[48:49]
	s_cbranch_vccz .LBB0_1210
	s_barrier

.LBB0_1304:
	s_ashr_i32 s51, s50, 31
	s_lshl_b64 s[2:3], s[50:51], 19
	s_add_u32 s52, s28, s2
	s_addc_u32 s53, s29, s3
	s_and_b64 s[2:3], s[38:39], exec
	s_cselect_b32 s36, s53, s35
	s_cselect_b32 s51, s52, s34
	s_ashr_i32 s49, s48, 31
	s_lshl_b64 s[2:3], s[48:49], 19
	s_add_u32 s54, s30, s2
	s_addc_u32 s55, s62, s3
	s_and_b64 s[2:3], s[38:39], exec
	s_cselect_b32 s49, s55, s61
	s_cselect_b32 s70, s54, s60
	s_add_u32 s2, s34, 0x40080
	s_addc_u32 s3, s35, 0
	s_add_u32 s71, s60, 0x100
	v_mov_b32_e32 v0, 0
	s_addc_u32 s72, s61, 0
	s_mov_b32 s73, -2
	v_mov_b32_e32 v1, v0
	v_mov_b32_e32 v2, v0
	v_mov_b32_e32 v3, v0
	v_mov_b32_e32 v4, v0
	v_mov_b32_e32 v5, v0
	v_mov_b32_e32 v6, v0
	v_mov_b32_e32 v7, v0
	v_mov_b32_e32 v16, v0
	v_mov_b32_e32 v17, v0
	v_mov_b32_e32 v18, v0
	v_mov_b32_e32 v19, v0
	v_mov_b32_e32 v20, v0
	v_mov_b32_e32 v21, v0
	v_mov_b32_e32 v22, v0
	v_mov_b32_e32 v23, v0
	v_mov_b32_e32 v32, v0
	v_mov_b32_e32 v33, v0
	v_mov_b32_e32 v34, v0
	v_mov_b32_e32 v35, v0
	v_mov_b32_e32 v36, v0
	v_mov_b32_e32 v37, v0
	v_mov_b32_e32 v38, v0
	v_mov_b32_e32 v39, v0
	v_mov_b32_e32 v48, v0
	v_mov_b32_e32 v49, v0
	v_mov_b32_e32 v50, v0
	v_mov_b32_e32 v51, v0
	v_mov_b32_e32 v52, v0
	v_mov_b32_e32 v53, v0
	v_mov_b32_e32 v54, v0
	v_mov_b32_e32 v55, v0
	v_mov_b32_e32 v8, v0
	v_mov_b32_e32 v9, v0
	v_mov_b32_e32 v10, v0
	v_mov_b32_e32 v11, v0
	v_mov_b32_e32 v12, v0
	v_mov_b32_e32 v13, v0
	v_mov_b32_e32 v14, v0
	v_mov_b32_e32 v15, v0
	v_mov_b32_e32 v24, v0
	v_mov_b32_e32 v25, v0
	v_mov_b32_e32 v26, v0
	v_mov_b32_e32 v27, v0
	v_mov_b32_e32 v28, v0
	v_mov_b32_e32 v29, v0
	v_mov_b32_e32 v30, v0
	v_mov_b32_e32 v31, v0
	v_mov_b32_e32 v40, v0
	v_mov_b32_e32 v41, v0
	v_mov_b32_e32 v42, v0
	v_mov_b32_e32 v43, v0
	v_mov_b32_e32 v44, v0
	v_mov_b32_e32 v45, v0
	v_mov_b32_e32 v46, v0
	v_mov_b32_e32 v47, v0
	v_mov_b32_e32 v56, v0
	v_mov_b32_e32 v57, v0
	v_mov_b32_e32 v58, v0
	v_mov_b32_e32 v59, v0
	v_mov_b32_e32 v60, v0
	v_mov_b32_e32 v61, v0
	v_mov_b32_e32 v62, v0
	v_mov_b32_e32 v63, v0
	v_mov_b32_e32 v64, v0
	v_mov_b32_e32 v65, v0
	v_mov_b32_e32 v66, v0
	v_mov_b32_e32 v67, v0
	v_mov_b32_e32 v68, v0
	v_mov_b32_e32 v69, v0
	v_mov_b32_e32 v70, v0
	v_mov_b32_e32 v71, v0
	v_mov_b32_e32 v80, v0
	v_mov_b32_e32 v81, v0
	v_mov_b32_e32 v82, v0
	v_mov_b32_e32 v83, v0
	v_mov_b32_e32 v84, v0
	v_mov_b32_e32 v85, v0
	v_mov_b32_e32 v86, v0
	v_mov_b32_e32 v87, v0
	v_mov_b32_e32 v96, v0
	v_mov_b32_e32 v97, v0
	v_mov_b32_e32 v98, v0
	v_mov_b32_e32 v99, v0
	v_mov_b32_e32 v100, v0
	v_mov_b32_e32 v101, v0
	v_mov_b32_e32 v102, v0
	v_mov_b32_e32 v103, v0
	v_mov_b32_e32 v112, v0
	v_mov_b32_e32 v113, v0
	v_mov_b32_e32 v114, v0
	v_mov_b32_e32 v115, v0
	v_mov_b32_e32 v116, v0
	v_mov_b32_e32 v117, v0
	v_mov_b32_e32 v118, v0
	v_mov_b32_e32 v119, v0
	v_mov_b32_e32 v72, v0
	v_mov_b32_e32 v73, v0
	v_mov_b32_e32 v74, v0
	v_mov_b32_e32 v75, v0
	v_mov_b32_e32 v76, v0
	v_mov_b32_e32 v77, v0
	v_mov_b32_e32 v78, v0
	v_mov_b32_e32 v79, v0
	v_mov_b32_e32 v88, v0
	v_mov_b32_e32 v89, v0
	v_mov_b32_e32 v90, v0
	v_mov_b32_e32 v91, v0
	v_mov_b32_e32 v92, v0
	v_mov_b32_e32 v93, v0
	v_mov_b32_e32 v94, v0
	v_mov_b32_e32 v95, v0
	v_mov_b32_e32 v104, v0
	v_mov_b32_e32 v105, v0
	v_mov_b32_e32 v106, v0
	v_mov_b32_e32 v107, v0
	v_mov_b32_e32 v108, v0
	v_mov_b32_e32 v109, v0
	v_mov_b32_e32 v110, v0
	v_mov_b32_e32 v111, v0
	v_mov_b32_e32 v120, v0
	v_mov_b32_e32 v121, v0
	v_mov_b32_e32 v122, v0
	v_mov_b32_e32 v123, v0
	v_mov_b32_e32 v124, v0
	v_mov_b32_e32 v125, v0
	v_mov_b32_e32 v126, v0
	v_mov_b32_e32 v127, v0
	v_readfirstlane_b32 s4, v182
	s_nop 3
	s_cmp_lt_u32 s4, 256
	s_cbranch_scc1 .Lkprio_1305
	s_setprio 1
.Lkprio_1305:
.LBB0_1305:
	s_add_u32 s4, s2, 0xfffc0080
	s_addc_u32 s5, s3, -1
	s_add_i32 s74, 0, 0x10000
	s_cmp_eq_u32 s73, 12
	s_cselect_b32 s61, s36, s5
	s_cselect_b32 s60, s51, s4
	s_cselect_b32 s35, s49, s72
	s_cselect_b32 s34, s70, s71
	s_add_i32 s75, 0, 0x14000
	v_add_u32_e32 v164, s74, v143
	v_add_u32_e32 v180, s75, v143
	ds_read_b128 v[138:141], v164
	ds_read_b128 v[156:159], v164 offset:1024
	ds_read_b128 v[160:163], v164 offset:2048
	ds_read_b128 v[164:167], v164 offset:3072
	ds_read_b128 v[168:171], v180
	ds_read_b128 v[172:175], v180 offset:1024
	ds_read_b128 v[176:179], v180 offset:2048
	ds_read_b128 v[204:207], v180 offset:3072
	v_lshl_add_u64 v[180:181], s[2:3], 0, v[134:135]
	s_add_i32 m0, s59, 0xc000
	ds_read_b128 v[208:211], v155
	ds_read_b128 v[212:215], v155 offset:1024
	ds_read_b128 v[216:219], v155 offset:2048
	ds_read_b128 v[220:223], v155 offset:3072
	ds_read_b128 v[224:227], v155 offset:4096
	ds_read_b128 v[228:231], v155 offset:5120
	ds_read_b128 v[232:235], v155 offset:6144
	ds_read_b128 v[236:239], v155 offset:7168
	global_load_lds_dwordx4 v[180:181], off
	v_lshl_add_u64 v[180:181], s[2:3], 0, v[136:137]
	s_add_i32 m0, s59, 0xe000
	s_nop 0
	global_load_lds_dwordx4 v[180:181], off
	s_waitcnt vmcnt(8)
	s_waitcnt lgkmcnt(0)
	s_barrier
	s_waitcnt lgkmcnt(0)
	v_mfma_f32_16x16x32_bf16 v[124:127], v[138:141], v[208:211], v[124:127]
	v_mfma_f32_16x16x32_bf16 v[120:123], v[160:163], v[208:211], v[120:123]
	v_mfma_f32_16x16x32_bf16 v[108:111], v[138:141], v[216:219], v[108:111]
	v_mfma_f32_16x16x32_bf16 v[104:107], v[160:163], v[216:219], v[104:107]
	v_mfma_f32_16x16x32_bf16 v[92:95], v[138:141], v[224:227], v[92:95]
	v_mfma_f32_16x16x32_bf16 v[88:91], v[160:163], v[224:227], v[88:91]
	v_mfma_f32_16x16x32_bf16 v[76:79], v[138:141], v[232:235], v[76:79]
	v_mfma_f32_16x16x32_bf16 v[72:75], v[160:163], v[232:235], v[72:75]
	v_mfma_f32_16x16x32_bf16 v[124:127], v[156:159], v[212:215], v[124:127]
	v_mfma_f32_16x16x32_bf16 v[120:123], v[164:167], v[212:215], v[120:123]
	v_mfma_f32_16x16x32_bf16 v[108:111], v[156:159], v[220:223], v[108:111]
	v_mfma_f32_16x16x32_bf16 v[104:107], v[164:167], v[220:223], v[104:107]
	v_mfma_f32_16x16x32_bf16 v[92:95], v[156:159], v[228:231], v[92:95]
	v_mfma_f32_16x16x32_bf16 v[88:91], v[164:167], v[228:231], v[88:91]
	v_mfma_f32_16x16x32_bf16 v[76:79], v[156:159], v[236:239], v[76:79]
	v_mfma_f32_16x16x32_bf16 v[72:75], v[164:167], v[236:239], v[72:75]
	v_mfma_f32_16x16x32_bf16 v[116:119], v[168:171], v[208:211], v[116:119]
	v_mfma_f32_16x16x32_bf16 v[112:115], v[176:179], v[208:211], v[112:115]
	v_mfma_f32_16x16x32_bf16 v[100:103], v[168:171], v[216:219], v[100:103]
	v_mfma_f32_16x16x32_bf16 v[96:99], v[176:179], v[216:219], v[96:99]
	v_mfma_f32_16x16x32_bf16 v[84:87], v[168:171], v[224:227], v[84:87]
	v_mfma_f32_16x16x32_bf16 v[80:83], v[176:179], v[224:227], v[80:83]
	v_mfma_f32_16x16x32_bf16 v[68:71], v[168:171], v[232:235], v[68:71]
	v_mfma_f32_16x16x32_bf16 v[64:67], v[176:179], v[232:235], v[64:67]
	v_mfma_f32_16x16x32_bf16 v[116:119], v[172:175], v[212:215], v[116:119]
	v_mfma_f32_16x16x32_bf16 v[112:115], v[204:207], v[212:215], v[112:115]
	v_mfma_f32_16x16x32_bf16 v[100:103], v[172:175], v[220:223], v[100:103]
	v_mfma_f32_16x16x32_bf16 v[96:99], v[204:207], v[220:223], v[96:99]
	v_mfma_f32_16x16x32_bf16 v[84:87], v[172:175], v[228:231], v[84:87]
	v_mfma_f32_16x16x32_bf16 v[80:83], v[204:207], v[228:231], v[80:83]
	v_mfma_f32_16x16x32_bf16 v[68:71], v[172:175], v[236:239], v[68:71]
	v_mfma_f32_16x16x32_bf16 v[64:67], v[204:207], v[236:239], v[64:67]
	s_barrier
	s_add_i32 s4, s74, s1
	v_lshl_add_u64 v[180:181], s[34:35], 0, v[144:145]
	s_mov_b32 m0, s4
	ds_read_b128 v[208:211], v155 offset:16384
	ds_read_b128 v[212:215], v155 offset:17408
	ds_read_b128 v[216:219], v155 offset:18432
	ds_read_b128 v[220:223], v155 offset:19456
	ds_read_b128 v[224:227], v155 offset:20480
	ds_read_b128 v[228:231], v155 offset:21504
	ds_read_b128 v[232:235], v155 offset:22528
	ds_read_b128 v[236:239], v155 offset:23552
	global_load_lds_dwordx4 v[180:181], off
	s_add_i32 m0, s4, 0x2000
	s_add_u32 s4, s34, 0x40000
	v_lshl_add_u64 v[202:203], s[34:35], 0, v[128:129]
	s_addc_u32 s5, s35, 0
	s_add_i32 s74, s75, s1
	global_load_lds_dwordx4 v[202:203], off
	v_lshl_add_u64 v[240:241], s[4:5], 0, v[144:145]
	s_mov_b32 m0, s74
	v_lshl_add_u64 v[242:243], s[60:61], 0, v[130:131]
	global_load_lds_dwordx4 v[240:241], off
	v_lshl_add_u64 v[240:241], s[4:5], 0, v[128:129]
	s_add_i32 m0, s74, 0x2000
	s_nop 0
	global_load_lds_dwordx4 v[240:241], off
	v_lshl_add_u64 v[240:241], s[60:61], 0, v[132:133]
	s_mov_b32 m0, s59
	s_nop 0
	global_load_lds_dwordx4 v[240:241], off
	s_mov_b32 m0, s64
	s_nop 0
	global_load_lds_dwordx4 v[242:243], off
	s_waitcnt vmcnt(8)
	s_waitcnt lgkmcnt(0)
	s_barrier
	s_waitcnt lgkmcnt(0)
	v_mfma_f32_16x16x32_bf16 v[60:63], v[138:141], v[208:211], v[60:63]
	v_mfma_f32_16x16x32_bf16 v[56:59], v[160:163], v[208:211], v[56:59]
	v_mfma_f32_16x16x32_bf16 v[44:47], v[138:141], v[216:219], v[44:47]
	v_mfma_f32_16x16x32_bf16 v[40:43], v[160:163], v[216:219], v[40:43]
	v_mfma_f32_16x16x32_bf16 v[28:31], v[138:141], v[224:227], v[28:31]
	v_mfma_f32_16x16x32_bf16 v[24:27], v[160:163], v[224:227], v[24:27]
	v_mfma_f32_16x16x32_bf16 v[12:15], v[138:141], v[232:235], v[12:15]
	v_mfma_f32_16x16x32_bf16 v[8:11], v[160:163], v[232:235], v[8:11]
	v_mfma_f32_16x16x32_bf16 v[60:63], v[156:159], v[212:215], v[60:63]
	v_mfma_f32_16x16x32_bf16 v[56:59], v[164:167], v[212:215], v[56:59]
	v_mfma_f32_16x16x32_bf16 v[44:47], v[156:159], v[220:223], v[44:47]
	v_mfma_f32_16x16x32_bf16 v[40:43], v[164:167], v[220:223], v[40:43]
	v_mfma_f32_16x16x32_bf16 v[28:31], v[156:159], v[228:231], v[28:31]
	v_mfma_f32_16x16x32_bf16 v[24:27], v[164:167], v[228:231], v[24:27]
	v_mfma_f32_16x16x32_bf16 v[12:15], v[156:159], v[236:239], v[12:15]
	v_mfma_f32_16x16x32_bf16 v[8:11], v[164:167], v[236:239], v[8:11]
	v_mfma_f32_16x16x32_bf16 v[52:55], v[168:171], v[208:211], v[52:55]
	v_mfma_f32_16x16x32_bf16 v[48:51], v[176:179], v[208:211], v[48:51]
	v_mfma_f32_16x16x32_bf16 v[36:39], v[168:171], v[216:219], v[36:39]
	v_mfma_f32_16x16x32_bf16 v[32:35], v[176:179], v[216:219], v[32:35]
	v_mfma_f32_16x16x32_bf16 v[20:23], v[168:171], v[224:227], v[20:23]
	v_mfma_f32_16x16x32_bf16 v[16:19], v[176:179], v[224:227], v[16:19]
	v_mfma_f32_16x16x32_bf16 v[4:7], v[168:171], v[232:235], v[4:7]
	v_mfma_f32_16x16x32_bf16 v[0:3], v[176:179], v[232:235], v[0:3]
	v_mfma_f32_16x16x32_bf16 v[52:55], v[172:175], v[212:215], v[52:55]
	v_mfma_f32_16x16x32_bf16 v[48:51], v[204:207], v[212:215], v[48:51]
	v_mfma_f32_16x16x32_bf16 v[36:39], v[172:175], v[220:223], v[36:39]
	v_mfma_f32_16x16x32_bf16 v[32:35], v[204:207], v[220:223], v[32:35]
	v_mfma_f32_16x16x32_bf16 v[20:23], v[172:175], v[228:231], v[20:23]
	v_mfma_f32_16x16x32_bf16 v[16:19], v[204:207], v[228:231], v[16:19]
	v_mfma_f32_16x16x32_bf16 v[4:7], v[172:175], v[236:239], v[4:7]
	v_mfma_f32_16x16x32_bf16 v[0:3], v[204:207], v[236:239], v[0:3]
	s_barrier
	s_add_i32 s74, 0, 0x18000
	s_add_i32 s75, 0, 0x1c000
	v_add_u32_e32 v164, s74, v143
	v_add_u32_e32 v204, s75, v143
	ds_read_b128 v[138:141], v164
	ds_read_b128 v[156:159], v164 offset:1024
	ds_read_b128 v[160:163], v164 offset:2048
	ds_read_b128 v[164:167], v164 offset:3072
	ds_read_b128 v[168:171], v204
	ds_read_b128 v[172:175], v204 offset:1024
	ds_read_b128 v[176:179], v204 offset:2048
	ds_read_b128 v[204:207], v204 offset:3072
	s_add_u32 s4, s60, 0x40000
	s_addc_u32 s5, s61, 0
	s_mov_b32 m0, s65
	v_lshl_add_u64 v[244:245], s[4:5], 0, v[132:133]
	ds_read_b128 v[208:211], v155 offset:32768
	ds_read_b128 v[212:215], v155 offset:33792
	ds_read_b128 v[216:219], v155 offset:34816
	ds_read_b128 v[220:223], v155 offset:35840
	ds_read_b128 v[224:227], v155 offset:36864
	ds_read_b128 v[228:231], v155 offset:37888
	ds_read_b128 v[232:235], v155 offset:38912
	ds_read_b128 v[236:239], v155 offset:39936
	global_load_lds_dwordx4 v[244:245], off
	v_lshl_add_u64 v[244:245], s[4:5], 0, v[130:131]
	s_mov_b32 m0, s66
	s_nop 0
	global_load_lds_dwordx4 v[244:245], off
	s_waitcnt vmcnt(8)
	s_waitcnt lgkmcnt(0)
	s_barrier
	s_waitcnt lgkmcnt(0)
	v_mfma_f32_16x16x32_bf16 v[124:127], v[138:141], v[208:211], v[124:127]
	v_mfma_f32_16x16x32_bf16 v[120:123], v[160:163], v[208:211], v[120:123]
	v_mfma_f32_16x16x32_bf16 v[108:111], v[138:141], v[216:219], v[108:111]
	v_mfma_f32_16x16x32_bf16 v[104:107], v[160:163], v[216:219], v[104:107]
	v_mfma_f32_16x16x32_bf16 v[92:95], v[138:141], v[224:227], v[92:95]
	v_mfma_f32_16x16x32_bf16 v[88:91], v[160:163], v[224:227], v[88:91]
	v_mfma_f32_16x16x32_bf16 v[76:79], v[138:141], v[232:235], v[76:79]
	v_mfma_f32_16x16x32_bf16 v[72:75], v[160:163], v[232:235], v[72:75]
	v_mfma_f32_16x16x32_bf16 v[124:127], v[156:159], v[212:215], v[124:127]
	v_mfma_f32_16x16x32_bf16 v[120:123], v[164:167], v[212:215], v[120:123]
	v_mfma_f32_16x16x32_bf16 v[108:111], v[156:159], v[220:223], v[108:111]
	v_mfma_f32_16x16x32_bf16 v[104:107], v[164:167], v[220:223], v[104:107]
	v_mfma_f32_16x16x32_bf16 v[92:95], v[156:159], v[228:231], v[92:95]
	v_mfma_f32_16x16x32_bf16 v[88:91], v[164:167], v[228:231], v[88:91]
	v_mfma_f32_16x16x32_bf16 v[76:79], v[156:159], v[236:239], v[76:79]
	v_mfma_f32_16x16x32_bf16 v[72:75], v[164:167], v[236:239], v[72:75]
	v_mfma_f32_16x16x32_bf16 v[116:119], v[168:171], v[208:211], v[116:119]
	v_mfma_f32_16x16x32_bf16 v[112:115], v[176:179], v[208:211], v[112:115]
	v_mfma_f32_16x16x32_bf16 v[100:103], v[168:171], v[216:219], v[100:103]
	v_mfma_f32_16x16x32_bf16 v[96:99], v[176:179], v[216:219], v[96:99]
	v_mfma_f32_16x16x32_bf16 v[84:87], v[168:171], v[224:227], v[84:87]
	v_mfma_f32_16x16x32_bf16 v[80:83], v[176:179], v[224:227], v[80:83]
	v_mfma_f32_16x16x32_bf16 v[68:71], v[168:171], v[232:235], v[68:71]
	v_mfma_f32_16x16x32_bf16 v[64:67], v[176:179], v[232:235], v[64:67]
	v_mfma_f32_16x16x32_bf16 v[116:119], v[172:175], v[212:215], v[116:119]
	v_mfma_f32_16x16x32_bf16 v[112:115], v[204:207], v[212:215], v[112:115]
	v_mfma_f32_16x16x32_bf16 v[100:103], v[172:175], v[220:223], v[100:103]
	v_mfma_f32_16x16x32_bf16 v[96:99], v[204:207], v[220:223], v[96:99]
	v_mfma_f32_16x16x32_bf16 v[84:87], v[172:175], v[228:231], v[84:87]
	v_mfma_f32_16x16x32_bf16 v[80:83], v[204:207], v[228:231], v[80:83]
	v_mfma_f32_16x16x32_bf16 v[68:71], v[172:175], v[236:239], v[68:71]
	v_mfma_f32_16x16x32_bf16 v[64:67], v[204:207], v[236:239], v[64:67]
	s_barrier
	s_add_i32 s4, s74, s1
	v_lshl_add_u64 v[180:181], v[180:181], 0, s[26:27]
	s_mov_b32 m0, s4
	ds_read_b128 v[208:211], v155 offset:49152
	ds_read_b128 v[212:215], v155 offset:50176
	ds_read_b128 v[216:219], v155 offset:51200
	ds_read_b128 v[220:223], v155 offset:52224
	ds_read_b128 v[224:227], v155 offset:53248
	ds_read_b128 v[228:231], v155 offset:54272
	ds_read_b128 v[232:235], v155 offset:55296
	ds_read_b128 v[236:239], v155 offset:56320
	global_load_lds_dwordx4 v[180:181], off
	s_add_i32 m0, s4, 0x2000
	s_add_u32 s4, s34, 0x40080
	v_lshl_add_u64 v[180:181], v[202:203], 0, s[26:27]
	s_addc_u32 s5, s35, 0
	s_add_i32 s34, s75, s1
	global_load_lds_dwordx4 v[180:181], off
	v_lshl_add_u64 v[180:181], s[4:5], 0, v[144:145]
	s_mov_b32 m0, s34
	s_nop 0
	global_load_lds_dwordx4 v[180:181], off
	v_lshl_add_u64 v[180:181], s[4:5], 0, v[128:129]
	s_add_i32 m0, s34, 0x2000
	s_nop 0
	global_load_lds_dwordx4 v[180:181], off
	v_lshl_add_u64 v[180:181], v[240:241], 0, s[26:27]
	s_mov_b32 m0, s67
	s_nop 0
	global_load_lds_dwordx4 v[180:181], off
	v_lshl_add_u64 v[180:181], v[242:243], 0, s[26:27]
	s_mov_b32 m0, s68
	s_nop 0
	global_load_lds_dwordx4 v[180:181], off
	s_waitcnt vmcnt(8)
	s_waitcnt lgkmcnt(0)
	s_barrier
	s_waitcnt lgkmcnt(0)
	v_mfma_f32_16x16x32_bf16 v[60:63], v[138:141], v[208:211], v[60:63]
	v_mfma_f32_16x16x32_bf16 v[56:59], v[160:163], v[208:211], v[56:59]
	v_mfma_f32_16x16x32_bf16 v[44:47], v[138:141], v[216:219], v[44:47]
	v_mfma_f32_16x16x32_bf16 v[40:43], v[160:163], v[216:219], v[40:43]
	v_mfma_f32_16x16x32_bf16 v[28:31], v[138:141], v[224:227], v[28:31]
	v_mfma_f32_16x16x32_bf16 v[24:27], v[160:163], v[224:227], v[24:27]
	v_mfma_f32_16x16x32_bf16 v[12:15], v[138:141], v[232:235], v[12:15]
	v_mfma_f32_16x16x32_bf16 v[8:11], v[160:163], v[232:235], v[8:11]
	v_mfma_f32_16x16x32_bf16 v[60:63], v[156:159], v[212:215], v[60:63]
	v_mfma_f32_16x16x32_bf16 v[56:59], v[164:167], v[212:215], v[56:59]
	v_mfma_f32_16x16x32_bf16 v[44:47], v[156:159], v[220:223], v[44:47]
	v_mfma_f32_16x16x32_bf16 v[40:43], v[164:167], v[220:223], v[40:43]
	v_mfma_f32_16x16x32_bf16 v[28:31], v[156:159], v[228:231], v[28:31]
	v_mfma_f32_16x16x32_bf16 v[24:27], v[164:167], v[228:231], v[24:27]
	v_mfma_f32_16x16x32_bf16 v[12:15], v[156:159], v[236:239], v[12:15]
	v_mfma_f32_16x16x32_bf16 v[8:11], v[164:167], v[236:239], v[8:11]
	v_mfma_f32_16x16x32_bf16 v[52:55], v[168:171], v[208:211], v[52:55]
	v_mfma_f32_16x16x32_bf16 v[48:51], v[176:179], v[208:211], v[48:51]
	v_mfma_f32_16x16x32_bf16 v[36:39], v[168:171], v[216:219], v[36:39]
	v_mfma_f32_16x16x32_bf16 v[32:35], v[176:179], v[216:219], v[32:35]
	v_mfma_f32_16x16x32_bf16 v[20:23], v[168:171], v[224:227], v[20:23]
	v_mfma_f32_16x16x32_bf16 v[16:19], v[176:179], v[224:227], v[16:19]
	v_mfma_f32_16x16x32_bf16 v[4:7], v[168:171], v[232:235], v[4:7]
	v_mfma_f32_16x16x32_bf16 v[0:3], v[176:179], v[232:235], v[0:3]
	v_mfma_f32_16x16x32_bf16 v[52:55], v[172:175], v[212:215], v[52:55]
	v_mfma_f32_16x16x32_bf16 v[48:51], v[204:207], v[212:215], v[48:51]
	v_mfma_f32_16x16x32_bf16 v[36:39], v[172:175], v[220:223], v[36:39]
	v_mfma_f32_16x16x32_bf16 v[32:35], v[204:207], v[220:223], v[32:35]
	v_mfma_f32_16x16x32_bf16 v[20:23], v[172:175], v[228:231], v[20:23]
	v_mfma_f32_16x16x32_bf16 v[16:19], v[204:207], v[228:231], v[16:19]
	v_mfma_f32_16x16x32_bf16 v[4:7], v[172:175], v[236:239], v[4:7]
	v_mfma_f32_16x16x32_bf16 v[0:3], v[204:207], v[236:239], v[0:3]
	s_barrier
	s_add_i32 s73, s73, 2
	s_add_u32 s2, s2, 0x100
	s_addc_u32 s3, s3, 0
	s_add_u32 s71, s71, 0x100
	s_addc_u32 s72, s72, 0
	s_cmp_gt_u32 s73, 13
	s_cbranch_scc0 .LBB0_1305
	s_setprio 0
	v_lshl_add_u32 v140, s58, 8, v142
	v_ashrrev_i32_e32 v141, 31, v140
	v_lshl_add_u64 v[156:157], v[140:141], 4, s[44:45]
	global_load_dwordx4 v[208:211], v[156:157], off
	global_load_dwordx4 v[212:215], v[156:157], off offset:256
	global_load_dwordx4 v[216:219], v[156:157], off offset:512
	global_load_dwordx4 v[220:223], v[156:157], off offset:768
	global_load_dwordx4 v[224:227], v[156:157], off offset:2048
	global_load_dwordx4 v[228:231], v[156:157], off offset:2304
	global_load_dwordx4 v[232:235], v[156:157], off offset:2560
	global_load_dwordx4 v[236:239], v[156:157], off offset:2816
	s_and_b64 vcc, exec, s[46:47]
	s_cbranch_vccz .LBB0_1308
	s_barrier

.LBB0_1398:
	s_add_u32 s3, s58, 0x100
	v_mov_b32_e32 v0, 0
	s_addc_u32 s28, s59, 0
	s_mov_b32 s29, -2
	s_waitcnt lgkmcnt(0)
	v_mov_b32_e32 v1, v0
	v_mov_b32_e32 v2, v0
	v_mov_b32_e32 v3, v0
	v_mov_b32_e32 v4, v0
	v_mov_b32_e32 v5, v0
	v_mov_b32_e32 v6, v0
	v_mov_b32_e32 v7, v0
	v_mov_b32_e32 v16, v0
	v_mov_b32_e32 v17, v0
	v_mov_b32_e32 v18, v0
	v_mov_b32_e32 v19, v0
	v_mov_b32_e32 v20, v0
	v_mov_b32_e32 v21, v0
	v_mov_b32_e32 v22, v0
	v_mov_b32_e32 v23, v0
	v_mov_b32_e32 v32, v0
	v_mov_b32_e32 v33, v0
	v_mov_b32_e32 v34, v0
	v_mov_b32_e32 v35, v0
	v_mov_b32_e32 v36, v0
	v_mov_b32_e32 v37, v0
	v_mov_b32_e32 v38, v0
	v_mov_b32_e32 v39, v0
	v_mov_b32_e32 v48, v0
	v_mov_b32_e32 v49, v0
	v_mov_b32_e32 v50, v0
	v_mov_b32_e32 v51, v0
	v_mov_b32_e32 v52, v0
	v_mov_b32_e32 v53, v0
	v_mov_b32_e32 v54, v0
	v_mov_b32_e32 v55, v0
	v_mov_b32_e32 v8, v0
	v_mov_b32_e32 v9, v0
	v_mov_b32_e32 v10, v0
	v_mov_b32_e32 v11, v0
	v_mov_b32_e32 v12, v0
	v_mov_b32_e32 v13, v0
	v_mov_b32_e32 v14, v0
	v_mov_b32_e32 v15, v0
	v_mov_b32_e32 v24, v0
	v_mov_b32_e32 v25, v0
	v_mov_b32_e32 v26, v0
	v_mov_b32_e32 v27, v0
	v_mov_b32_e32 v28, v0
	v_mov_b32_e32 v29, v0
	v_mov_b32_e32 v30, v0
	v_mov_b32_e32 v31, v0
	v_mov_b32_e32 v40, v0
	v_mov_b32_e32 v41, v0
	v_mov_b32_e32 v42, v0
	v_mov_b32_e32 v43, v0
	v_mov_b32_e32 v44, v0
	v_mov_b32_e32 v45, v0
	v_mov_b32_e32 v46, v0
	v_mov_b32_e32 v47, v0
	v_mov_b32_e32 v56, v0
	v_mov_b32_e32 v57, v0
	v_mov_b32_e32 v58, v0
	v_mov_b32_e32 v59, v0
	v_mov_b32_e32 v60, v0
	v_mov_b32_e32 v61, v0
	v_mov_b32_e32 v62, v0
	v_mov_b32_e32 v63, v0
	v_mov_b32_e32 v64, v0
	v_mov_b32_e32 v65, v0
	v_mov_b32_e32 v66, v0
	v_mov_b32_e32 v67, v0
	v_mov_b32_e32 v68, v0
	v_mov_b32_e32 v69, v0
	v_mov_b32_e32 v70, v0
	v_mov_b32_e32 v71, v0
	v_mov_b32_e32 v80, v0
	v_mov_b32_e32 v81, v0
	v_mov_b32_e32 v82, v0
	v_mov_b32_e32 v83, v0
	v_mov_b32_e32 v84, v0
	v_mov_b32_e32 v85, v0
	v_mov_b32_e32 v86, v0
	v_mov_b32_e32 v87, v0
	v_mov_b32_e32 v96, v0
	v_mov_b32_e32 v97, v0
	v_mov_b32_e32 v98, v0
	v_mov_b32_e32 v99, v0
	v_mov_b32_e32 v100, v0
	v_mov_b32_e32 v101, v0
	v_mov_b32_e32 v102, v0
	v_mov_b32_e32 v103, v0
	v_mov_b32_e32 v112, v0
	v_mov_b32_e32 v113, v0
	v_mov_b32_e32 v114, v0
	v_mov_b32_e32 v115, v0
	v_mov_b32_e32 v116, v0
	v_mov_b32_e32 v117, v0
	v_mov_b32_e32 v118, v0
	v_mov_b32_e32 v119, v0
	v_mov_b32_e32 v72, v0
	v_mov_b32_e32 v73, v0
	v_mov_b32_e32 v74, v0
	v_mov_b32_e32 v75, v0
	v_mov_b32_e32 v76, v0
	v_mov_b32_e32 v77, v0
	v_mov_b32_e32 v78, v0
	v_mov_b32_e32 v79, v0
	v_mov_b32_e32 v88, v0
	v_mov_b32_e32 v89, v0
	v_mov_b32_e32 v90, v0
	v_mov_b32_e32 v91, v0
	v_mov_b32_e32 v92, v0
	v_mov_b32_e32 v93, v0
	v_mov_b32_e32 v94, v0
	v_mov_b32_e32 v95, v0
	v_mov_b32_e32 v104, v0
	v_mov_b32_e32 v105, v0
	v_mov_b32_e32 v106, v0
	v_mov_b32_e32 v107, v0
	v_mov_b32_e32 v108, v0
	v_mov_b32_e32 v109, v0
	v_mov_b32_e32 v110, v0
	v_mov_b32_e32 v111, v0
	v_mov_b32_e32 v120, v0
	v_mov_b32_e32 v121, v0
	v_mov_b32_e32 v122, v0
	v_mov_b32_e32 v123, v0
	v_mov_b32_e32 v124, v0
	v_mov_b32_e32 v125, v0
	v_mov_b32_e32 v126, v0
	v_mov_b32_e32 v127, v0
	v_readfirstlane_b32 s4, v182
	s_nop 3
	s_cmp_lt_u32 s4, 256
	s_cbranch_scc1 .Lkprio_1399
	s_setprio 1
.Lkprio_1399:
.LBB0_1399:
	s_add_u32 s58, s54, 0x100
	s_addc_u32 s59, s55, 0
	s_add_i32 s4, 0, 0x10000
	s_cmp_eq_u32 s29, 40
	s_cselect_b32 s61, s45, s59
	s_cselect_b32 s60, s44, s58
	v_add_u32_e32 v142, s4, v160
	s_cselect_b32 s35, s53, s28
	s_cselect_b32 s34, s52, s3
	s_add_i32 s47, 0, 0x14000
	ds_read_b128 v[138:141], v142
	ds_read_b128 v[154:157], v142 offset:1024
	ds_read_b128 v[172:175], v142 offset:2048
	ds_read_b128 v[176:179], v142 offset:3072
	v_add_u32_e32 v142, s47, v160
	ds_read_b128 v[204:207], v142
	ds_read_b128 v[208:211], v142 offset:1024
	ds_read_b128 v[212:215], v142 offset:2048
	ds_read_b128 v[216:219], v142 offset:3072
	v_lshl_add_u64 v[142:143], s[54:55], 0, v[134:135]
	s_add_i32 m0, s65, 0xc000
	ds_read_b128 v[220:223], v170
	ds_read_b128 v[224:227], v170 offset:1024
	ds_read_b128 v[228:231], v170 offset:2048
	ds_read_b128 v[232:235], v170 offset:3072
	ds_read_b128 v[236:239], v170 offset:4096
	ds_read_b128 v[240:243], v170 offset:5120
	ds_read_b128 v[244:247], v170 offset:6144
	ds_read_b128 v[248:251], v170 offset:7168
	global_load_lds_dwordx4 v[142:143], off
	v_lshl_add_u64 v[142:143], s[54:55], 0, v[136:137]
	s_add_i32 m0, s65, 0xe000
	s_nop 0
	global_load_lds_dwordx4 v[142:143], off
	s_waitcnt vmcnt(8)
	s_waitcnt lgkmcnt(0)
	s_barrier
	s_waitcnt lgkmcnt(0)
	v_mfma_f32_16x16x32_bf16 v[124:127], v[138:141], v[220:223], v[124:127]
	v_mfma_f32_16x16x32_bf16 v[120:123], v[172:175], v[220:223], v[120:123]
	v_mfma_f32_16x16x32_bf16 v[108:111], v[138:141], v[228:231], v[108:111]
	v_mfma_f32_16x16x32_bf16 v[104:107], v[172:175], v[228:231], v[104:107]
	v_mfma_f32_16x16x32_bf16 v[92:95], v[138:141], v[236:239], v[92:95]
	v_mfma_f32_16x16x32_bf16 v[88:91], v[172:175], v[236:239], v[88:91]
	v_mfma_f32_16x16x32_bf16 v[76:79], v[138:141], v[244:247], v[76:79]
	v_mfma_f32_16x16x32_bf16 v[72:75], v[172:175], v[244:247], v[72:75]
	v_mfma_f32_16x16x32_bf16 v[124:127], v[154:157], v[224:227], v[124:127]
	v_mfma_f32_16x16x32_bf16 v[120:123], v[176:179], v[224:227], v[120:123]
	v_mfma_f32_16x16x32_bf16 v[108:111], v[154:157], v[232:235], v[108:111]
	v_mfma_f32_16x16x32_bf16 v[104:107], v[176:179], v[232:235], v[104:107]
	v_mfma_f32_16x16x32_bf16 v[92:95], v[154:157], v[240:243], v[92:95]
	v_mfma_f32_16x16x32_bf16 v[88:91], v[176:179], v[240:243], v[88:91]
	v_mfma_f32_16x16x32_bf16 v[76:79], v[154:157], v[248:251], v[76:79]
	v_mfma_f32_16x16x32_bf16 v[72:75], v[176:179], v[248:251], v[72:75]
	v_mfma_f32_16x16x32_bf16 v[116:119], v[204:207], v[220:223], v[116:119]
	v_mfma_f32_16x16x32_bf16 v[112:115], v[212:215], v[220:223], v[112:115]
	v_mfma_f32_16x16x32_bf16 v[100:103], v[204:207], v[228:231], v[100:103]
	v_mfma_f32_16x16x32_bf16 v[96:99], v[212:215], v[228:231], v[96:99]
	v_mfma_f32_16x16x32_bf16 v[84:87], v[204:207], v[236:239], v[84:87]
	v_mfma_f32_16x16x32_bf16 v[80:83], v[212:215], v[236:239], v[80:83]
	v_mfma_f32_16x16x32_bf16 v[68:71], v[204:207], v[244:247], v[68:71]
	v_mfma_f32_16x16x32_bf16 v[64:67], v[212:215], v[244:247], v[64:67]
	v_mfma_f32_16x16x32_bf16 v[116:119], v[208:211], v[224:227], v[116:119]
	v_mfma_f32_16x16x32_bf16 v[112:115], v[216:219], v[224:227], v[112:115]
	v_mfma_f32_16x16x32_bf16 v[100:103], v[208:211], v[232:235], v[100:103]
	v_mfma_f32_16x16x32_bf16 v[96:99], v[216:219], v[232:235], v[96:99]
	v_mfma_f32_16x16x32_bf16 v[84:87], v[208:211], v[240:243], v[84:87]
	v_mfma_f32_16x16x32_bf16 v[80:83], v[216:219], v[240:243], v[80:83]
	v_mfma_f32_16x16x32_bf16 v[68:71], v[208:211], v[248:251], v[68:71]
	v_mfma_f32_16x16x32_bf16 v[64:67], v[216:219], v[248:251], v[64:67]
	s_barrier
	s_add_i32 s4, s4, s33
	v_lshl_add_u64 v[142:143], s[34:35], 0, v[128:129]
	s_mov_b32 m0, s4
	ds_read_b128 v[220:223], v170 offset:16384
	ds_read_b128 v[224:227], v170 offset:17408
	ds_read_b128 v[228:231], v170 offset:18432
	ds_read_b128 v[232:235], v170 offset:19456
	ds_read_b128 v[236:239], v170 offset:20480
	ds_read_b128 v[240:243], v170 offset:21504
	ds_read_b128 v[244:247], v170 offset:22528
	ds_read_b128 v[248:251], v170 offset:23552
	global_load_lds_dwordx4 v[142:143], off
	s_add_i32 m0, s4, 0x2000
	s_add_u32 s4, s34, 0xb0000
	v_lshl_add_u64 v[158:159], s[34:35], 0, v[130:131]
	s_addc_u32 s5, s35, 0
	s_add_i32 s47, s47, s33
	global_load_lds_dwordx4 v[158:159], off
	v_lshl_add_u64 v[180:181], s[4:5], 0, v[128:129]
	s_mov_b32 m0, s47
	v_lshl_add_u64 v[202:203], s[60:61], 0, v[130:131]
	global_load_lds_dwordx4 v[180:181], off
	v_lshl_add_u64 v[180:181], s[4:5], 0, v[130:131]
	s_add_i32 m0, s47, 0x2000
	s_nop 0
	global_load_lds_dwordx4 v[180:181], off
	v_lshl_add_u64 v[180:181], s[60:61], 0, v[128:129]
	s_mov_b32 m0, s65
	s_nop 0
	global_load_lds_dwordx4 v[180:181], off
	s_mov_b32 m0, s66
	s_nop 0
	global_load_lds_dwordx4 v[202:203], off
	s_waitcnt vmcnt(8)
	s_waitcnt lgkmcnt(0)
	s_barrier
	s_waitcnt lgkmcnt(0)
	v_mfma_f32_16x16x32_bf16 v[60:63], v[138:141], v[220:223], v[60:63]
	v_mfma_f32_16x16x32_bf16 v[56:59], v[172:175], v[220:223], v[56:59]
	v_mfma_f32_16x16x32_bf16 v[44:47], v[138:141], v[228:231], v[44:47]
	v_mfma_f32_16x16x32_bf16 v[40:43], v[172:175], v[228:231], v[40:43]
	v_mfma_f32_16x16x32_bf16 v[28:31], v[138:141], v[236:239], v[28:31]
	v_mfma_f32_16x16x32_bf16 v[24:27], v[172:175], v[236:239], v[24:27]
	v_mfma_f32_16x16x32_bf16 v[12:15], v[138:141], v[244:247], v[12:15]
	v_mfma_f32_16x16x32_bf16 v[8:11], v[172:175], v[244:247], v[8:11]
	v_mfma_f32_16x16x32_bf16 v[60:63], v[154:157], v[224:227], v[60:63]
	v_mfma_f32_16x16x32_bf16 v[56:59], v[176:179], v[224:227], v[56:59]
	v_mfma_f32_16x16x32_bf16 v[44:47], v[154:157], v[232:235], v[44:47]
	v_mfma_f32_16x16x32_bf16 v[40:43], v[176:179], v[232:235], v[40:43]
	v_mfma_f32_16x16x32_bf16 v[28:31], v[154:157], v[240:243], v[28:31]
	v_mfma_f32_16x16x32_bf16 v[24:27], v[176:179], v[240:243], v[24:27]
	v_mfma_f32_16x16x32_bf16 v[12:15], v[154:157], v[248:251], v[12:15]
	v_mfma_f32_16x16x32_bf16 v[8:11], v[176:179], v[248:251], v[8:11]
	v_mfma_f32_16x16x32_bf16 v[52:55], v[204:207], v[220:223], v[52:55]
	v_mfma_f32_16x16x32_bf16 v[48:51], v[212:215], v[220:223], v[48:51]
	v_mfma_f32_16x16x32_bf16 v[36:39], v[204:207], v[228:231], v[36:39]
	v_mfma_f32_16x16x32_bf16 v[32:35], v[212:215], v[228:231], v[32:35]
	v_mfma_f32_16x16x32_bf16 v[20:23], v[204:207], v[236:239], v[20:23]
	v_mfma_f32_16x16x32_bf16 v[16:19], v[212:215], v[236:239], v[16:19]
	v_mfma_f32_16x16x32_bf16 v[4:7], v[204:207], v[244:247], v[4:7]
	v_mfma_f32_16x16x32_bf16 v[0:3], v[212:215], v[244:247], v[0:3]
	v_mfma_f32_16x16x32_bf16 v[52:55], v[208:211], v[224:227], v[52:55]
	v_mfma_f32_16x16x32_bf16 v[48:51], v[216:219], v[224:227], v[48:51]
	v_mfma_f32_16x16x32_bf16 v[36:39], v[208:211], v[232:235], v[36:39]
	v_mfma_f32_16x16x32_bf16 v[32:35], v[216:219], v[232:235], v[32:35]
	v_mfma_f32_16x16x32_bf16 v[20:23], v[208:211], v[240:243], v[20:23]
	v_mfma_f32_16x16x32_bf16 v[16:19], v[216:219], v[240:243], v[16:19]
	v_mfma_f32_16x16x32_bf16 v[4:7], v[208:211], v[248:251], v[4:7]
	v_mfma_f32_16x16x32_bf16 v[0:3], v[216:219], v[248:251], v[0:3]
	s_barrier
	s_add_i32 s47, 0, 0x18000
	v_add_u32_e32 v144, s47, v160
	s_add_i32 s54, 0, 0x1c000
	ds_read_b128 v[138:141], v144
	ds_read_b128 v[154:157], v144 offset:1024
	ds_read_b128 v[172:175], v144 offset:2048
	ds_read_b128 v[176:179], v144 offset:3072
	v_add_u32_e32 v144, s54, v160
	ds_read_b128 v[204:207], v144
	ds_read_b128 v[208:211], v144 offset:1024
	ds_read_b128 v[212:215], v144 offset:2048
	ds_read_b128 v[216:219], v144 offset:3072
	s_add_u32 s4, s60, 0xb0000
	s_addc_u32 s5, s61, 0
	s_mov_b32 m0, s67
	v_lshl_add_u64 v[252:253], s[4:5], 0, v[128:129]
	ds_read_b128 v[220:223], v170 offset:32768
	ds_read_b128 v[224:227], v170 offset:33792
	ds_read_b128 v[228:231], v170 offset:34816
	ds_read_b128 v[232:235], v170 offset:35840
	ds_read_b128 v[236:239], v170 offset:36864
	ds_read_b128 v[240:243], v170 offset:37888
	ds_read_b128 v[244:247], v170 offset:38912
	ds_read_b128 v[248:251], v170 offset:39936
	global_load_lds_dwordx4 v[252:253], off
	v_lshl_add_u64 v[252:253], s[4:5], 0, v[130:131]
	s_mov_b32 m0, s68
	s_nop 0
	global_load_lds_dwordx4 v[252:253], off
	s_waitcnt vmcnt(8)
	s_waitcnt lgkmcnt(0)
	s_barrier
	s_waitcnt lgkmcnt(0)
	v_mfma_f32_16x16x32_bf16 v[124:127], v[138:141], v[220:223], v[124:127]
	v_mfma_f32_16x16x32_bf16 v[120:123], v[172:175], v[220:223], v[120:123]
	v_mfma_f32_16x16x32_bf16 v[108:111], v[138:141], v[228:231], v[108:111]
	v_mfma_f32_16x16x32_bf16 v[104:107], v[172:175], v[228:231], v[104:107]
	v_mfma_f32_16x16x32_bf16 v[92:95], v[138:141], v[236:239], v[92:95]
	v_mfma_f32_16x16x32_bf16 v[88:91], v[172:175], v[236:239], v[88:91]
	v_mfma_f32_16x16x32_bf16 v[76:79], v[138:141], v[244:247], v[76:79]
	v_mfma_f32_16x16x32_bf16 v[72:75], v[172:175], v[244:247], v[72:75]
	v_mfma_f32_16x16x32_bf16 v[124:127], v[154:157], v[224:227], v[124:127]
	v_mfma_f32_16x16x32_bf16 v[120:123], v[176:179], v[224:227], v[120:123]
	v_mfma_f32_16x16x32_bf16 v[108:111], v[154:157], v[232:235], v[108:111]
	v_mfma_f32_16x16x32_bf16 v[104:107], v[176:179], v[232:235], v[104:107]
	v_mfma_f32_16x16x32_bf16 v[92:95], v[154:157], v[240:243], v[92:95]
	v_mfma_f32_16x16x32_bf16 v[88:91], v[176:179], v[240:243], v[88:91]
	v_mfma_f32_16x16x32_bf16 v[76:79], v[154:157], v[248:251], v[76:79]
	v_mfma_f32_16x16x32_bf16 v[72:75], v[176:179], v[248:251], v[72:75]
	v_mfma_f32_16x16x32_bf16 v[116:119], v[204:207], v[220:223], v[116:119]
	v_mfma_f32_16x16x32_bf16 v[112:115], v[212:215], v[220:223], v[112:115]
	v_mfma_f32_16x16x32_bf16 v[100:103], v[204:207], v[228:231], v[100:103]
	v_mfma_f32_16x16x32_bf16 v[96:99], v[212:215], v[228:231], v[96:99]
	v_mfma_f32_16x16x32_bf16 v[84:87], v[204:207], v[236:239], v[84:87]
	v_mfma_f32_16x16x32_bf16 v[80:83], v[212:215], v[236:239], v[80:83]
	v_mfma_f32_16x16x32_bf16 v[68:71], v[204:207], v[244:247], v[68:71]
	v_mfma_f32_16x16x32_bf16 v[64:67], v[212:215], v[244:247], v[64:67]
	v_mfma_f32_16x16x32_bf16 v[116:119], v[208:211], v[224:227], v[116:119]
	v_mfma_f32_16x16x32_bf16 v[112:115], v[216:219], v[224:227], v[112:115]
	v_mfma_f32_16x16x32_bf16 v[100:103], v[208:211], v[232:235], v[100:103]
	v_mfma_f32_16x16x32_bf16 v[96:99], v[216:219], v[232:235], v[96:99]
	v_mfma_f32_16x16x32_bf16 v[84:87], v[208:211], v[240:243], v[84:87]
	v_mfma_f32_16x16x32_bf16 v[80:83], v[216:219], v[240:243], v[80:83]
	v_mfma_f32_16x16x32_bf16 v[68:71], v[208:211], v[248:251], v[68:71]
	v_mfma_f32_16x16x32_bf16 v[64:67], v[216:219], v[248:251], v[64:67]
	s_barrier
	s_add_i32 s4, s47, s33
	v_lshl_add_u64 v[142:143], v[142:143], 0, s[26:27]
	s_mov_b32 m0, s4
	ds_read_b128 v[220:223], v170 offset:49152
	ds_read_b128 v[224:227], v170 offset:50176
	ds_read_b128 v[228:231], v170 offset:51200
	ds_read_b128 v[232:235], v170 offset:52224
	ds_read_b128 v[236:239], v170 offset:53248
	ds_read_b128 v[240:243], v170 offset:54272
	ds_read_b128 v[244:247], v170 offset:55296
	ds_read_b128 v[248:251], v170 offset:56320
	global_load_lds_dwordx4 v[142:143], off
	s_add_i32 m0, s4, 0x2000
	s_add_u32 s4, s34, 0xb0080
	v_lshl_add_u64 v[142:143], v[158:159], 0, s[26:27]
	s_addc_u32 s5, s35, 0
	s_add_i32 s34, s54, s33
	global_load_lds_dwordx4 v[142:143], off
	v_lshl_add_u64 v[142:143], s[4:5], 0, v[128:129]
	s_mov_b32 m0, s34
	s_nop 0
	global_load_lds_dwordx4 v[142:143], off
	v_lshl_add_u64 v[142:143], s[4:5], 0, v[130:131]
	s_add_i32 m0, s34, 0x2000
	s_nop 0
	global_load_lds_dwordx4 v[142:143], off
	v_lshl_add_u64 v[142:143], v[180:181], 0, s[26:27]
	s_mov_b32 m0, s69
	s_nop 0
	global_load_lds_dwordx4 v[142:143], off
	v_lshl_add_u64 v[142:143], v[202:203], 0, s[26:27]
	s_mov_b32 m0, s70
	s_nop 0
	global_load_lds_dwordx4 v[142:143], off
	s_waitcnt vmcnt(8)
	s_waitcnt lgkmcnt(0)
	s_barrier
	s_waitcnt lgkmcnt(0)
	v_mfma_f32_16x16x32_bf16 v[60:63], v[138:141], v[220:223], v[60:63]
	v_mfma_f32_16x16x32_bf16 v[56:59], v[172:175], v[220:223], v[56:59]
	v_mfma_f32_16x16x32_bf16 v[44:47], v[138:141], v[228:231], v[44:47]
	v_mfma_f32_16x16x32_bf16 v[40:43], v[172:175], v[228:231], v[40:43]
	v_mfma_f32_16x16x32_bf16 v[28:31], v[138:141], v[236:239], v[28:31]
	v_mfma_f32_16x16x32_bf16 v[24:27], v[172:175], v[236:239], v[24:27]
	v_mfma_f32_16x16x32_bf16 v[12:15], v[138:141], v[244:247], v[12:15]
	v_mfma_f32_16x16x32_bf16 v[8:11], v[172:175], v[244:247], v[8:11]
	v_mfma_f32_16x16x32_bf16 v[60:63], v[154:157], v[224:227], v[60:63]
	v_mfma_f32_16x16x32_bf16 v[56:59], v[176:179], v[224:227], v[56:59]
	v_mfma_f32_16x16x32_bf16 v[44:47], v[154:157], v[232:235], v[44:47]
	v_mfma_f32_16x16x32_bf16 v[40:43], v[176:179], v[232:235], v[40:43]
	v_mfma_f32_16x16x32_bf16 v[28:31], v[154:157], v[240:243], v[28:31]
	v_mfma_f32_16x16x32_bf16 v[24:27], v[176:179], v[240:243], v[24:27]
	v_mfma_f32_16x16x32_bf16 v[12:15], v[154:157], v[248:251], v[12:15]
	v_mfma_f32_16x16x32_bf16 v[8:11], v[176:179], v[248:251], v[8:11]
	v_mfma_f32_16x16x32_bf16 v[52:55], v[204:207], v[220:223], v[52:55]
	v_mfma_f32_16x16x32_bf16 v[48:51], v[212:215], v[220:223], v[48:51]
	v_mfma_f32_16x16x32_bf16 v[36:39], v[204:207], v[228:231], v[36:39]
	v_mfma_f32_16x16x32_bf16 v[32:35], v[212:215], v[228:231], v[32:35]
	v_mfma_f32_16x16x32_bf16 v[20:23], v[204:207], v[236:239], v[20:23]
	v_mfma_f32_16x16x32_bf16 v[16:19], v[212:215], v[236:239], v[16:19]
	v_mfma_f32_16x16x32_bf16 v[4:7], v[204:207], v[244:247], v[4:7]
	v_mfma_f32_16x16x32_bf16 v[0:3], v[212:215], v[244:247], v[0:3]
	v_mfma_f32_16x16x32_bf16 v[52:55], v[208:211], v[224:227], v[52:55]
	v_mfma_f32_16x16x32_bf16 v[48:51], v[216:219], v[224:227], v[48:51]
	v_mfma_f32_16x16x32_bf16 v[36:39], v[208:211], v[232:235], v[36:39]
	v_mfma_f32_16x16x32_bf16 v[32:35], v[216:219], v[232:235], v[32:35]
	v_mfma_f32_16x16x32_bf16 v[20:23], v[208:211], v[240:243], v[20:23]
	v_mfma_f32_16x16x32_bf16 v[16:19], v[216:219], v[240:243], v[16:19]
	v_mfma_f32_16x16x32_bf16 v[4:7], v[208:211], v[248:251], v[4:7]
	v_mfma_f32_16x16x32_bf16 v[0:3], v[216:219], v[248:251], v[0:3]
	s_barrier
	s_add_i32 s29, s29, 2
	s_add_u32 s3, s3, 0x100
	s_addc_u32 s28, s28, 0
	s_cmp_gt_u32 s29, 41
	s_mov_b64 s[54:55], s[58:59]
	s_cbranch_scc0 .LBB0_1399
	s_setprio 0
	s_and_b64 vcc, exec, s[50:51]
	s_cbranch_vccz .LBB0_1402
	s_barrier
